# GEMM K-loops: the duplicated s_waitcnt lgkmcnt(0) in front of each MFMA block removed (30 sites)
# speedup vs baseline: 1.0065x; 1.0065x over previous
; #define STAGE(P, BASE, br, kt) STAGET(tid_, P, BASE, br, kt)
; #define LDA(dst, b, h) UFOR(m, 4) UFOR(k, 2) \
;     dst[m][k] = *reinterpret_cast<const bf16x8*>((char*)SA(b, h) + lds_byte(wr * 64 + m * 16 + fr, k * 32 + fq * 8))
; #define LDB(dst, b, h) UFOR(n, 2) UFOR(k, 2) \
;     dst[n][k] = *reinterpret_cast<const bf16x8*>((char*)SB(b, h) + lds_byte(wc * 32 + n * 16 + fr, k * 32 + fq * 8))
; #define MMA(ai, bj, At, Bq) do { __builtin_amdgcn_s_setprio(1); \
;     UFOR(m, 4) UFOR(n, 2) UFOR(k, 2) \
;       acc[ai][bj][m][n] = __builtin_amdgcn_mfma_f32_16x16x32_bf16(Bq[n][k], At[m][k], acc[ai][bj][m][n], 0, 0, 0); \
;     __builtin_amdgcn_s_setprio(0); } while (0)
; #define WAIT_L(n) asm volatile("s_waitcnt lgkmcnt(" #n ")" ::: "memory")
; #define BAR __builtin_amdgcn_s_barrier()
; #define SCHED __builtin_amdgcn_sched_barrier(0)
; template <int EPI, int K, int KL> ...
;     ...
;     LDB(B0, 0, 0); SCHED; LDA(At, 0, 0); STAGE(SA(1, 1), A, brow + HALF, t + 1);
;     WAIT_L(8); BAR; WAIT_L(0); MMA(0, 0, At, B0); BAR; SCHED;
;     LDB(B1, 0, 1); STAGE(SB(0, 0), Bt, bcol, t + 2);
;     BAR; WAIT_L(0); MMA(0, 1, At, B1); BAR;
;     LDA(At, 0, 1); STAGE(SA(0, 0), A, brow, t + 2);
;     BAR; WAIT_L(0); MMA(1, 0, At, B0); BAR; SCHED;
.LBB0_236:
	ds_read_b128 v[174:177], v170
	ds_read_b128 v[178:181], v170 offset:1024
	ds_read_b128 v[182:185], v170 offset:2048
	ds_read_b128 v[186:189], v170 offset:3072
	ds_read_b128 v[190:193], v162
	ds_read_b128 v[194:197], v162 offset:1024
	ds_read_b128 v[198:201], v161
	ds_read_b128 v[202:205], v161 offset:1024
	ds_read_b128 v[218:221], v160
	ds_read_b128 v[222:225], v160 offset:1024
	ds_read_b128 v[226:229], v159
	ds_read_b128 v[230:233], v159 offset:1024
	v_add_u32_e32 v171, 0xc000, v157
	v_lshl_add_u64 v[136:137], s[92:93], 0, v[150:151]
	v_readfirstlane_b32 s18, v171
	v_lshl_add_u64 v[138:139], v[136:137], 0, s[88:89]
	s_mov_b32 m0, s18
	v_add_u32_e32 v172, 0xe000, v157
	global_load_lds_dwordx4 v[138:139], off
	v_lshl_add_u64 v[138:139], s[92:93], 0, v[152:153]
	v_readfirstlane_b32 s18, v172
	v_lshl_add_u64 v[208:209], v[138:139], 0, s[88:89]
	s_mov_b32 m0, s18
	s_nop 0
	global_load_lds_dwordx4 v[208:209], off
	s_waitcnt lgkmcnt(8)
	s_barrier
	s_waitcnt lgkmcnt(0)
	v_mfma_f32_16x16x32_bf16 v[124:127], v[174:177], v[190:193], v[124:127]
	v_mfma_f32_16x16x32_bf16 v[120:123], v[182:185], v[190:193], v[120:123]
	v_mfma_f32_16x16x32_bf16 v[116:119], v[174:177], v[198:201], v[116:119]
	v_mfma_f32_16x16x32_bf16 v[112:115], v[182:185], v[198:201], v[112:115]
	v_mfma_f32_16x16x32_bf16 v[108:111], v[174:177], v[218:221], v[108:111]
	v_mfma_f32_16x16x32_bf16 v[104:107], v[182:185], v[218:221], v[104:107]
	v_mfma_f32_16x16x32_bf16 v[100:103], v[174:177], v[226:229], v[100:103]
	v_mfma_f32_16x16x32_bf16 v[96:99], v[182:185], v[226:229], v[96:99]
	v_mfma_f32_16x16x32_bf16 v[124:127], v[178:181], v[194:197], v[124:127]
	v_mfma_f32_16x16x32_bf16 v[120:123], v[186:189], v[194:197], v[120:123]
	v_mfma_f32_16x16x32_bf16 v[116:119], v[178:181], v[202:205], v[116:119]
	v_mfma_f32_16x16x32_bf16 v[112:115], v[186:189], v[202:205], v[112:115]
	v_mfma_f32_16x16x32_bf16 v[108:111], v[178:181], v[222:225], v[108:111]
	v_mfma_f32_16x16x32_bf16 v[104:107], v[186:189], v[222:225], v[104:107]
	v_mfma_f32_16x16x32_bf16 v[100:103], v[178:181], v[230:233], v[100:103]
	v_mfma_f32_16x16x32_bf16 v[96:99], v[186:189], v[230:233], v[96:99]
	s_barrier
	ds_read_b128 v[234:237], v168
	ds_read_b128 v[238:241], v168 offset:1024
	ds_read_b128 v[242:245], v168 offset:2048
	ds_read_b128 v[246:249], v168 offset:3072
	v_lshl_add_u64 v[208:209], s[92:93], 0, v[146:147]
	v_readfirstlane_b32 s18, v156
	v_lshl_add_u64 v[210:211], v[208:209], 0, s[52:53]
	s_mov_b32 m0, s18
	v_add_u32_e32 v134, 0x2000, v156
	global_load_lds_dwordx4 v[210:211], off
	v_lshl_add_u64 v[210:211], s[92:93], 0, v[148:149]
	v_readfirstlane_b32 s18, v134
	v_lshl_add_u64 v[214:215], v[210:211], 0, s[52:53]
	s_mov_b32 m0, s18
	s_nop 0
	global_load_lds_dwordx4 v[214:215], off
	s_barrier
	s_waitcnt lgkmcnt(0)
	v_mfma_f32_16x16x32_bf16 v[92:95], v[234:237], v[190:193], v[92:95]
	v_mfma_f32_16x16x32_bf16 v[88:91], v[242:245], v[190:193], v[88:91]
	v_mfma_f32_16x16x32_bf16 v[84:87], v[234:237], v[198:201], v[84:87]
	v_mfma_f32_16x16x32_bf16 v[80:83], v[242:245], v[198:201], v[80:83]
	v_mfma_f32_16x16x32_bf16 v[76:79], v[234:237], v[218:221], v[76:79]
	v_mfma_f32_16x16x32_bf16 v[72:75], v[242:245], v[218:221], v[72:75]
	v_mfma_f32_16x16x32_bf16 v[68:71], v[234:237], v[226:229], v[68:71]
	v_mfma_f32_16x16x32_bf16 v[64:67], v[242:245], v[226:229], v[64:67]
	v_mfma_f32_16x16x32_bf16 v[92:95], v[238:241], v[194:197], v[92:95]
	v_mfma_f32_16x16x32_bf16 v[88:91], v[246:249], v[194:197], v[88:91]
	v_mfma_f32_16x16x32_bf16 v[84:87], v[238:241], v[202:205], v[84:87]
	v_mfma_f32_16x16x32_bf16 v[80:83], v[246:249], v[202:205], v[80:83]
	v_mfma_f32_16x16x32_bf16 v[76:79], v[238:241], v[222:225], v[76:79]
	v_mfma_f32_16x16x32_bf16 v[72:75], v[246:249], v[222:225], v[72:75]
	v_mfma_f32_16x16x32_bf16 v[68:71], v[238:241], v[230:233], v[68:71]
	v_mfma_f32_16x16x32_bf16 v[64:67], v[246:249], v[230:233], v[64:67]
	v_readfirstlane_b32 s18, v157
	v_add_u32_e32 v134, 0x2000, v157
	v_lshl_add_u64 v[214:215], v[136:137], 0, s[8:9]
	s_mov_b32 m0, s18
	v_readfirstlane_b32 s18, v134
	s_barrier
	ds_read_b128 v[190:193], v162 offset:16384
	ds_read_b128 v[194:197], v162 offset:17408
	ds_read_b128 v[198:201], v161 offset:16384
	ds_read_b128 v[202:205], v161 offset:17408
	ds_read_b128 v[218:221], v160 offset:16384
	ds_read_b128 v[222:225], v160 offset:17408
	ds_read_b128 v[226:229], v159 offset:16384
	ds_read_b128 v[230:233], v159 offset:17408
	global_load_lds_dwordx4 v[214:215], off
	v_lshl_add_u64 v[214:215], v[138:139], 0, s[8:9]
	s_mov_b32 m0, s18
	s_nop 0
	global_load_lds_dwordx4 v[214:215], off
	s_barrier
	s_waitcnt lgkmcnt(0)
	v_mfma_f32_16x16x32_bf16 v[60:63], v[174:177], v[190:193], v[60:63]
	v_mfma_f32_16x16x32_bf16 v[56:59], v[182:185], v[190:193], v[56:59]
	v_mfma_f32_16x16x32_bf16 v[52:55], v[174:177], v[198:201], v[52:55]
	v_mfma_f32_16x16x32_bf16 v[48:51], v[182:185], v[198:201], v[48:51]
	v_mfma_f32_16x16x32_bf16 v[44:47], v[174:177], v[218:221], v[44:47]
	v_mfma_f32_16x16x32_bf16 v[40:43], v[182:185], v[218:221], v[40:43]
	v_mfma_f32_16x16x32_bf16 v[36:39], v[174:177], v[226:229], v[36:39]
	v_mfma_f32_16x16x32_bf16 v[32:35], v[182:185], v[226:229], v[32:35]
	v_mfma_f32_16x16x32_bf16 v[60:63], v[178:181], v[194:197], v[60:63]
	v_mfma_f32_16x16x32_bf16 v[56:59], v[186:189], v[194:197], v[56:59]
	v_mfma_f32_16x16x32_bf16 v[52:55], v[178:181], v[202:205], v[52:55]
	v_mfma_f32_16x16x32_bf16 v[48:51], v[186:189], v[202:205], v[48:51]
	v_mfma_f32_16x16x32_bf16 v[44:47], v[178:181], v[222:225], v[44:47]
	v_mfma_f32_16x16x32_bf16 v[40:43], v[186:189], v[222:225], v[40:43]
	v_mfma_f32_16x16x32_bf16 v[36:39], v[178:181], v[230:233], v[36:39]
	v_mfma_f32_16x16x32_bf16 v[32:35], v[186:189], v[230:233], v[32:35]
	s_barrier
; #define STAGE(P, BASE, br, kt) STAGET(tid_, P, BASE, br, kt)
; #define LDA(dst, b, h) UFOR(m, 4) UFOR(k, 2) \
;     dst[m][k] = *reinterpret_cast<const bf16x8*>((char*)SA(b, h) + lds_byte(wr * 64 + m * 16 + fr, k * 32 + fq * 8))
; #define LDB(dst, b, h) UFOR(n, 2) UFOR(k, 2) \
;     dst[n][k] = *reinterpret_cast<const bf16x8*>((char*)SB(b, h) + lds_byte(wc * 32 + n * 16 + fr, k * 32 + fq * 8))
; #define MMA(ai, bj, At, Bq) do { __builtin_amdgcn_s_setprio(1); \
;     UFOR(m, 4) UFOR(n, 2) UFOR(k, 2) \
;       acc[ai][bj][m][n] = __builtin_amdgcn_mfma_f32_16x16x32_bf16(Bq[n][k], At[m][k], acc[ai][bj][m][n], 0, 0, 0); \
;     __builtin_amdgcn_s_setprio(0); } while (0)
; #define WAIT_V(n) asm volatile("s_waitcnt vmcnt(" #n ")" ::: "memory")
; #define WAIT_L(n) asm volatile("s_waitcnt lgkmcnt(" #n ")" ::: "memory")
; #define BAR __builtin_amdgcn_s_barrier()
; #define SCHED __builtin_amdgcn_sched_barrier(0)
; template <int EPI, int K, int KL> ...
;     ...
;     STAGE(SB(0, 1), Bt, bcol + HALF, t + 2);
;     WAIT_V(6); BAR; MMA(1, 1, At, B1); BAR;
;     LDB(B0, 1, 0); SCHED; LDA(At, 1, 0); STAGE(SA(0, 1), A, brow + HALF, t + 2);
;     WAIT_L(8); BAR; WAIT_L(0); MMA(0, 0, At, B0); BAR; SCHED;
;     LDB(B1, 1, 1); STAGE(SB(1, 0), Bt, bcol, t + 3);
;     BAR; WAIT_L(0); MMA(0, 1, At, B1); BAR;
;     LDA(At, 1, 1); STAGE(SA(1, 0), A, brow, t + 3);
	v_readfirstlane_b32 s18, v158
	v_add_u32_e32 v134, 0x2000, v158
	v_lshl_add_u64 v[174:175], v[208:209], 0, s[54:55]
	s_mov_b32 m0, s18
	v_readfirstlane_b32 s18, v134
	global_load_lds_dwordx4 v[174:175], off
	v_lshl_add_u64 v[174:175], v[210:211], 0, s[54:55]
	s_mov_b32 m0, s18
	s_nop 0
	global_load_lds_dwordx4 v[174:175], off
	s_waitcnt vmcnt(6)
	s_barrier
	v_mfma_f32_16x16x32_bf16 v[28:31], v[234:237], v[190:193], v[28:31]
	v_mfma_f32_16x16x32_bf16 v[24:27], v[242:245], v[190:193], v[24:27]
	v_mfma_f32_16x16x32_bf16 v[20:23], v[234:237], v[198:201], v[20:23]
	v_mfma_f32_16x16x32_bf16 v[16:19], v[242:245], v[198:201], v[16:19]
	v_mfma_f32_16x16x32_bf16 v[12:15], v[234:237], v[218:221], v[12:15]
	v_mfma_f32_16x16x32_bf16 v[8:11], v[242:245], v[218:221], v[8:11]
	v_mfma_f32_16x16x32_bf16 v[4:7], v[234:237], v[226:229], v[4:7]
	v_mfma_f32_16x16x32_bf16 v[0:3], v[242:245], v[226:229], v[0:3]
	v_mfma_f32_16x16x32_bf16 v[28:31], v[238:241], v[194:197], v[28:31]
	v_mfma_f32_16x16x32_bf16 v[24:27], v[246:249], v[194:197], v[24:27]
	v_mfma_f32_16x16x32_bf16 v[20:23], v[238:241], v[202:205], v[20:23]
	v_mfma_f32_16x16x32_bf16 v[16:19], v[246:249], v[202:205], v[16:19]
	v_mfma_f32_16x16x32_bf16 v[12:15], v[238:241], v[222:225], v[12:15]
	v_mfma_f32_16x16x32_bf16 v[8:11], v[246:249], v[222:225], v[8:11]
	v_mfma_f32_16x16x32_bf16 v[4:7], v[238:241], v[230:233], v[4:7]
	v_mfma_f32_16x16x32_bf16 v[0:3], v[246:249], v[230:233], v[0:3]
	s_barrier
	ds_read_b128 v[174:177], v164
	ds_read_b128 v[178:181], v164 offset:1024
	ds_read_b128 v[182:185], v164 offset:2048
	ds_read_b128 v[186:189], v164 offset:3072
	ds_read_b128 v[190:193], v162 offset:32768
	ds_read_b128 v[194:197], v162 offset:33792
	ds_read_b128 v[198:201], v161 offset:32768
	ds_read_b128 v[202:205], v161 offset:33792
	ds_read_b128 v[218:221], v160 offset:32768
	ds_read_b128 v[222:225], v160 offset:33792
	ds_read_b128 v[226:229], v159 offset:32768
	ds_read_b128 v[230:233], v159 offset:33792
	v_add_u32_e32 v134, 0x4000, v157
	v_lshl_add_u64 v[214:215], v[136:137], 0, s[12:13]
	v_readfirstlane_b32 s18, v134
	v_add_u32_e32 v134, 0x6000, v157
	s_mov_b32 m0, s18
	v_readfirstlane_b32 s18, v134
	global_load_lds_dwordx4 v[214:215], off
	v_lshl_add_u64 v[214:215], v[138:139], 0, s[12:13]
	s_mov_b32 m0, s18
	s_nop 0
	global_load_lds_dwordx4 v[214:215], off
	s_waitcnt lgkmcnt(8)
	s_barrier
	s_waitcnt lgkmcnt(0)
	v_mfma_f32_16x16x32_bf16 v[124:127], v[174:177], v[190:193], v[124:127]
	v_mfma_f32_16x16x32_bf16 v[120:123], v[182:185], v[190:193], v[120:123]
	v_mfma_f32_16x16x32_bf16 v[116:119], v[174:177], v[198:201], v[116:119]
	v_mfma_f32_16x16x32_bf16 v[112:115], v[182:185], v[198:201], v[112:115]
	v_mfma_f32_16x16x32_bf16 v[108:111], v[174:177], v[218:221], v[108:111]
	v_mfma_f32_16x16x32_bf16 v[104:107], v[182:185], v[218:221], v[104:107]
	v_mfma_f32_16x16x32_bf16 v[100:103], v[174:177], v[226:229], v[100:103]
	v_mfma_f32_16x16x32_bf16 v[96:99], v[182:185], v[226:229], v[96:99]
	v_mfma_f32_16x16x32_bf16 v[124:127], v[178:181], v[194:197], v[124:127]
	v_mfma_f32_16x16x32_bf16 v[120:123], v[186:189], v[194:197], v[120:123]
	v_mfma_f32_16x16x32_bf16 v[116:119], v[178:181], v[202:205], v[116:119]
	v_mfma_f32_16x16x32_bf16 v[112:115], v[186:189], v[202:205], v[112:115]
	v_mfma_f32_16x16x32_bf16 v[108:111], v[178:181], v[222:225], v[108:111]
	v_mfma_f32_16x16x32_bf16 v[104:107], v[186:189], v[222:225], v[104:107]
	v_mfma_f32_16x16x32_bf16 v[100:103], v[178:181], v[230:233], v[100:103]
	v_mfma_f32_16x16x32_bf16 v[96:99], v[186:189], v[230:233], v[96:99]
	s_barrier
	ds_read_b128 v[234:237], v163
	ds_read_b128 v[238:241], v163 offset:1024
	ds_read_b128 v[242:245], v163 offset:2048
	ds_read_b128 v[246:249], v163 offset:3072
	v_readfirstlane_b32 s18, v165
	v_add_u32_e32 v134, 0x2000, v165
	v_lshl_add_u64 v[214:215], v[208:209], 0, s[56:57]
	s_mov_b32 m0, s18
	v_readfirstlane_b32 s18, v134
	global_load_lds_dwordx4 v[214:215], off
	v_lshl_add_u64 v[214:215], v[210:211], 0, s[56:57]
	s_mov_b32 m0, s18
	s_nop 0
	global_load_lds_dwordx4 v[214:215], off
	s_barrier
	s_waitcnt lgkmcnt(0)
	v_mfma_f32_16x16x32_bf16 v[92:95], v[234:237], v[190:193], v[92:95]
	v_mfma_f32_16x16x32_bf16 v[88:91], v[242:245], v[190:193], v[88:91]
	v_mfma_f32_16x16x32_bf16 v[84:87], v[234:237], v[198:201], v[84:87]
	v_mfma_f32_16x16x32_bf16 v[80:83], v[242:245], v[198:201], v[80:83]
	v_mfma_f32_16x16x32_bf16 v[76:79], v[234:237], v[218:221], v[76:79]
	v_mfma_f32_16x16x32_bf16 v[72:75], v[242:245], v[218:221], v[72:75]
	v_mfma_f32_16x16x32_bf16 v[68:71], v[234:237], v[226:229], v[68:71]
	v_mfma_f32_16x16x32_bf16 v[64:67], v[242:245], v[226:229], v[64:67]
	v_mfma_f32_16x16x32_bf16 v[92:95], v[238:241], v[194:197], v[92:95]
	v_mfma_f32_16x16x32_bf16 v[88:91], v[246:249], v[194:197], v[88:91]
	v_mfma_f32_16x16x32_bf16 v[84:87], v[238:241], v[202:205], v[84:87]
	v_mfma_f32_16x16x32_bf16 v[80:83], v[246:249], v[202:205], v[80:83]
	v_mfma_f32_16x16x32_bf16 v[76:79], v[238:241], v[222:225], v[76:79]
	v_mfma_f32_16x16x32_bf16 v[72:75], v[246:249], v[222:225], v[72:75]
	v_mfma_f32_16x16x32_bf16 v[68:71], v[238:241], v[230:233], v[68:71]
	v_mfma_f32_16x16x32_bf16 v[64:67], v[246:249], v[230:233], v[64:67]
	v_readfirstlane_b32 s18, v166
	v_lshl_add_u64 v[136:137], v[136:137], 0, s[16:17]
	s_mov_b32 m0, s18
	v_readfirstlane_b32 s18, v167
	s_barrier
	ds_read_b128 v[190:193], v162 offset:49152
	ds_read_b128 v[194:197], v162 offset:50176
	ds_read_b128 v[198:201], v161 offset:49152
	ds_read_b128 v[202:205], v161 offset:50176
	ds_read_b128 v[218:221], v160 offset:49152
	ds_read_b128 v[222:225], v160 offset:50176
	ds_read_b128 v[226:229], v159 offset:49152
	ds_read_b128 v[230:233], v159 offset:50176
	global_load_lds_dwordx4 v[136:137], off
	v_lshl_add_u64 v[136:137], v[138:139], 0, s[16:17]
	s_mov_b32 m0, s18
	s_nop 0
	global_load_lds_dwordx4 v[136:137], off
	s_barrier
; #define STAGE(P, BASE, br, kt) STAGET(tid_, P, BASE, br, kt)
; #define LDA(dst, b, h) UFOR(m, 4) UFOR(k, 2) \
;     dst[m][k] = *reinterpret_cast<const bf16x8*>((char*)SA(b, h) + lds_byte(wr * 64 + m * 16 + fr, k * 32 + fq * 8))
; #define LDB(dst, b, h) UFOR(n, 2) UFOR(k, 2) \
;     dst[n][k] = *reinterpret_cast<const bf16x8*>((char*)SB(b, h) + lds_byte(wc * 32 + n * 16 + fr, k * 32 + fq * 8))
; #define MMA(ai, bj, At, Bq) do { __builtin_amdgcn_s_setprio(1); \
;     UFOR(m, 4) UFOR(n, 2) UFOR(k, 2) \
;       acc[ai][bj][m][n] = __builtin_amdgcn_mfma_f32_16x16x32_bf16(Bq[n][k], At[m][k], acc[ai][bj][m][n], 0, 0, 0); \
;     __builtin_amdgcn_s_setprio(0); } while (0)
; #define WAIT_V(n) asm volatile("s_waitcnt vmcnt(" #n ")" ::: "memory")
; #define WAIT_L(n) asm volatile("s_waitcnt lgkmcnt(" #n ")" ::: "memory")
; #define BAR __builtin_amdgcn_s_barrier()
; #define SCHED __builtin_amdgcn_sched_barrier(0)
; template <int EPI, int K, int KL> ...
;     ...
;     BAR; WAIT_L(0); MMA(1, 0, At, B0); BAR; SCHED;
;     STAGE(SB(1, 1), Bt, bcol + HALF, t + 3);
;     WAIT_V(6); BAR; MMA(1, 1, At, B1); BAR;
;   }
;   { LDB(B0, 0, 0); LDA(At, 0, 0); STAGE(SA(1, 1), A, brow + HALF, nt - 1);
;     BAR; WAIT_L(0); MMA(0, 0, At, B0); BAR;
;     LDB(B1, 0, 1); BAR; WAIT_L(0); MMA(0, 1, At, B1); BAR;
	s_waitcnt lgkmcnt(0)
	v_mfma_f32_16x16x32_bf16 v[60:63], v[174:177], v[190:193], v[60:63]
	v_mfma_f32_16x16x32_bf16 v[56:59], v[182:185], v[190:193], v[56:59]
	v_mfma_f32_16x16x32_bf16 v[52:55], v[174:177], v[198:201], v[52:55]
	v_mfma_f32_16x16x32_bf16 v[48:51], v[182:185], v[198:201], v[48:51]
	v_mfma_f32_16x16x32_bf16 v[44:47], v[174:177], v[218:221], v[44:47]
	v_mfma_f32_16x16x32_bf16 v[40:43], v[182:185], v[218:221], v[40:43]
	v_mfma_f32_16x16x32_bf16 v[36:39], v[174:177], v[226:229], v[36:39]
	v_mfma_f32_16x16x32_bf16 v[32:35], v[182:185], v[226:229], v[32:35]
	v_mfma_f32_16x16x32_bf16 v[60:63], v[178:181], v[194:197], v[60:63]
	v_mfma_f32_16x16x32_bf16 v[56:59], v[186:189], v[194:197], v[56:59]
	v_mfma_f32_16x16x32_bf16 v[52:55], v[178:181], v[202:205], v[52:55]
	v_mfma_f32_16x16x32_bf16 v[48:51], v[186:189], v[202:205], v[48:51]
	v_mfma_f32_16x16x32_bf16 v[44:47], v[178:181], v[222:225], v[44:47]
	v_mfma_f32_16x16x32_bf16 v[40:43], v[186:189], v[222:225], v[40:43]
	v_mfma_f32_16x16x32_bf16 v[36:39], v[178:181], v[230:233], v[36:39]
	v_mfma_f32_16x16x32_bf16 v[32:35], v[186:189], v[230:233], v[32:35]
	s_barrier
	v_readfirstlane_b32 s18, v169
	v_add_u32_e32 v134, 0x2000, v169
	v_lshl_add_u64 v[136:137], v[208:209], 0, s[58:59]
	s_mov_b32 m0, s18
	v_readfirstlane_b32 s18, v134
	global_load_lds_dwordx4 v[136:137], off
	v_lshl_add_u64 v[136:137], v[210:211], 0, s[58:59]
	s_mov_b32 m0, s18
	s_nop 0
	global_load_lds_dwordx4 v[136:137], off
	s_waitcnt vmcnt(6)
	s_barrier
	v_mfma_f32_16x16x32_bf16 v[28:31], v[234:237], v[190:193], v[28:31]
	v_mfma_f32_16x16x32_bf16 v[24:27], v[242:245], v[190:193], v[24:27]
	v_mfma_f32_16x16x32_bf16 v[20:23], v[234:237], v[198:201], v[20:23]
	v_mfma_f32_16x16x32_bf16 v[16:19], v[242:245], v[198:201], v[16:19]
	v_mfma_f32_16x16x32_bf16 v[12:15], v[234:237], v[218:221], v[12:15]
	v_mfma_f32_16x16x32_bf16 v[8:11], v[242:245], v[218:221], v[8:11]
	v_mfma_f32_16x16x32_bf16 v[4:7], v[234:237], v[226:229], v[4:7]
	v_mfma_f32_16x16x32_bf16 v[0:3], v[242:245], v[226:229], v[0:3]
	v_mfma_f32_16x16x32_bf16 v[28:31], v[238:241], v[194:197], v[28:31]
	v_mfma_f32_16x16x32_bf16 v[24:27], v[246:249], v[194:197], v[24:27]
	v_mfma_f32_16x16x32_bf16 v[20:23], v[238:241], v[202:205], v[20:23]
	v_mfma_f32_16x16x32_bf16 v[16:19], v[246:249], v[202:205], v[16:19]
	v_mfma_f32_16x16x32_bf16 v[12:15], v[238:241], v[222:225], v[12:15]
	v_mfma_f32_16x16x32_bf16 v[8:11], v[246:249], v[222:225], v[8:11]
	v_mfma_f32_16x16x32_bf16 v[4:7], v[238:241], v[230:233], v[4:7]
	v_mfma_f32_16x16x32_bf16 v[0:3], v[246:249], v[230:233], v[0:3]
	s_add_i32 s15, s15, 2
	v_lshl_add_u64 v[146:147], v[146:147], 0, s[20:21]
	v_lshl_add_u64 v[148:149], v[148:149], 0, s[20:21]
	v_lshl_add_u64 v[150:151], v[150:151], 0, s[20:21]
	s_cmp_lt_u32 s15, 28
	v_lshl_add_u64 v[152:153], v[152:153], 0, s[20:21]
	s_cbranch_scc1 .Lkrot_236
	s_barrier
	s_add_u32 s18, s50, 0x80f80
	s_addc_u32 s19, s51, 0
	v_lshl_add_u64 v[136:137], s[18:19], 0, v[140:141]
	v_readfirstlane_b32 s15, v171
	v_lshl_add_u64 v[130:131], v[130:131], 1, v[136:137]
	s_mov_b32 m0, s15
	ds_read_b128 v[146:149], v170
	ds_read_b128 v[150:153], v170 offset:1024
	ds_read_b128 v[174:177], v170 offset:2048
	ds_read_b128 v[178:181], v170 offset:3072
	ds_read_b128 v[182:185], v162
	ds_read_b128 v[186:189], v162 offset:1024
	ds_read_b128 v[190:193], v161
	ds_read_b128 v[194:197], v161 offset:1024
	ds_read_b128 v[198:201], v160
	ds_read_b128 v[202:205], v160 offset:1024
	ds_read_b128 v[218:221], v159
	ds_read_b128 v[222:225], v159 offset:1024
	global_load_lds_dwordx4 v[130:131], off
	v_lshl_add_u64 v[130:131], s[18:19], 0, v[144:145]
	v_readfirstlane_b32 s15, v172
	v_lshl_add_u64 v[130:131], v[142:143], 1, v[130:131]
	s_mov_b32 m0, s15
	s_nop 0
	global_load_lds_dwordx4 v[130:131], off
	s_barrier
	s_waitcnt lgkmcnt(0)
	s_waitcnt lgkmcnt(0)
	v_mfma_f32_16x16x32_bf16 v[124:127], v[146:149], v[182:185], v[124:127]
	v_mfma_f32_16x16x32_bf16 v[120:123], v[174:177], v[182:185], v[120:123]
	v_mfma_f32_16x16x32_bf16 v[116:119], v[146:149], v[190:193], v[116:119]
	v_mfma_f32_16x16x32_bf16 v[112:115], v[174:177], v[190:193], v[112:115]
	v_mfma_f32_16x16x32_bf16 v[108:111], v[146:149], v[198:201], v[108:111]
	v_mfma_f32_16x16x32_bf16 v[104:107], v[174:177], v[198:201], v[104:107]
	v_mfma_f32_16x16x32_bf16 v[100:103], v[146:149], v[218:221], v[100:103]
	v_mfma_f32_16x16x32_bf16 v[96:99], v[174:177], v[218:221], v[96:99]
	v_mfma_f32_16x16x32_bf16 v[124:127], v[150:153], v[186:189], v[124:127]
	v_mfma_f32_16x16x32_bf16 v[120:123], v[178:181], v[186:189], v[120:123]
	v_mfma_f32_16x16x32_bf16 v[116:119], v[150:153], v[194:197], v[116:119]
	v_mfma_f32_16x16x32_bf16 v[112:115], v[178:181], v[194:197], v[112:115]
	v_mfma_f32_16x16x32_bf16 v[108:111], v[150:153], v[202:205], v[108:111]
	v_mfma_f32_16x16x32_bf16 v[104:107], v[178:181], v[202:205], v[104:107]
	v_mfma_f32_16x16x32_bf16 v[100:103], v[150:153], v[222:225], v[100:103]
	v_mfma_f32_16x16x32_bf16 v[96:99], v[178:181], v[222:225], v[96:99]
	s_barrier
	ds_read_b128 v[140:143], v168
	ds_read_b128 v[170:173], v168 offset:1024
	ds_read_b128 v[226:229], v168 offset:2048
	ds_read_b128 v[166:169], v168 offset:3072
	s_barrier
; #define LDA(dst, b, h) UFOR(m, 4) UFOR(k, 2) \
;     dst[m][k] = *reinterpret_cast<const bf16x8*>((char*)SA(b, h) + lds_byte(wr * 64 + m * 16 + fr, k * 32 + fq * 8))
; #define LDB(dst, b, h) UFOR(n, 2) UFOR(k, 2) \
;     dst[n][k] = *reinterpret_cast<const bf16x8*>((char*)SB(b, h) + lds_byte(wc * 32 + n * 16 + fr, k * 32 + fq * 8))
; #define MMA(ai, bj, At, Bq) do { __builtin_amdgcn_s_setprio(1); \
;     UFOR(m, 4) UFOR(n, 2) UFOR(k, 2) \
;       acc[ai][bj][m][n] = __builtin_amdgcn_mfma_f32_16x16x32_bf16(Bq[n][k], At[m][k], acc[ai][bj][m][n], 0, 0, 0); \
;     __builtin_amdgcn_s_setprio(0); } while (0)
; #define WAIT_V(n) asm volatile("s_waitcnt vmcnt(" #n ")" ::: "memory")
; #define WAIT_L(n) asm volatile("s_waitcnt lgkmcnt(" #n ")" ::: "memory")
; #define BAR __builtin_amdgcn_s_barrier()
; template <int EPI, int K, int KL> ...
;     ...
;     LDB(B1, 0, 1); BAR; WAIT_L(0); MMA(0, 1, At, B1); BAR;
;     LDA(At, 0, 1); WAIT_V(4); BAR; WAIT_L(0); MMA(1, 0, At, B0); MMA(1, 1, At, B1); BAR; }
;   { LDB(B0, 1, 0); LDA(At, 1, 0); WAIT_V(2); BAR; WAIT_L(0); MMA(0, 0, At, B0); BAR;
;     LDB(B1, 1, 1); WAIT_V(0); BAR; WAIT_L(0); MMA(0, 1, At, B1); BAR;
;     LDA(At, 1, 1); BAR; WAIT_L(0); MMA(1, 0, At, B0); MMA(1, 1, At, B1); BAR; }
	s_waitcnt lgkmcnt(0)
	s_waitcnt lgkmcnt(0)
	v_mfma_f32_16x16x32_bf16 v[92:95], v[140:143], v[182:185], v[92:95]
	v_mfma_f32_16x16x32_bf16 v[88:91], v[226:229], v[182:185], v[88:91]
	v_mfma_f32_16x16x32_bf16 v[84:87], v[140:143], v[190:193], v[84:87]
	v_mfma_f32_16x16x32_bf16 v[80:83], v[226:229], v[190:193], v[80:83]
	v_mfma_f32_16x16x32_bf16 v[76:79], v[140:143], v[198:201], v[76:79]
	v_mfma_f32_16x16x32_bf16 v[72:75], v[226:229], v[198:201], v[72:75]
	v_mfma_f32_16x16x32_bf16 v[68:71], v[140:143], v[218:221], v[68:71]
	v_mfma_f32_16x16x32_bf16 v[64:67], v[226:229], v[218:221], v[64:67]
	v_mfma_f32_16x16x32_bf16 v[92:95], v[170:173], v[186:189], v[92:95]
	v_mfma_f32_16x16x32_bf16 v[88:91], v[166:169], v[186:189], v[88:91]
	v_mfma_f32_16x16x32_bf16 v[84:87], v[170:173], v[194:197], v[84:87]
	v_mfma_f32_16x16x32_bf16 v[80:83], v[166:169], v[194:197], v[80:83]
	v_mfma_f32_16x16x32_bf16 v[76:79], v[170:173], v[202:205], v[76:79]
	v_mfma_f32_16x16x32_bf16 v[72:75], v[166:169], v[202:205], v[72:75]
	v_mfma_f32_16x16x32_bf16 v[68:71], v[170:173], v[222:225], v[68:71]
	v_mfma_f32_16x16x32_bf16 v[64:67], v[166:169], v[222:225], v[64:67]
	s_barrier
	ds_read_b128 v[182:185], v162 offset:16384
	ds_read_b128 v[186:189], v162 offset:17408
	ds_read_b128 v[190:193], v161 offset:16384
	ds_read_b128 v[194:197], v161 offset:17408
	ds_read_b128 v[198:201], v160 offset:16384
	ds_read_b128 v[202:205], v160 offset:17408
	ds_read_b128 v[218:221], v159 offset:16384
	ds_read_b128 v[222:225], v159 offset:17408
	s_waitcnt vmcnt(4)
	s_barrier
	s_waitcnt lgkmcnt(0)
	s_waitcnt lgkmcnt(0)
	v_mfma_f32_16x16x32_bf16 v[60:63], v[146:149], v[182:185], v[60:63]
	v_mfma_f32_16x16x32_bf16 v[56:59], v[174:177], v[182:185], v[56:59]
	v_mfma_f32_16x16x32_bf16 v[52:55], v[146:149], v[190:193], v[52:55]
	v_mfma_f32_16x16x32_bf16 v[48:51], v[174:177], v[190:193], v[48:51]
	v_mfma_f32_16x16x32_bf16 v[44:47], v[146:149], v[198:201], v[44:47]
	v_mfma_f32_16x16x32_bf16 v[40:43], v[174:177], v[198:201], v[40:43]
	v_mfma_f32_16x16x32_bf16 v[36:39], v[146:149], v[218:221], v[36:39]
	v_mfma_f32_16x16x32_bf16 v[32:35], v[174:177], v[218:221], v[32:35]
	v_mfma_f32_16x16x32_bf16 v[60:63], v[150:153], v[186:189], v[60:63]
	v_mfma_f32_16x16x32_bf16 v[56:59], v[178:181], v[186:189], v[56:59]
	v_mfma_f32_16x16x32_bf16 v[52:55], v[150:153], v[194:197], v[52:55]
	v_mfma_f32_16x16x32_bf16 v[48:51], v[178:181], v[194:197], v[48:51]
	v_mfma_f32_16x16x32_bf16 v[44:47], v[150:153], v[202:205], v[44:47]
	v_mfma_f32_16x16x32_bf16 v[40:43], v[178:181], v[202:205], v[40:43]
	v_mfma_f32_16x16x32_bf16 v[36:39], v[150:153], v[222:225], v[36:39]
	v_mfma_f32_16x16x32_bf16 v[32:35], v[178:181], v[222:225], v[32:35]
	v_mfma_f32_16x16x32_bf16 v[28:31], v[140:143], v[182:185], v[28:31]
	v_mfma_f32_16x16x32_bf16 v[24:27], v[226:229], v[182:185], v[24:27]
	v_mfma_f32_16x16x32_bf16 v[20:23], v[140:143], v[190:193], v[20:23]
	v_mfma_f32_16x16x32_bf16 v[16:19], v[226:229], v[190:193], v[16:19]
	v_mfma_f32_16x16x32_bf16 v[12:15], v[140:143], v[198:201], v[12:15]
	v_mfma_f32_16x16x32_bf16 v[8:11], v[226:229], v[198:201], v[8:11]
	v_mfma_f32_16x16x32_bf16 v[4:7], v[140:143], v[218:221], v[4:7]
	v_mfma_f32_16x16x32_bf16 v[0:3], v[226:229], v[218:221], v[0:3]
	v_mfma_f32_16x16x32_bf16 v[28:31], v[170:173], v[186:189], v[28:31]
	v_mfma_f32_16x16x32_bf16 v[24:27], v[166:169], v[186:189], v[24:27]
	v_mfma_f32_16x16x32_bf16 v[20:23], v[170:173], v[194:197], v[20:23]
	v_mfma_f32_16x16x32_bf16 v[16:19], v[166:169], v[194:197], v[16:19]
	v_mfma_f32_16x16x32_bf16 v[12:15], v[170:173], v[202:205], v[12:15]
	v_mfma_f32_16x16x32_bf16 v[8:11], v[166:169], v[202:205], v[8:11]
	v_mfma_f32_16x16x32_bf16 v[4:7], v[170:173], v[222:225], v[4:7]
	v_mfma_f32_16x16x32_bf16 v[0:3], v[166:169], v[222:225], v[0:3]
	s_barrier
	ds_read_b128 v[140:143], v164
	ds_read_b128 v[144:147], v164 offset:1024
	ds_read_b128 v[148:151], v164 offset:2048
	ds_read_b128 v[164:167], v164 offset:3072
	ds_read_b128 v[168:171], v162 offset:32768
	ds_read_b128 v[172:175], v162 offset:33792
	ds_read_b128 v[176:179], v161 offset:32768
	ds_read_b128 v[180:183], v161 offset:33792
	ds_read_b128 v[184:187], v160 offset:32768
	ds_read_b128 v[188:191], v160 offset:33792
	ds_read_b128 v[192:195], v159 offset:32768
	ds_read_b128 v[196:199], v159 offset:33792
	s_waitcnt vmcnt(2)
	s_barrier
; #define STAGE(P, BASE, br, kt) STAGET(tid_, P, BASE, br, kt)
; #define LDA(dst, b, h) UFOR(m, 4) UFOR(k, 2) \
;     dst[m][k] = *reinterpret_cast<const bf16x8*>((char*)SA(b, h) + lds_byte(wr * 64 + m * 16 + fr, k * 32 + fq * 8))
; #define LDB(dst, b, h) UFOR(n, 2) UFOR(k, 2) \
;     dst[n][k] = *reinterpret_cast<const bf16x8*>((char*)SB(b, h) + lds_byte(wc * 32 + n * 16 + fr, k * 32 + fq * 8))
; #define MMA(ai, bj, At, Bq) do { __builtin_amdgcn_s_setprio(1); \
;     UFOR(m, 4) UFOR(n, 2) UFOR(k, 2) \
;       acc[ai][bj][m][n] = __builtin_amdgcn_mfma_f32_16x16x32_bf16(Bq[n][k], At[m][k], acc[ai][bj][m][n], 0, 0, 0); \
;     __builtin_amdgcn_s_setprio(0); } while (0)
; #define WAIT_V(n) asm volatile("s_waitcnt vmcnt(" #n ")" ::: "memory")
; #define WAIT_L(n) asm volatile("s_waitcnt lgkmcnt(" #n ")" ::: "memory")
; #define BAR __builtin_amdgcn_s_barrier()
; template <int EPI, int K, int KL> ...
;     ...
;   { LDB(B0, 0, 0); LDA(At, 0, 0); STAGE(SA(1, 1), A, brow + HALF, nt - 1);
;     BAR; WAIT_L(0); MMA(0, 0, At, B0); BAR;
;     LDB(B1, 0, 1); BAR; WAIT_L(0); MMA(0, 1, At, B1); BAR;
;     LDA(At, 0, 1); WAIT_V(4); BAR; WAIT_L(0); MMA(1, 0, At, B0); MMA(1, 1, At, B1); BAR; }
;   { LDB(B0, 1, 0); LDA(At, 1, 0); WAIT_V(2); BAR; WAIT_L(0); MMA(0, 0, At, B0); BAR;
;     LDB(B1, 1, 1); WAIT_V(0); BAR; WAIT_L(0); MMA(0, 1, At, B1); BAR;
;     LDA(At, 1, 1); BAR; WAIT_L(0); MMA(1, 0, At, B0); MMA(1, 1, At, B1); BAR; }
;   if (wr == 0) BAR;
	s_waitcnt lgkmcnt(0)
	s_waitcnt lgkmcnt(0)
	v_mfma_f32_16x16x32_bf16 v[124:127], v[140:143], v[168:171], v[124:127]
	v_mfma_f32_16x16x32_bf16 v[120:123], v[148:151], v[168:171], v[120:123]
	v_mfma_f32_16x16x32_bf16 v[116:119], v[140:143], v[176:179], v[116:119]
	v_mfma_f32_16x16x32_bf16 v[112:115], v[148:151], v[176:179], v[112:115]
	v_mfma_f32_16x16x32_bf16 v[108:111], v[140:143], v[184:187], v[108:111]
	v_mfma_f32_16x16x32_bf16 v[104:107], v[148:151], v[184:187], v[104:107]
	v_mfma_f32_16x16x32_bf16 v[100:103], v[140:143], v[192:195], v[100:103]
	v_mfma_f32_16x16x32_bf16 v[96:99], v[148:151], v[192:195], v[96:99]
	v_mfma_f32_16x16x32_bf16 v[124:127], v[144:147], v[172:175], v[124:127]
	v_mfma_f32_16x16x32_bf16 v[120:123], v[164:167], v[172:175], v[120:123]
	v_mfma_f32_16x16x32_bf16 v[116:119], v[144:147], v[180:183], v[116:119]
	v_mfma_f32_16x16x32_bf16 v[112:115], v[164:167], v[180:183], v[112:115]
	v_mfma_f32_16x16x32_bf16 v[108:111], v[144:147], v[188:191], v[108:111]
	v_mfma_f32_16x16x32_bf16 v[104:107], v[164:167], v[188:191], v[104:107]
	v_mfma_f32_16x16x32_bf16 v[100:103], v[144:147], v[196:199], v[100:103]
	v_mfma_f32_16x16x32_bf16 v[96:99], v[164:167], v[196:199], v[96:99]
	s_barrier
	ds_read_b128 v[200:203], v163
	ds_read_b128 v[218:221], v163 offset:1024
	ds_read_b128 v[222:225], v163 offset:2048
	ds_read_b128 v[226:229], v163 offset:3072
	s_waitcnt vmcnt(0)
	s_barrier
	s_waitcnt lgkmcnt(0)
	s_waitcnt lgkmcnt(0)
	v_mfma_f32_16x16x32_bf16 v[92:95], v[200:203], v[168:171], v[92:95]
	v_mfma_f32_16x16x32_bf16 v[88:91], v[222:225], v[168:171], v[88:91]
	v_mfma_f32_16x16x32_bf16 v[84:87], v[200:203], v[176:179], v[84:87]
	v_mfma_f32_16x16x32_bf16 v[80:83], v[222:225], v[176:179], v[80:83]
	v_mfma_f32_16x16x32_bf16 v[76:79], v[200:203], v[184:187], v[76:79]
	v_mfma_f32_16x16x32_bf16 v[72:75], v[222:225], v[184:187], v[72:75]
	v_mfma_f32_16x16x32_bf16 v[68:71], v[200:203], v[192:195], v[68:71]
	v_mfma_f32_16x16x32_bf16 v[64:67], v[222:225], v[192:195], v[64:67]
	v_mfma_f32_16x16x32_bf16 v[92:95], v[218:221], v[172:175], v[92:95]
	v_mfma_f32_16x16x32_bf16 v[88:91], v[226:229], v[172:175], v[88:91]
	v_mfma_f32_16x16x32_bf16 v[84:87], v[218:221], v[180:183], v[84:87]
	v_mfma_f32_16x16x32_bf16 v[80:83], v[226:229], v[180:183], v[80:83]
	v_mfma_f32_16x16x32_bf16 v[76:79], v[218:221], v[188:191], v[76:79]
	v_mfma_f32_16x16x32_bf16 v[72:75], v[226:229], v[188:191], v[72:75]
	v_mfma_f32_16x16x32_bf16 v[68:71], v[218:221], v[196:199], v[68:71]
	v_mfma_f32_16x16x32_bf16 v[64:67], v[226:229], v[196:199], v[64:67]
	s_barrier
	ds_read_b128 v[168:171], v162 offset:49152
	ds_read_b128 v[172:175], v162 offset:50176
	ds_read_b128 v[176:179], v161 offset:49152
	ds_read_b128 v[180:183], v161 offset:50176
	ds_read_b128 v[184:187], v160 offset:49152
	ds_read_b128 v[160:163], v160 offset:50176
	ds_read_b128 v[188:191], v159 offset:49152
	ds_read_b128 v[156:159], v159 offset:50176
	s_barrier
	s_waitcnt lgkmcnt(0)
	s_waitcnt lgkmcnt(0)
	v_mfma_f32_16x16x32_bf16 v[60:63], v[140:143], v[168:171], v[60:63]
	v_mfma_f32_16x16x32_bf16 v[56:59], v[148:151], v[168:171], v[56:59]
	v_mfma_f32_16x16x32_bf16 v[52:55], v[140:143], v[176:179], v[52:55]
	v_mfma_f32_16x16x32_bf16 v[48:51], v[148:151], v[176:179], v[48:51]
	v_mfma_f32_16x16x32_bf16 v[44:47], v[140:143], v[184:187], v[44:47]
	v_mfma_f32_16x16x32_bf16 v[40:43], v[148:151], v[184:187], v[40:43]
	v_mfma_f32_16x16x32_bf16 v[36:39], v[140:143], v[188:191], v[36:39]
	v_mfma_f32_16x16x32_bf16 v[32:35], v[148:151], v[188:191], v[32:35]
	v_mfma_f32_16x16x32_bf16 v[60:63], v[144:147], v[172:175], v[60:63]
	v_mfma_f32_16x16x32_bf16 v[56:59], v[164:167], v[172:175], v[56:59]
	v_mfma_f32_16x16x32_bf16 v[52:55], v[144:147], v[180:183], v[52:55]
	v_mfma_f32_16x16x32_bf16 v[48:51], v[164:167], v[180:183], v[48:51]
	v_mfma_f32_16x16x32_bf16 v[44:47], v[144:147], v[160:163], v[44:47]
	v_mfma_f32_16x16x32_bf16 v[40:43], v[164:167], v[160:163], v[40:43]
	v_mfma_f32_16x16x32_bf16 v[36:39], v[144:147], v[156:159], v[36:39]
	v_mfma_f32_16x16x32_bf16 v[32:35], v[164:167], v[156:159], v[32:35]
	v_mfma_f32_16x16x32_bf16 v[28:31], v[200:203], v[168:171], v[28:31]
	v_mfma_f32_16x16x32_bf16 v[24:27], v[222:225], v[168:171], v[24:27]
	v_mfma_f32_16x16x32_bf16 v[20:23], v[200:203], v[176:179], v[20:23]
	v_mfma_f32_16x16x32_bf16 v[16:19], v[222:225], v[176:179], v[16:19]
	v_mfma_f32_16x16x32_bf16 v[12:15], v[200:203], v[184:187], v[12:15]
	v_mfma_f32_16x16x32_bf16 v[8:11], v[222:225], v[184:187], v[8:11]
	v_mfma_f32_16x16x32_bf16 v[4:7], v[200:203], v[188:191], v[4:7]
	v_mfma_f32_16x16x32_bf16 v[0:3], v[222:225], v[188:191], v[0:3]
	v_mfma_f32_16x16x32_bf16 v[28:31], v[218:221], v[172:175], v[28:31]
	v_mfma_f32_16x16x32_bf16 v[24:27], v[226:229], v[172:175], v[24:27]
	v_mfma_f32_16x16x32_bf16 v[20:23], v[218:221], v[180:183], v[20:23]
	v_mfma_f32_16x16x32_bf16 v[16:19], v[226:229], v[180:183], v[16:19]
	v_mfma_f32_16x16x32_bf16 v[12:15], v[218:221], v[160:163], v[12:15]
	v_mfma_f32_16x16x32_bf16 v[8:11], v[226:229], v[160:163], v[8:11]
	v_mfma_f32_16x16x32_bf16 v[4:7], v[218:221], v[156:159], v[4:7]
	v_mfma_f32_16x16x32_bf16 v[0:3], v[226:229], v[156:159], v[0:3]
	s_movk_i32 s15, 0x100
	v_cmp_gt_u32_e32 vcc, s15, v129
	s_barrier
	s_and_saveexec_b64 s[50:51], vcc
	s_cbranch_execz .LBB0_239
	s_barrier

; #define STAGE(P, BASE, br, kt) STAGET(tid_, P, BASE, br, kt)
; #define LDA(dst, b, h) UFOR(m, 4) UFOR(k, 2) \
;     dst[m][k] = *reinterpret_cast<const bf16x8*>((char*)SA(b, h) + lds_byte(wr * 64 + m * 16 + fr, k * 32 + fq * 8))
; #define LDB(dst, b, h) UFOR(n, 2) UFOR(k, 2) \
;     dst[n][k] = *reinterpret_cast<const bf16x8*>((char*)SB(b, h) + lds_byte(wc * 32 + n * 16 + fr, k * 32 + fq * 8))
; #define MMA(ai, bj, At, Bq) do { __builtin_amdgcn_s_setprio(1); \
;     UFOR(m, 4) UFOR(n, 2) UFOR(k, 2) \
;       acc[ai][bj][m][n] = __builtin_amdgcn_mfma_f32_16x16x32_bf16(Bq[n][k], At[m][k], acc[ai][bj][m][n], 0, 0, 0); \
;     __builtin_amdgcn_s_setprio(0); } while (0)
; #define WAIT_L(n) asm volatile("s_waitcnt lgkmcnt(" #n ")" ::: "memory")
; #define BAR __builtin_amdgcn_s_barrier()
; #define SCHED __builtin_amdgcn_sched_barrier(0)
; template <int EPI, int K, int KL> ...
;     ...
;   for (int t = 0; t < nt - 2; t += 2) {
;     LDB(B0, 0, 0); SCHED; LDA(At, 0, 0); STAGE(SA(1, 1), A, brow + HALF, t + 1);
;     WAIT_L(8); BAR; WAIT_L(0); MMA(0, 0, At, B0); BAR; SCHED;
;     LDB(B1, 0, 1); STAGE(SB(0, 0), Bt, bcol, t + 2);
;     BAR; WAIT_L(0); MMA(0, 1, At, B1); BAR;
;     LDA(At, 0, 1); STAGE(SA(0, 0), A, brow, t + 2);
;     BAR; WAIT_L(0); MMA(1, 0, At, B0); BAR; SCHED;
.LBB0_940:
	ds_read_b128 v[174:177], v170
	ds_read_b128 v[178:181], v170 offset:1024
	ds_read_b128 v[182:185], v170 offset:2048
	ds_read_b128 v[186:189], v170 offset:3072
	ds_read_b128 v[190:193], v162
	ds_read_b128 v[194:197], v162 offset:1024
	ds_read_b128 v[198:201], v161
	ds_read_b128 v[202:205], v161 offset:1024
	ds_read_b128 v[218:221], v160
	ds_read_b128 v[222:225], v160 offset:1024
	ds_read_b128 v[226:229], v159
	ds_read_b128 v[230:233], v159 offset:1024
	v_add_u32_e32 v171, 0xc000, v157
	v_lshl_add_u64 v[136:137], s[92:93], 0, v[148:149]
	v_readfirstlane_b32 s60, v171
	v_lshl_add_u64 v[138:139], v[136:137], 0, s[88:89]
	s_mov_b32 m0, s60
	v_add_u32_e32 v172, 0xe000, v157
	global_load_lds_dwordx4 v[138:139], off
	v_lshl_add_u64 v[138:139], s[92:93], 0, v[150:151]
	v_readfirstlane_b32 s60, v172
	v_lshl_add_u64 v[208:209], v[138:139], 0, s[88:89]
	s_mov_b32 m0, s60
	s_nop 0
	global_load_lds_dwordx4 v[208:209], off
	s_waitcnt lgkmcnt(8)
	s_barrier
	s_waitcnt lgkmcnt(0)
	v_mfma_f32_16x16x32_bf16 v[124:127], v[174:177], v[190:193], v[124:127]
	v_mfma_f32_16x16x32_bf16 v[120:123], v[182:185], v[190:193], v[120:123]
	v_mfma_f32_16x16x32_bf16 v[116:119], v[174:177], v[198:201], v[116:119]
	v_mfma_f32_16x16x32_bf16 v[112:115], v[182:185], v[198:201], v[112:115]
	v_mfma_f32_16x16x32_bf16 v[108:111], v[174:177], v[218:221], v[108:111]
	v_mfma_f32_16x16x32_bf16 v[104:107], v[182:185], v[218:221], v[104:107]
	v_mfma_f32_16x16x32_bf16 v[100:103], v[174:177], v[226:229], v[100:103]
	v_mfma_f32_16x16x32_bf16 v[96:99], v[182:185], v[226:229], v[96:99]
	v_mfma_f32_16x16x32_bf16 v[124:127], v[178:181], v[194:197], v[124:127]
	v_mfma_f32_16x16x32_bf16 v[120:123], v[186:189], v[194:197], v[120:123]
	v_mfma_f32_16x16x32_bf16 v[116:119], v[178:181], v[202:205], v[116:119]
	v_mfma_f32_16x16x32_bf16 v[112:115], v[186:189], v[202:205], v[112:115]
	v_mfma_f32_16x16x32_bf16 v[108:111], v[178:181], v[222:225], v[108:111]
	v_mfma_f32_16x16x32_bf16 v[104:107], v[186:189], v[222:225], v[104:107]
	v_mfma_f32_16x16x32_bf16 v[100:103], v[178:181], v[230:233], v[100:103]
	v_mfma_f32_16x16x32_bf16 v[96:99], v[186:189], v[230:233], v[96:99]
	s_barrier
	ds_read_b128 v[234:237], v168
	ds_read_b128 v[238:241], v168 offset:1024
	ds_read_b128 v[242:245], v168 offset:2048
	ds_read_b128 v[246:249], v168 offset:3072
	v_lshl_add_u64 v[208:209], s[92:93], 0, v[144:145]
	v_readfirstlane_b32 s60, v156
	v_lshl_add_u64 v[210:211], v[208:209], 0, s[62:63]
	s_mov_b32 m0, s60
	v_add_u32_e32 v134, 0x2000, v156
	global_load_lds_dwordx4 v[210:211], off
	v_lshl_add_u64 v[210:211], s[92:93], 0, v[146:147]
	v_readfirstlane_b32 s60, v134
	v_lshl_add_u64 v[214:215], v[210:211], 0, s[62:63]
	s_mov_b32 m0, s60
	s_nop 0
	global_load_lds_dwordx4 v[214:215], off
	s_barrier
	s_waitcnt lgkmcnt(0)
	v_mfma_f32_16x16x32_bf16 v[92:95], v[234:237], v[190:193], v[92:95]
	v_mfma_f32_16x16x32_bf16 v[88:91], v[242:245], v[190:193], v[88:91]
	v_mfma_f32_16x16x32_bf16 v[84:87], v[234:237], v[198:201], v[84:87]
	v_mfma_f32_16x16x32_bf16 v[80:83], v[242:245], v[198:201], v[80:83]
	v_mfma_f32_16x16x32_bf16 v[76:79], v[234:237], v[218:221], v[76:79]
	v_mfma_f32_16x16x32_bf16 v[72:75], v[242:245], v[218:221], v[72:75]
	v_mfma_f32_16x16x32_bf16 v[68:71], v[234:237], v[226:229], v[68:71]
	v_mfma_f32_16x16x32_bf16 v[64:67], v[242:245], v[226:229], v[64:67]
	v_mfma_f32_16x16x32_bf16 v[92:95], v[238:241], v[194:197], v[92:95]
	v_mfma_f32_16x16x32_bf16 v[88:91], v[246:249], v[194:197], v[88:91]
	v_mfma_f32_16x16x32_bf16 v[84:87], v[238:241], v[202:205], v[84:87]
	v_mfma_f32_16x16x32_bf16 v[80:83], v[246:249], v[202:205], v[80:83]
	v_mfma_f32_16x16x32_bf16 v[76:79], v[238:241], v[222:225], v[76:79]
	v_mfma_f32_16x16x32_bf16 v[72:75], v[246:249], v[222:225], v[72:75]
	v_mfma_f32_16x16x32_bf16 v[68:71], v[238:241], v[230:233], v[68:71]
	v_mfma_f32_16x16x32_bf16 v[64:67], v[246:249], v[230:233], v[64:67]
	v_readfirstlane_b32 s60, v157
	v_add_u32_e32 v134, 0x2000, v157
	v_lshl_add_u64 v[214:215], v[136:137], 0, s[8:9]
	s_mov_b32 m0, s60
	v_readfirstlane_b32 s60, v134
	s_barrier
	ds_read_b128 v[190:193], v162 offset:16384
	ds_read_b128 v[194:197], v162 offset:17408
	ds_read_b128 v[198:201], v161 offset:16384
	ds_read_b128 v[202:205], v161 offset:17408
	ds_read_b128 v[218:221], v160 offset:16384
	ds_read_b128 v[222:225], v160 offset:17408
	ds_read_b128 v[226:229], v159 offset:16384
	ds_read_b128 v[230:233], v159 offset:17408
	global_load_lds_dwordx4 v[214:215], off
	v_lshl_add_u64 v[214:215], v[138:139], 0, s[8:9]
	s_mov_b32 m0, s60
	s_nop 0
	global_load_lds_dwordx4 v[214:215], off
	s_barrier
	s_waitcnt lgkmcnt(0)
	v_mfma_f32_16x16x32_bf16 v[60:63], v[174:177], v[190:193], v[60:63]
	v_mfma_f32_16x16x32_bf16 v[56:59], v[182:185], v[190:193], v[56:59]
	v_mfma_f32_16x16x32_bf16 v[52:55], v[174:177], v[198:201], v[52:55]
	v_mfma_f32_16x16x32_bf16 v[48:51], v[182:185], v[198:201], v[48:51]
	v_mfma_f32_16x16x32_bf16 v[44:47], v[174:177], v[218:221], v[44:47]
	v_mfma_f32_16x16x32_bf16 v[40:43], v[182:185], v[218:221], v[40:43]
	v_mfma_f32_16x16x32_bf16 v[36:39], v[174:177], v[226:229], v[36:39]
	v_mfma_f32_16x16x32_bf16 v[32:35], v[182:185], v[226:229], v[32:35]
	v_mfma_f32_16x16x32_bf16 v[60:63], v[178:181], v[194:197], v[60:63]
	v_mfma_f32_16x16x32_bf16 v[56:59], v[186:189], v[194:197], v[56:59]
	v_mfma_f32_16x16x32_bf16 v[52:55], v[178:181], v[202:205], v[52:55]
	v_mfma_f32_16x16x32_bf16 v[48:51], v[186:189], v[202:205], v[48:51]
	v_mfma_f32_16x16x32_bf16 v[44:47], v[178:181], v[222:225], v[44:47]
	v_mfma_f32_16x16x32_bf16 v[40:43], v[186:189], v[222:225], v[40:43]
	v_mfma_f32_16x16x32_bf16 v[36:39], v[178:181], v[230:233], v[36:39]
	v_mfma_f32_16x16x32_bf16 v[32:35], v[186:189], v[230:233], v[32:35]
	s_barrier
; #define STAGE(P, BASE, br, kt) STAGET(tid_, P, BASE, br, kt)
; #define LDA(dst, b, h) UFOR(m, 4) UFOR(k, 2) \
;     dst[m][k] = *reinterpret_cast<const bf16x8*>((char*)SA(b, h) + lds_byte(wr * 64 + m * 16 + fr, k * 32 + fq * 8))
; #define LDB(dst, b, h) UFOR(n, 2) UFOR(k, 2) \
;     dst[n][k] = *reinterpret_cast<const bf16x8*>((char*)SB(b, h) + lds_byte(wc * 32 + n * 16 + fr, k * 32 + fq * 8))
; #define MMA(ai, bj, At, Bq) do { __builtin_amdgcn_s_setprio(1); \
;     UFOR(m, 4) UFOR(n, 2) UFOR(k, 2) \
;       acc[ai][bj][m][n] = __builtin_amdgcn_mfma_f32_16x16x32_bf16(Bq[n][k], At[m][k], acc[ai][bj][m][n], 0, 0, 0); \
;     __builtin_amdgcn_s_setprio(0); } while (0)
; #define WAIT_V(n) asm volatile("s_waitcnt vmcnt(" #n ")" ::: "memory")
; #define WAIT_L(n) asm volatile("s_waitcnt lgkmcnt(" #n ")" ::: "memory")
; #define BAR __builtin_amdgcn_s_barrier()
; #define SCHED __builtin_amdgcn_sched_barrier(0)
; template <int EPI, int K, int KL> ...
;     ...
;     BAR; WAIT_L(0); MMA(1, 0, At, B0); BAR; SCHED;
;     STAGE(SB(0, 1), Bt, bcol + HALF, t + 2);
;     WAIT_V(6); BAR; MMA(1, 1, At, B1); BAR;
;     LDB(B0, 1, 0); SCHED; LDA(At, 1, 0); STAGE(SA(0, 1), A, brow + HALF, t + 2);
;     WAIT_L(8); BAR; WAIT_L(0); MMA(0, 0, At, B0); BAR; SCHED;
;     LDB(B1, 1, 1); STAGE(SB(1, 0), Bt, bcol, t + 3);
;     BAR; WAIT_L(0); MMA(0, 1, At, B1); BAR;
;     LDA(At, 1, 1); STAGE(SA(1, 0), A, brow, t + 3);
	v_readfirstlane_b32 s60, v158
	v_add_u32_e32 v134, 0x2000, v158
	v_lshl_add_u64 v[174:175], v[208:209], 0, s[66:67]
	s_mov_b32 m0, s60
	v_readfirstlane_b32 s60, v134
	global_load_lds_dwordx4 v[174:175], off
	v_lshl_add_u64 v[174:175], v[210:211], 0, s[66:67]
	s_mov_b32 m0, s60
	s_nop 0
	global_load_lds_dwordx4 v[174:175], off
	s_waitcnt vmcnt(6)
	s_barrier
	v_mfma_f32_16x16x32_bf16 v[28:31], v[234:237], v[190:193], v[28:31]
	v_mfma_f32_16x16x32_bf16 v[24:27], v[242:245], v[190:193], v[24:27]
	v_mfma_f32_16x16x32_bf16 v[20:23], v[234:237], v[198:201], v[20:23]
	v_mfma_f32_16x16x32_bf16 v[16:19], v[242:245], v[198:201], v[16:19]
	v_mfma_f32_16x16x32_bf16 v[12:15], v[234:237], v[218:221], v[12:15]
	v_mfma_f32_16x16x32_bf16 v[8:11], v[242:245], v[218:221], v[8:11]
	v_mfma_f32_16x16x32_bf16 v[4:7], v[234:237], v[226:229], v[4:7]
	v_mfma_f32_16x16x32_bf16 v[0:3], v[242:245], v[226:229], v[0:3]
	v_mfma_f32_16x16x32_bf16 v[28:31], v[238:241], v[194:197], v[28:31]
	v_mfma_f32_16x16x32_bf16 v[24:27], v[246:249], v[194:197], v[24:27]
	v_mfma_f32_16x16x32_bf16 v[20:23], v[238:241], v[202:205], v[20:23]
	v_mfma_f32_16x16x32_bf16 v[16:19], v[246:249], v[202:205], v[16:19]
	v_mfma_f32_16x16x32_bf16 v[12:15], v[238:241], v[222:225], v[12:15]
	v_mfma_f32_16x16x32_bf16 v[8:11], v[246:249], v[222:225], v[8:11]
	v_mfma_f32_16x16x32_bf16 v[4:7], v[238:241], v[230:233], v[4:7]
	v_mfma_f32_16x16x32_bf16 v[0:3], v[246:249], v[230:233], v[0:3]
	s_barrier
	ds_read_b128 v[174:177], v165
	ds_read_b128 v[178:181], v165 offset:1024
	ds_read_b128 v[182:185], v165 offset:2048
	ds_read_b128 v[186:189], v165 offset:3072
	ds_read_b128 v[190:193], v162 offset:32768
	ds_read_b128 v[194:197], v162 offset:33792
	ds_read_b128 v[198:201], v161 offset:32768
	ds_read_b128 v[202:205], v161 offset:33792
	ds_read_b128 v[218:221], v160 offset:32768
	ds_read_b128 v[222:225], v160 offset:33792
	ds_read_b128 v[226:229], v159 offset:32768
	ds_read_b128 v[230:233], v159 offset:33792
	v_add_u32_e32 v134, 0x4000, v157
	v_lshl_add_u64 v[214:215], v[136:137], 0, s[12:13]
	v_readfirstlane_b32 s60, v134
	v_add_u32_e32 v134, 0x6000, v157
	s_mov_b32 m0, s60
	v_readfirstlane_b32 s60, v134
	global_load_lds_dwordx4 v[214:215], off
	v_lshl_add_u64 v[214:215], v[138:139], 0, s[12:13]
	s_mov_b32 m0, s60
	s_nop 0
	global_load_lds_dwordx4 v[214:215], off
	s_waitcnt lgkmcnt(8)
	s_barrier
	s_waitcnt lgkmcnt(0)
	v_mfma_f32_16x16x32_bf16 v[124:127], v[174:177], v[190:193], v[124:127]
	v_mfma_f32_16x16x32_bf16 v[120:123], v[182:185], v[190:193], v[120:123]
	v_mfma_f32_16x16x32_bf16 v[116:119], v[174:177], v[198:201], v[116:119]
	v_mfma_f32_16x16x32_bf16 v[112:115], v[182:185], v[198:201], v[112:115]
	v_mfma_f32_16x16x32_bf16 v[108:111], v[174:177], v[218:221], v[108:111]
	v_mfma_f32_16x16x32_bf16 v[104:107], v[182:185], v[218:221], v[104:107]
	v_mfma_f32_16x16x32_bf16 v[100:103], v[174:177], v[226:229], v[100:103]
	v_mfma_f32_16x16x32_bf16 v[96:99], v[182:185], v[226:229], v[96:99]
	v_mfma_f32_16x16x32_bf16 v[124:127], v[178:181], v[194:197], v[124:127]
	v_mfma_f32_16x16x32_bf16 v[120:123], v[186:189], v[194:197], v[120:123]
	v_mfma_f32_16x16x32_bf16 v[116:119], v[178:181], v[202:205], v[116:119]
	v_mfma_f32_16x16x32_bf16 v[112:115], v[186:189], v[202:205], v[112:115]
	v_mfma_f32_16x16x32_bf16 v[108:111], v[178:181], v[222:225], v[108:111]
	v_mfma_f32_16x16x32_bf16 v[104:107], v[186:189], v[222:225], v[104:107]
	v_mfma_f32_16x16x32_bf16 v[100:103], v[178:181], v[230:233], v[100:103]
	v_mfma_f32_16x16x32_bf16 v[96:99], v[186:189], v[230:233], v[96:99]
	s_barrier
	ds_read_b128 v[234:237], v163
	ds_read_b128 v[238:241], v163 offset:1024
	ds_read_b128 v[242:245], v163 offset:2048
	ds_read_b128 v[246:249], v163 offset:3072
	v_readfirstlane_b32 s60, v164
	v_add_u32_e32 v134, 0x2000, v164
	v_lshl_add_u64 v[214:215], v[208:209], 0, s[70:71]
	s_mov_b32 m0, s60
	v_readfirstlane_b32 s60, v134
	global_load_lds_dwordx4 v[214:215], off
	v_lshl_add_u64 v[214:215], v[210:211], 0, s[70:71]
	s_mov_b32 m0, s60
	s_nop 0
	global_load_lds_dwordx4 v[214:215], off
	s_barrier
	s_waitcnt lgkmcnt(0)
	v_mfma_f32_16x16x32_bf16 v[92:95], v[234:237], v[190:193], v[92:95]
	v_mfma_f32_16x16x32_bf16 v[88:91], v[242:245], v[190:193], v[88:91]
	v_mfma_f32_16x16x32_bf16 v[84:87], v[234:237], v[198:201], v[84:87]
	v_mfma_f32_16x16x32_bf16 v[80:83], v[242:245], v[198:201], v[80:83]
	v_mfma_f32_16x16x32_bf16 v[76:79], v[234:237], v[218:221], v[76:79]
	v_mfma_f32_16x16x32_bf16 v[72:75], v[242:245], v[218:221], v[72:75]
	v_mfma_f32_16x16x32_bf16 v[68:71], v[234:237], v[226:229], v[68:71]
	v_mfma_f32_16x16x32_bf16 v[64:67], v[242:245], v[226:229], v[64:67]
	v_mfma_f32_16x16x32_bf16 v[92:95], v[238:241], v[194:197], v[92:95]
	v_mfma_f32_16x16x32_bf16 v[88:91], v[246:249], v[194:197], v[88:91]
	v_mfma_f32_16x16x32_bf16 v[84:87], v[238:241], v[202:205], v[84:87]
	v_mfma_f32_16x16x32_bf16 v[80:83], v[246:249], v[202:205], v[80:83]
	v_mfma_f32_16x16x32_bf16 v[76:79], v[238:241], v[222:225], v[76:79]
	v_mfma_f32_16x16x32_bf16 v[72:75], v[246:249], v[222:225], v[72:75]
	v_mfma_f32_16x16x32_bf16 v[68:71], v[238:241], v[230:233], v[68:71]
	v_mfma_f32_16x16x32_bf16 v[64:67], v[246:249], v[230:233], v[64:67]
	v_readfirstlane_b32 s60, v166
	v_lshl_add_u64 v[136:137], v[136:137], 0, s[16:17]
	s_mov_b32 m0, s60
	v_readfirstlane_b32 s60, v167
	s_barrier
	ds_read_b128 v[190:193], v162 offset:49152
	ds_read_b128 v[194:197], v162 offset:50176
	ds_read_b128 v[198:201], v161 offset:49152
	ds_read_b128 v[202:205], v161 offset:50176
	ds_read_b128 v[218:221], v160 offset:49152
	ds_read_b128 v[222:225], v160 offset:50176
	ds_read_b128 v[226:229], v159 offset:49152
	ds_read_b128 v[230:233], v159 offset:50176
	global_load_lds_dwordx4 v[136:137], off
	v_lshl_add_u64 v[136:137], v[138:139], 0, s[16:17]
	s_mov_b32 m0, s60
	s_nop 0
	global_load_lds_dwordx4 v[136:137], off
	s_barrier
; #define STAGE(P, BASE, br, kt) STAGET(tid_, P, BASE, br, kt)
; #define LDA(dst, b, h) UFOR(m, 4) UFOR(k, 2) \
;     dst[m][k] = *reinterpret_cast<const bf16x8*>((char*)SA(b, h) + lds_byte(wr * 64 + m * 16 + fr, k * 32 + fq * 8))
; #define LDB(dst, b, h) UFOR(n, 2) UFOR(k, 2) \
;     dst[n][k] = *reinterpret_cast<const bf16x8*>((char*)SB(b, h) + lds_byte(wc * 32 + n * 16 + fr, k * 32 + fq * 8))
; #define MMA(ai, bj, At, Bq) do { __builtin_amdgcn_s_setprio(1); \
;     UFOR(m, 4) UFOR(n, 2) UFOR(k, 2) \
;       acc[ai][bj][m][n] = __builtin_amdgcn_mfma_f32_16x16x32_bf16(Bq[n][k], At[m][k], acc[ai][bj][m][n], 0, 0, 0); \
;     __builtin_amdgcn_s_setprio(0); } while (0)
; #define WAIT_V(n) asm volatile("s_waitcnt vmcnt(" #n ")" ::: "memory")
; #define WAIT_L(n) asm volatile("s_waitcnt lgkmcnt(" #n ")" ::: "memory")
; #define BAR __builtin_amdgcn_s_barrier()
; #define SCHED __builtin_amdgcn_sched_barrier(0)
; template <int EPI, int K, int KL> ...
;     ...
;     LDA(At, 1, 1); STAGE(SA(1, 0), A, brow, t + 3);
;     BAR; WAIT_L(0); MMA(1, 0, At, B0); BAR; SCHED;
;     STAGE(SB(1, 1), Bt, bcol + HALF, t + 3);
;     WAIT_V(6); BAR; MMA(1, 1, At, B1); BAR;
;   }
;   { LDB(B0, 0, 0); LDA(At, 0, 0); STAGE(SA(1, 1), A, brow + HALF, nt - 1);
;     BAR; WAIT_L(0); MMA(0, 0, At, B0); BAR;
	s_waitcnt lgkmcnt(0)
	v_mfma_f32_16x16x32_bf16 v[60:63], v[174:177], v[190:193], v[60:63]
	v_mfma_f32_16x16x32_bf16 v[56:59], v[182:185], v[190:193], v[56:59]
	v_mfma_f32_16x16x32_bf16 v[52:55], v[174:177], v[198:201], v[52:55]
	v_mfma_f32_16x16x32_bf16 v[48:51], v[182:185], v[198:201], v[48:51]
	v_mfma_f32_16x16x32_bf16 v[44:47], v[174:177], v[218:221], v[44:47]
	v_mfma_f32_16x16x32_bf16 v[40:43], v[182:185], v[218:221], v[40:43]
	v_mfma_f32_16x16x32_bf16 v[36:39], v[174:177], v[226:229], v[36:39]
	v_mfma_f32_16x16x32_bf16 v[32:35], v[182:185], v[226:229], v[32:35]
	v_mfma_f32_16x16x32_bf16 v[60:63], v[178:181], v[194:197], v[60:63]
	v_mfma_f32_16x16x32_bf16 v[56:59], v[186:189], v[194:197], v[56:59]
	v_mfma_f32_16x16x32_bf16 v[52:55], v[178:181], v[202:205], v[52:55]
	v_mfma_f32_16x16x32_bf16 v[48:51], v[186:189], v[202:205], v[48:51]
	v_mfma_f32_16x16x32_bf16 v[44:47], v[178:181], v[222:225], v[44:47]
	v_mfma_f32_16x16x32_bf16 v[40:43], v[186:189], v[222:225], v[40:43]
	v_mfma_f32_16x16x32_bf16 v[36:39], v[178:181], v[230:233], v[36:39]
	v_mfma_f32_16x16x32_bf16 v[32:35], v[186:189], v[230:233], v[32:35]
	s_barrier
	v_readfirstlane_b32 s60, v169
	v_add_u32_e32 v134, 0x2000, v169
	v_lshl_add_u64 v[136:137], v[208:209], 0, s[74:75]
	s_mov_b32 m0, s60
	v_readfirstlane_b32 s60, v134
	global_load_lds_dwordx4 v[136:137], off
	v_lshl_add_u64 v[136:137], v[210:211], 0, s[74:75]
	s_mov_b32 m0, s60
	s_nop 0
	global_load_lds_dwordx4 v[136:137], off
	s_waitcnt vmcnt(6)
	s_barrier
	v_mfma_f32_16x16x32_bf16 v[28:31], v[234:237], v[190:193], v[28:31]
	v_mfma_f32_16x16x32_bf16 v[24:27], v[242:245], v[190:193], v[24:27]
	v_mfma_f32_16x16x32_bf16 v[20:23], v[234:237], v[198:201], v[20:23]
	v_mfma_f32_16x16x32_bf16 v[16:19], v[242:245], v[198:201], v[16:19]
	v_mfma_f32_16x16x32_bf16 v[12:15], v[234:237], v[218:221], v[12:15]
	v_mfma_f32_16x16x32_bf16 v[8:11], v[242:245], v[218:221], v[8:11]
	v_mfma_f32_16x16x32_bf16 v[4:7], v[234:237], v[226:229], v[4:7]
	v_mfma_f32_16x16x32_bf16 v[0:3], v[242:245], v[226:229], v[0:3]
	v_mfma_f32_16x16x32_bf16 v[28:31], v[238:241], v[194:197], v[28:31]
	v_mfma_f32_16x16x32_bf16 v[24:27], v[246:249], v[194:197], v[24:27]
	v_mfma_f32_16x16x32_bf16 v[20:23], v[238:241], v[202:205], v[20:23]
	v_mfma_f32_16x16x32_bf16 v[16:19], v[246:249], v[202:205], v[16:19]
	v_mfma_f32_16x16x32_bf16 v[12:15], v[238:241], v[222:225], v[12:15]
	v_mfma_f32_16x16x32_bf16 v[8:11], v[246:249], v[222:225], v[8:11]
	v_mfma_f32_16x16x32_bf16 v[4:7], v[238:241], v[230:233], v[4:7]
	v_mfma_f32_16x16x32_bf16 v[0:3], v[246:249], v[230:233], v[0:3]
	s_add_i32 s55, s55, 2
	v_lshl_add_u64 v[144:145], v[144:145], 0, s[20:21]
	v_lshl_add_u64 v[146:147], v[146:147], 0, s[20:21]
	v_lshl_add_u64 v[148:149], v[148:149], 0, s[20:21]
	s_cmp_lt_u32 s55, 28
	v_lshl_add_u64 v[150:151], v[150:151], 0, s[20:21]
	s_cbranch_scc1 .Lkrot_940
	s_barrier
	s_add_u32 s58, s58, 0x80f80
	s_addc_u32 s59, s59, 0
	v_lshl_add_u64 v[130:131], s[58:59], 0, v[130:131]
	v_readfirstlane_b32 s55, v171
	v_lshl_add_u64 v[128:129], v[128:129], 1, v[130:131]
	s_mov_b32 m0, s55
	ds_read_b128 v[144:147], v170
	ds_read_b128 v[148:151], v170 offset:1024
	ds_read_b128 v[174:177], v170 offset:2048
	ds_read_b128 v[178:181], v170 offset:3072
	ds_read_b128 v[182:185], v162
	ds_read_b128 v[186:189], v162 offset:1024
	ds_read_b128 v[190:193], v161
	ds_read_b128 v[194:197], v161 offset:1024
	ds_read_b128 v[198:201], v160
	ds_read_b128 v[202:205], v160 offset:1024
	ds_read_b128 v[218:221], v159
	ds_read_b128 v[222:225], v159 offset:1024
	global_load_lds_dwordx4 v[128:129], off
	v_lshl_add_u64 v[128:129], s[58:59], 0, v[142:143]
	v_readfirstlane_b32 s55, v172
	v_lshl_add_u64 v[128:129], v[140:141], 1, v[128:129]
	s_mov_b32 m0, s55
	s_nop 0
	global_load_lds_dwordx4 v[128:129], off
	s_barrier
	s_waitcnt lgkmcnt(0)
	s_waitcnt lgkmcnt(0)
	v_mfma_f32_16x16x32_bf16 v[124:127], v[144:147], v[182:185], v[124:127]
	v_mfma_f32_16x16x32_bf16 v[120:123], v[174:177], v[182:185], v[120:123]
	v_mfma_f32_16x16x32_bf16 v[116:119], v[144:147], v[190:193], v[116:119]
	v_mfma_f32_16x16x32_bf16 v[112:115], v[174:177], v[190:193], v[112:115]
	v_mfma_f32_16x16x32_bf16 v[108:111], v[144:147], v[198:201], v[108:111]
	v_mfma_f32_16x16x32_bf16 v[104:107], v[174:177], v[198:201], v[104:107]
	v_mfma_f32_16x16x32_bf16 v[100:103], v[144:147], v[218:221], v[100:103]
	v_mfma_f32_16x16x32_bf16 v[96:99], v[174:177], v[218:221], v[96:99]
	v_mfma_f32_16x16x32_bf16 v[124:127], v[148:151], v[186:189], v[124:127]
	v_mfma_f32_16x16x32_bf16 v[120:123], v[178:181], v[186:189], v[120:123]
	v_mfma_f32_16x16x32_bf16 v[116:119], v[148:151], v[194:197], v[116:119]
	v_mfma_f32_16x16x32_bf16 v[112:115], v[178:181], v[194:197], v[112:115]
	v_mfma_f32_16x16x32_bf16 v[108:111], v[148:151], v[202:205], v[108:111]
	v_mfma_f32_16x16x32_bf16 v[104:107], v[178:181], v[202:205], v[104:107]
	v_mfma_f32_16x16x32_bf16 v[100:103], v[148:151], v[222:225], v[100:103]
	v_mfma_f32_16x16x32_bf16 v[96:99], v[178:181], v[222:225], v[96:99]
	s_barrier
	ds_read_b128 v[128:131], v168
	ds_read_b128 v[140:143], v168 offset:1024
	ds_read_b128 v[170:173], v168 offset:2048
	ds_read_b128 v[166:169], v168 offset:3072
	s_barrier
; #define STAGE(P, BASE, br, kt) STAGET(tid_, P, BASE, br, kt)
; #define LDA(dst, b, h) UFOR(m, 4) UFOR(k, 2) \
;     dst[m][k] = *reinterpret_cast<const bf16x8*>((char*)SA(b, h) + lds_byte(wr * 64 + m * 16 + fr, k * 32 + fq * 8))
; #define LDB(dst, b, h) UFOR(n, 2) UFOR(k, 2) \
;     dst[n][k] = *reinterpret_cast<const bf16x8*>((char*)SB(b, h) + lds_byte(wc * 32 + n * 16 + fr, k * 32 + fq * 8))
; #define MMA(ai, bj, At, Bq) do { __builtin_amdgcn_s_setprio(1); \
;     UFOR(m, 4) UFOR(n, 2) UFOR(k, 2) \
;       acc[ai][bj][m][n] = __builtin_amdgcn_mfma_f32_16x16x32_bf16(Bq[n][k], At[m][k], acc[ai][bj][m][n], 0, 0, 0); \
;     __builtin_amdgcn_s_setprio(0); } while (0)
; #define WAIT_V(n) asm volatile("s_waitcnt vmcnt(" #n ")" ::: "memory")
; #define WAIT_L(n) asm volatile("s_waitcnt lgkmcnt(" #n ")" ::: "memory")
; #define BAR __builtin_amdgcn_s_barrier()
; template <int EPI, int K, int KL> ...
;     ...
;   { LDB(B0, 0, 0); LDA(At, 0, 0); STAGE(SA(1, 1), A, brow + HALF, nt - 1);
;     BAR; WAIT_L(0); MMA(0, 0, At, B0); BAR;
;     LDB(B1, 0, 1); BAR; WAIT_L(0); MMA(0, 1, At, B1); BAR;
;     LDA(At, 0, 1); WAIT_V(4); BAR; WAIT_L(0); MMA(1, 0, At, B0); MMA(1, 1, At, B1); BAR; }
;   { LDB(B0, 1, 0); LDA(At, 1, 0); WAIT_V(2); BAR; WAIT_L(0); MMA(0, 0, At, B0); BAR;
	s_waitcnt lgkmcnt(0)
	s_waitcnt lgkmcnt(0)
	v_mfma_f32_16x16x32_bf16 v[80:83], v[170:173], v[190:193], v[80:83]
	v_mfma_f32_16x16x32_bf16 v[72:75], v[170:173], v[198:201], v[72:75]
	v_mfma_f32_16x16x32_bf16 v[68:71], v[128:131], v[218:221], v[68:71]
	v_mfma_f32_16x16x32_bf16 v[64:67], v[170:173], v[218:221], v[64:67]
	v_mfma_f32_16x16x32_bf16 v[92:95], v[128:131], v[182:185], v[92:95]
	v_mfma_f32_16x16x32_bf16 v[88:91], v[170:173], v[182:185], v[88:91]
	v_mfma_f32_16x16x32_bf16 v[84:87], v[128:131], v[190:193], v[84:87]
	v_mfma_f32_16x16x32_bf16 v[80:83], v[166:169], v[194:197], v[80:83]
	v_mfma_f32_16x16x32_bf16 v[76:79], v[128:131], v[198:201], v[76:79]
	v_mfma_f32_16x16x32_bf16 v[72:75], v[166:169], v[202:205], v[72:75]
	v_mfma_f32_16x16x32_bf16 v[68:71], v[140:143], v[222:225], v[68:71]
	v_mfma_f32_16x16x32_bf16 v[64:67], v[166:169], v[222:225], v[64:67]
	v_mfma_f32_16x16x32_bf16 v[226:229], v[140:143], v[186:189], v[92:95]
	v_mfma_f32_16x16x32_bf16 v[182:185], v[166:169], v[186:189], v[88:91]
	v_mfma_f32_16x16x32_bf16 v[186:189], v[140:143], v[194:197], v[84:87]
	v_mfma_f32_16x16x32_bf16 v[190:193], v[140:143], v[202:205], v[76:79]
	s_barrier
	s_nop 0
	ds_read_b128 v[76:79], v162 offset:16384
	ds_read_b128 v[84:87], v162 offset:17408
	ds_read_b128 v[88:91], v161 offset:16384
	ds_read_b128 v[92:95], v161 offset:17408
	ds_read_b128 v[194:197], v160 offset:16384
	ds_read_b128 v[198:201], v160 offset:17408
	ds_read_b128 v[202:205], v159 offset:16384
	ds_read_b128 v[218:221], v159 offset:17408
	s_waitcnt vmcnt(4)
	s_barrier
	s_waitcnt lgkmcnt(0)
	s_waitcnt lgkmcnt(0)
	v_mfma_f32_16x16x32_bf16 v[48:51], v[174:177], v[88:91], v[48:51]
	v_mfma_f32_16x16x32_bf16 v[40:43], v[174:177], v[194:197], v[40:43]
	v_mfma_f32_16x16x32_bf16 v[36:39], v[144:147], v[202:205], v[36:39]
	v_mfma_f32_16x16x32_bf16 v[32:35], v[174:177], v[202:205], v[32:35]
	v_mfma_f32_16x16x32_bf16 v[60:63], v[144:147], v[76:79], v[60:63]
	v_mfma_f32_16x16x32_bf16 v[56:59], v[174:177], v[76:79], v[56:59]
	v_mfma_f32_16x16x32_bf16 v[52:55], v[144:147], v[88:91], v[52:55]
	v_mfma_f32_16x16x32_bf16 v[48:51], v[178:181], v[92:95], v[48:51]
	v_mfma_f32_16x16x32_bf16 v[44:47], v[144:147], v[194:197], v[44:47]
	v_mfma_f32_16x16x32_bf16 v[40:43], v[178:181], v[198:201], v[40:43]
	v_mfma_f32_16x16x32_bf16 v[36:39], v[148:151], v[218:221], v[36:39]
	v_mfma_f32_16x16x32_bf16 v[32:35], v[178:181], v[218:221], v[32:35]
	v_mfma_f32_16x16x32_bf16 v[222:225], v[148:151], v[84:87], v[60:63]
	v_mfma_f32_16x16x32_bf16 v[230:233], v[178:181], v[84:87], v[56:59]
	v_mfma_f32_16x16x32_bf16 v[234:237], v[148:151], v[92:95], v[52:55]
	v_mfma_f32_16x16x32_bf16 v[238:241], v[148:151], v[198:201], v[44:47]
	v_mfma_f32_16x16x32_bf16 v[0:3], v[170:173], v[202:205], v[0:3]
	v_mfma_f32_16x16x32_bf16 v[28:31], v[128:131], v[76:79], v[28:31]
	v_mfma_f32_16x16x32_bf16 v[24:27], v[170:173], v[76:79], v[24:27]
	v_mfma_f32_16x16x32_bf16 v[20:23], v[128:131], v[88:91], v[20:23]
	v_mfma_f32_16x16x32_bf16 v[16:19], v[170:173], v[88:91], v[16:19]
	v_mfma_f32_16x16x32_bf16 v[12:15], v[128:131], v[194:197], v[12:15]
	v_mfma_f32_16x16x32_bf16 v[8:11], v[170:173], v[194:197], v[8:11]
	v_mfma_f32_16x16x32_bf16 v[4:7], v[128:131], v[202:205], v[4:7]
	v_mfma_f32_16x16x32_bf16 v[0:3], v[166:169], v[218:221], v[0:3]
	v_mfma_f32_16x16x32_bf16 v[144:147], v[140:143], v[84:87], v[28:31]
	v_mfma_f32_16x16x32_bf16 v[148:151], v[166:169], v[84:87], v[24:27]
	v_mfma_f32_16x16x32_bf16 v[174:177], v[140:143], v[92:95], v[20:23]
	v_mfma_f32_16x16x32_bf16 v[178:181], v[166:169], v[92:95], v[16:19]
	v_mfma_f32_16x16x32_bf16 v[242:245], v[140:143], v[198:201], v[12:15]
	v_mfma_f32_16x16x32_bf16 v[194:197], v[166:169], v[198:201], v[8:11]
	v_mfma_f32_16x16x32_bf16 v[128:131], v[140:143], v[218:221], v[4:7]
	s_barrier
	s_nop 0
	ds_read_b128 v[4:7], v165
	ds_read_b128 v[8:11], v165 offset:1024
	ds_read_b128 v[16:19], v165 offset:2048
	ds_read_b128 v[140:143], v165 offset:3072
	ds_read_b128 v[12:15], v162 offset:32768
	ds_read_b128 v[20:23], v162 offset:33792
	ds_read_b128 v[24:27], v161 offset:32768
	ds_read_b128 v[44:47], v161 offset:33792
	ds_read_b128 v[164:167], v160 offset:32768
	ds_read_b128 v[168:171], v160 offset:33792
	ds_read_b128 v[198:201], v159 offset:32768
	ds_read_b128 v[202:205], v159 offset:33792
	s_waitcnt vmcnt(2)
	s_barrier
; #define LDA(dst, b, h) UFOR(m, 4) UFOR(k, 2) \
;     dst[m][k] = *reinterpret_cast<const bf16x8*>((char*)SA(b, h) + lds_byte(wr * 64 + m * 16 + fr, k * 32 + fq * 8))
; #define LDB(dst, b, h) UFOR(n, 2) UFOR(k, 2) \
;     dst[n][k] = *reinterpret_cast<const bf16x8*>((char*)SB(b, h) + lds_byte(wc * 32 + n * 16 + fr, k * 32 + fq * 8))
; #define MMA(ai, bj, At, Bq) do { __builtin_amdgcn_s_setprio(1); \
;     UFOR(m, 4) UFOR(n, 2) UFOR(k, 2) \
;       acc[ai][bj][m][n] = __builtin_amdgcn_mfma_f32_16x16x32_bf16(Bq[n][k], At[m][k], acc[ai][bj][m][n], 0, 0, 0); \
;     __builtin_amdgcn_s_setprio(0); } while (0)
; #define WAIT_V(n) asm volatile("s_waitcnt vmcnt(" #n ")" ::: "memory")
; #define WAIT_L(n) asm volatile("s_waitcnt lgkmcnt(" #n ")" ::: "memory")
; #define BAR __builtin_amdgcn_s_barrier()
; template <int EPI, int K, int KL> ...
;     ...
;   { LDB(B0, 1, 0); LDA(At, 1, 0); WAIT_V(2); BAR; WAIT_L(0); MMA(0, 0, At, B0); BAR;
;     LDB(B1, 1, 1); WAIT_V(0); BAR; WAIT_L(0); MMA(0, 1, At, B1); BAR;
;     LDA(At, 1, 1); BAR; WAIT_L(0); MMA(1, 0, At, B0); MMA(1, 1, At, B1); BAR; }
;   if (wr == 0) BAR;
	s_waitcnt lgkmcnt(0)
	s_waitcnt lgkmcnt(0)
	v_mfma_f32_16x16x32_bf16 v[28:31], v[4:7], v[12:15], v[124:127]
	v_mfma_f32_16x16x32_bf16 v[124:127], v[8:11], v[20:23], v[28:31]
	v_mfma_f32_16x16x32_bf16 v[28:31], v[16:19], v[12:15], v[120:123]
	v_mfma_f32_16x16x32_bf16 v[92:95], v[140:143], v[20:23], v[28:31]
	v_mfma_f32_16x16x32_bf16 v[28:31], v[4:7], v[24:27], v[116:119]
	v_mfma_f32_16x16x32_bf16 v[120:123], v[8:11], v[44:47], v[28:31]
	v_mfma_f32_16x16x32_bf16 v[28:31], v[16:19], v[24:27], v[112:115]
	v_mfma_f32_16x16x32_bf16 v[88:91], v[140:143], v[44:47], v[28:31]
	v_mfma_f32_16x16x32_bf16 v[28:31], v[4:7], v[164:167], v[108:111]
	v_mfma_f32_16x16x32_bf16 v[116:119], v[8:11], v[168:171], v[28:31]
	v_mfma_f32_16x16x32_bf16 v[28:31], v[16:19], v[164:167], v[104:107]
	v_mfma_f32_16x16x32_bf16 v[84:87], v[140:143], v[168:171], v[28:31]
	v_mfma_f32_16x16x32_bf16 v[28:31], v[4:7], v[198:201], v[100:103]
	v_mfma_f32_16x16x32_bf16 v[108:111], v[8:11], v[202:205], v[28:31]
	v_mfma_f32_16x16x32_bf16 v[28:31], v[16:19], v[198:201], v[96:99]
	v_mfma_f32_16x16x32_bf16 v[76:79], v[140:143], v[202:205], v[28:31]
	s_barrier
	ds_read_b128 v[218:221], v163
	ds_read_b128 v[246:249], v163 offset:1024
	ds_read_b128 v[136:139], v163 offset:2048
	ds_read_b128 v[208:211], v163 offset:3072
	s_waitcnt vmcnt(0)
	s_barrier
	s_waitcnt lgkmcnt(0)
	s_waitcnt lgkmcnt(0)
	v_mfma_f32_16x16x32_bf16 v[28:31], v[218:221], v[12:15], v[226:229]
	v_mfma_f32_16x16x32_bf16 v[12:15], v[136:139], v[12:15], v[182:185]
	v_mfma_f32_16x16x32_bf16 v[60:63], v[246:249], v[20:23], v[28:31]
	v_mfma_f32_16x16x32_bf16 v[28:31], v[208:211], v[20:23], v[12:15]
	v_mfma_f32_16x16x32_bf16 v[12:15], v[218:221], v[24:27], v[186:189]
	v_mfma_f32_16x16x32_bf16 v[56:59], v[246:249], v[44:47], v[12:15]
	v_mfma_f32_16x16x32_bf16 v[12:15], v[136:139], v[24:27], v[80:83]
	v_mfma_f32_16x16x32_bf16 v[24:27], v[208:211], v[44:47], v[12:15]
	v_mfma_f32_16x16x32_bf16 v[12:15], v[218:221], v[164:167], v[190:193]
	v_mfma_f32_16x16x32_bf16 v[52:55], v[246:249], v[168:171], v[12:15]
	v_mfma_f32_16x16x32_bf16 v[12:15], v[136:139], v[164:167], v[72:75]
	v_mfma_f32_16x16x32_bf16 v[20:23], v[208:211], v[168:171], v[12:15]
	v_mfma_f32_16x16x32_bf16 v[12:15], v[218:221], v[198:201], v[68:71]
	v_mfma_f32_16x16x32_bf16 v[44:47], v[246:249], v[202:205], v[12:15]
	v_mfma_f32_16x16x32_bf16 v[12:15], v[136:139], v[198:201], v[64:67]
	v_mfma_f32_16x16x32_bf16 v[12:15], v[208:211], v[202:205], v[12:15]
	s_barrier
	ds_read_b128 v[164:167], v162 offset:49152
	ds_read_b128 v[168:171], v162 offset:50176
	ds_read_b128 v[182:185], v161 offset:49152
	ds_read_b128 v[186:189], v161 offset:50176
	ds_read_b128 v[190:193], v160 offset:49152
	ds_read_b128 v[160:163], v160 offset:50176
	ds_read_b128 v[198:201], v159 offset:49152
	ds_read_b128 v[156:159], v159 offset:50176
	s_barrier
	s_waitcnt lgkmcnt(0)
	s_waitcnt lgkmcnt(0)
	v_mfma_f32_16x16x32_bf16 v[64:67], v[4:7], v[164:167], v[222:225]
	v_mfma_f32_16x16x32_bf16 v[112:115], v[8:11], v[168:171], v[64:67]
	v_mfma_f32_16x16x32_bf16 v[64:67], v[16:19], v[164:167], v[230:233]
	v_mfma_f32_16x16x32_bf16 v[48:51], v[16:19], v[182:185], v[48:51]
	v_mfma_f32_16x16x32_bf16 v[80:83], v[140:143], v[168:171], v[64:67]
	v_mfma_f32_16x16x32_bf16 v[64:67], v[4:7], v[182:185], v[234:237]
	v_mfma_f32_16x16x32_bf16 v[72:75], v[140:143], v[186:189], v[48:51]
	v_mfma_f32_16x16x32_bf16 v[48:51], v[4:7], v[190:193], v[238:241]
	v_mfma_f32_16x16x32_bf16 v[4:7], v[4:7], v[198:201], v[36:39]
	v_mfma_f32_16x16x32_bf16 v[40:43], v[16:19], v[190:193], v[40:43]
	v_mfma_f32_16x16x32_bf16 v[96:99], v[8:11], v[156:159], v[4:7]
	v_mfma_f32_16x16x32_bf16 v[4:7], v[16:19], v[198:201], v[32:35]
	v_mfma_f32_16x16x32_bf16 v[104:107], v[8:11], v[186:189], v[64:67]
	v_mfma_f32_16x16x32_bf16 v[100:103], v[8:11], v[160:163], v[48:51]
	v_mfma_f32_16x16x32_bf16 v[68:71], v[140:143], v[160:163], v[40:43]
	v_mfma_f32_16x16x32_bf16 v[64:67], v[140:143], v[156:159], v[4:7]
	v_mfma_f32_16x16x32_bf16 v[4:7], v[218:221], v[164:167], v[144:147]
	v_mfma_f32_16x16x32_bf16 v[48:51], v[246:249], v[168:171], v[4:7]
	v_mfma_f32_16x16x32_bf16 v[4:7], v[136:139], v[164:167], v[148:151]
	v_mfma_f32_16x16x32_bf16 v[16:19], v[208:211], v[168:171], v[4:7]
	v_mfma_f32_16x16x32_bf16 v[4:7], v[218:221], v[182:185], v[174:177]
	v_mfma_f32_16x16x32_bf16 v[40:43], v[246:249], v[186:189], v[4:7]
	v_mfma_f32_16x16x32_bf16 v[4:7], v[136:139], v[182:185], v[178:181]
	v_mfma_f32_16x16x32_bf16 v[8:11], v[208:211], v[186:189], v[4:7]
	v_mfma_f32_16x16x32_bf16 v[4:7], v[218:221], v[190:193], v[242:245]
	v_mfma_f32_16x16x32_bf16 v[36:39], v[246:249], v[160:163], v[4:7]
	v_mfma_f32_16x16x32_bf16 v[4:7], v[136:139], v[190:193], v[194:197]
	v_mfma_f32_16x16x32_bf16 v[32:35], v[218:221], v[198:201], v[128:131]
	v_mfma_f32_16x16x32_bf16 v[0:3], v[136:139], v[198:201], v[0:3]
	v_mfma_f32_16x16x32_bf16 v[4:7], v[208:211], v[160:163], v[4:7]
	v_mfma_f32_16x16x32_bf16 v[32:35], v[246:249], v[156:159], v[32:35]
	v_mfma_f32_16x16x32_bf16 v[0:3], v[208:211], v[156:159], v[0:3]
	s_movk_i32 s55, 0x100
	v_cmp_gt_u32_e32 vcc, s55, v154
	s_barrier
	s_and_saveexec_b64 s[58:59], vcc
	s_cbranch_execz .LBB0_943
	s_barrier

; #define STAGE(P, BASE, br, kt) STAGET(tid_, P, BASE, br, kt)
; #define LDA(dst, b, h) UFOR(m, 4) UFOR(k, 2) \
;     dst[m][k] = *reinterpret_cast<const bf16x8*>((char*)SA(b, h) + lds_byte(wr * 64 + m * 16 + fr, k * 32 + fq * 8))
; #define LDB(dst, b, h) UFOR(n, 2) UFOR(k, 2) \
;     dst[n][k] = *reinterpret_cast<const bf16x8*>((char*)SB(b, h) + lds_byte(wc * 32 + n * 16 + fr, k * 32 + fq * 8))
; #define MMA(ai, bj, At, Bq) do { __builtin_amdgcn_s_setprio(1); \
;     UFOR(m, 4) UFOR(n, 2) UFOR(k, 2) \
;       acc[ai][bj][m][n] = __builtin_amdgcn_mfma_f32_16x16x32_bf16(Bq[n][k], At[m][k], acc[ai][bj][m][n], 0, 0, 0); \
;     __builtin_amdgcn_s_setprio(0); } while (0)
; #define WAIT_L(n) asm volatile("s_waitcnt lgkmcnt(" #n ")" ::: "memory")
; #define BAR __builtin_amdgcn_s_barrier()
; #define SCHED __builtin_amdgcn_sched_barrier(0)
; template <int EPI, int K, int KL> ...
;     ...
;   for (int t = 0; t < nt - 2; t += 2) {
;     LDB(B0, 0, 0); SCHED; LDA(At, 0, 0); STAGE(SA(1, 1), A, brow + HALF, t + 1);
;     WAIT_L(8); BAR; WAIT_L(0); MMA(0, 0, At, B0); BAR; SCHED;
;     LDB(B1, 0, 1); STAGE(SB(0, 0), Bt, bcol, t + 2);
;     BAR; WAIT_L(0); MMA(0, 1, At, B1); BAR;
;     LDA(At, 0, 1); STAGE(SA(0, 0), A, brow, t + 2);
;     BAR; WAIT_L(0); MMA(1, 0, At, B0); BAR; SCHED;
.LBB0_1107:
	ds_read_b128 v[136:139], v171
	ds_read_b128 v[174:177], v171 offset:1024
	ds_read_b128 v[178:181], v171 offset:2048
	ds_read_b128 v[182:185], v171 offset:3072
	ds_read_b128 v[186:189], v163
	ds_read_b128 v[190:193], v163 offset:1024
	ds_read_b128 v[194:197], v162
	ds_read_b128 v[198:201], v162 offset:1024
	ds_read_b128 v[202:205], v161
	ds_read_b128 v[208:211], v161 offset:1024
	ds_read_b128 v[218:221], v160
	ds_read_b128 v[222:225], v160 offset:1024
	v_add_u32_e32 v172, 0xc000, v158
	v_lshl_add_u64 v[214:215], s[92:93], 0, v[148:149]
	v_readfirstlane_b32 s56, v172
	v_lshl_add_u64 v[216:217], v[214:215], 0, s[88:89]
	s_mov_b32 m0, s56
	v_add_u32_e32 v173, 0xe000, v158
	global_load_lds_dwordx4 v[216:217], off
	v_lshl_add_u64 v[216:217], s[92:93], 0, v[150:151]
	v_readfirstlane_b32 s56, v173
	v_lshl_add_u64 v[226:227], v[216:217], 0, s[88:89]
	s_mov_b32 m0, s56
	s_nop 0
	global_load_lds_dwordx4 v[226:227], off
	s_waitcnt lgkmcnt(8)
	s_barrier
	s_waitcnt lgkmcnt(0)
	v_mfma_f32_16x16x32_bf16 v[0:3], v[136:139], v[186:189], v[0:3]
	v_mfma_f32_16x16x32_bf16 v[4:7], v[178:181], v[186:189], v[4:7]
	v_mfma_f32_16x16x32_bf16 v[8:11], v[136:139], v[194:197], v[8:11]
	v_mfma_f32_16x16x32_bf16 v[16:19], v[178:181], v[194:197], v[16:19]
	v_mfma_f32_16x16x32_bf16 v[28:31], v[136:139], v[202:205], v[28:31]
	v_mfma_f32_16x16x32_bf16 v[40:43], v[178:181], v[202:205], v[40:43]
	v_mfma_f32_16x16x32_bf16 v[52:55], v[136:139], v[218:221], v[52:55]
	v_mfma_f32_16x16x32_bf16 v[64:67], v[178:181], v[218:221], v[64:67]
	v_mfma_f32_16x16x32_bf16 v[0:3], v[174:177], v[190:193], v[0:3]
	v_mfma_f32_16x16x32_bf16 v[4:7], v[182:185], v[190:193], v[4:7]
	v_mfma_f32_16x16x32_bf16 v[8:11], v[174:177], v[198:201], v[8:11]
	v_mfma_f32_16x16x32_bf16 v[16:19], v[182:185], v[198:201], v[16:19]
	v_mfma_f32_16x16x32_bf16 v[28:31], v[174:177], v[208:211], v[28:31]
	v_mfma_f32_16x16x32_bf16 v[40:43], v[182:185], v[208:211], v[40:43]
	v_mfma_f32_16x16x32_bf16 v[52:55], v[174:177], v[222:225], v[52:55]
	v_mfma_f32_16x16x32_bf16 v[64:67], v[182:185], v[222:225], v[64:67]
	s_barrier
	ds_read_b128 v[226:229], v169
	ds_read_b128 v[230:233], v169 offset:1024
	ds_read_b128 v[234:237], v169 offset:2048
	ds_read_b128 v[238:241], v169 offset:3072
	v_lshl_add_u64 v[242:243], s[92:93], 0, v[144:145]
	v_readfirstlane_b32 s56, v157
	v_lshl_add_u64 v[244:245], v[242:243], 0, s[2:3]
	s_mov_b32 m0, s56
	v_add_u32_e32 v134, 0x2000, v157
	global_load_lds_dwordx4 v[244:245], off
	v_lshl_add_u64 v[244:245], s[92:93], 0, v[146:147]
	v_readfirstlane_b32 s56, v134
	v_lshl_add_u64 v[246:247], v[244:245], 0, s[2:3]
	s_mov_b32 m0, s56
	s_nop 0
	global_load_lds_dwordx4 v[246:247], off
	s_barrier
	s_waitcnt lgkmcnt(0)
	v_mfma_f32_16x16x32_bf16 v[12:15], v[226:229], v[186:189], v[12:15]
	v_mfma_f32_16x16x32_bf16 v[24:27], v[234:237], v[186:189], v[24:27]
	v_mfma_f32_16x16x32_bf16 v[36:39], v[226:229], v[194:197], v[36:39]
	v_mfma_f32_16x16x32_bf16 v[48:51], v[234:237], v[194:197], v[48:51]
	v_mfma_f32_16x16x32_bf16 v[60:63], v[226:229], v[202:205], v[60:63]
	v_mfma_f32_16x16x32_bf16 v[72:75], v[234:237], v[202:205], v[72:75]
	v_mfma_f32_16x16x32_bf16 v[80:83], v[226:229], v[218:221], v[80:83]
	v_mfma_f32_16x16x32_bf16 v[88:91], v[234:237], v[218:221], v[88:91]
	v_mfma_f32_16x16x32_bf16 v[12:15], v[230:233], v[190:193], v[12:15]
	v_mfma_f32_16x16x32_bf16 v[24:27], v[238:241], v[190:193], v[24:27]
	v_mfma_f32_16x16x32_bf16 v[36:39], v[230:233], v[198:201], v[36:39]
	v_mfma_f32_16x16x32_bf16 v[48:51], v[238:241], v[198:201], v[48:51]
	v_mfma_f32_16x16x32_bf16 v[60:63], v[230:233], v[208:211], v[60:63]
	v_mfma_f32_16x16x32_bf16 v[72:75], v[238:241], v[208:211], v[72:75]
	v_mfma_f32_16x16x32_bf16 v[80:83], v[230:233], v[222:225], v[80:83]
	v_mfma_f32_16x16x32_bf16 v[88:91], v[238:241], v[222:225], v[88:91]
	v_readfirstlane_b32 s56, v158
	v_add_u32_e32 v134, 0x2000, v158
	v_lshl_add_u64 v[246:247], v[214:215], 0, s[8:9]
	s_mov_b32 m0, s56
	v_readfirstlane_b32 s56, v134
	s_barrier
	ds_read_b128 v[186:189], v163 offset:16384
	ds_read_b128 v[190:193], v163 offset:17408
	ds_read_b128 v[194:197], v162 offset:16384
	ds_read_b128 v[198:201], v162 offset:17408
	ds_read_b128 v[202:205], v161 offset:16384
	ds_read_b128 v[208:211], v161 offset:17408
	ds_read_b128 v[218:221], v160 offset:16384
	ds_read_b128 v[222:225], v160 offset:17408
	global_load_lds_dwordx4 v[246:247], off
	v_lshl_add_u64 v[246:247], v[216:217], 0, s[8:9]
	s_mov_b32 m0, s56
	s_nop 0
	global_load_lds_dwordx4 v[246:247], off
	s_barrier
	s_waitcnt lgkmcnt(0)
	v_mfma_f32_16x16x32_bf16 v[20:23], v[136:139], v[186:189], v[20:23]
	v_mfma_f32_16x16x32_bf16 v[32:35], v[178:181], v[186:189], v[32:35]
	v_mfma_f32_16x16x32_bf16 v[44:47], v[136:139], v[194:197], v[44:47]
	v_mfma_f32_16x16x32_bf16 v[56:59], v[178:181], v[194:197], v[56:59]
	v_mfma_f32_16x16x32_bf16 v[68:71], v[136:139], v[202:205], v[68:71]
	v_mfma_f32_16x16x32_bf16 v[76:79], v[178:181], v[202:205], v[76:79]
	v_mfma_f32_16x16x32_bf16 v[84:87], v[136:139], v[218:221], v[84:87]
	v_mfma_f32_16x16x32_bf16 v[92:95], v[178:181], v[218:221], v[92:95]
	v_mfma_f32_16x16x32_bf16 v[20:23], v[174:177], v[190:193], v[20:23]
	v_mfma_f32_16x16x32_bf16 v[32:35], v[182:185], v[190:193], v[32:35]
	v_mfma_f32_16x16x32_bf16 v[44:47], v[174:177], v[198:201], v[44:47]
	v_mfma_f32_16x16x32_bf16 v[56:59], v[182:185], v[198:201], v[56:59]
	v_mfma_f32_16x16x32_bf16 v[68:71], v[174:177], v[208:211], v[68:71]
	v_mfma_f32_16x16x32_bf16 v[76:79], v[182:185], v[208:211], v[76:79]
	v_mfma_f32_16x16x32_bf16 v[84:87], v[174:177], v[222:225], v[84:87]
	v_mfma_f32_16x16x32_bf16 v[92:95], v[182:185], v[222:225], v[92:95]
	s_barrier
; #define STAGE(P, BASE, br, kt) STAGET(tid_, P, BASE, br, kt)
; #define LDA(dst, b, h) UFOR(m, 4) UFOR(k, 2) \
;     dst[m][k] = *reinterpret_cast<const bf16x8*>((char*)SA(b, h) + lds_byte(wr * 64 + m * 16 + fr, k * 32 + fq * 8))
; #define LDB(dst, b, h) UFOR(n, 2) UFOR(k, 2) \
;     dst[n][k] = *reinterpret_cast<const bf16x8*>((char*)SB(b, h) + lds_byte(wc * 32 + n * 16 + fr, k * 32 + fq * 8))
; #define MMA(ai, bj, At, Bq) do { __builtin_amdgcn_s_setprio(1); \
;     UFOR(m, 4) UFOR(n, 2) UFOR(k, 2) \
;       acc[ai][bj][m][n] = __builtin_amdgcn_mfma_f32_16x16x32_bf16(Bq[n][k], At[m][k], acc[ai][bj][m][n], 0, 0, 0); \
;     __builtin_amdgcn_s_setprio(0); } while (0)
; #define WAIT_V(n) asm volatile("s_waitcnt vmcnt(" #n ")" ::: "memory")
; #define WAIT_L(n) asm volatile("s_waitcnt lgkmcnt(" #n ")" ::: "memory")
; #define BAR __builtin_amdgcn_s_barrier()
; #define SCHED __builtin_amdgcn_sched_barrier(0)
; template <int EPI, int K, int KL> ...
;     ...
;     BAR; WAIT_L(0); MMA(1, 0, At, B0); BAR; SCHED;
;     STAGE(SB(0, 1), Bt, bcol + HALF, t + 2);
;     WAIT_V(6); BAR; MMA(1, 1, At, B1); BAR;
;     LDB(B0, 1, 0); SCHED; LDA(At, 1, 0); STAGE(SA(0, 1), A, brow + HALF, t + 2);
;     WAIT_L(8); BAR; WAIT_L(0); MMA(0, 0, At, B0); BAR; SCHED;
;     LDB(B1, 1, 1); STAGE(SB(1, 0), Bt, bcol, t + 3);
;     BAR; WAIT_L(0); MMA(0, 1, At, B1); BAR;
;     LDA(At, 1, 1); STAGE(SA(1, 0), A, brow, t + 3);
	v_readfirstlane_b32 s56, v159
	v_add_u32_e32 v134, 0x2000, v159
	v_lshl_add_u64 v[136:137], v[242:243], 0, s[96:97]
	s_mov_b32 m0, s56
	v_readfirstlane_b32 s56, v134
	global_load_lds_dwordx4 v[136:137], off
	v_lshl_add_u64 v[136:137], v[244:245], 0, s[96:97]
	s_mov_b32 m0, s56
	s_nop 0
	global_load_lds_dwordx4 v[136:137], off
	s_waitcnt vmcnt(6)
	s_barrier
	v_mfma_f32_16x16x32_bf16 v[96:99], v[226:229], v[186:189], v[96:99]
	v_mfma_f32_16x16x32_bf16 v[100:103], v[234:237], v[186:189], v[100:103]
	v_mfma_f32_16x16x32_bf16 v[104:107], v[226:229], v[194:197], v[104:107]
	v_mfma_f32_16x16x32_bf16 v[108:111], v[234:237], v[194:197], v[108:111]
	v_mfma_f32_16x16x32_bf16 v[112:115], v[226:229], v[202:205], v[112:115]
	v_mfma_f32_16x16x32_bf16 v[116:119], v[234:237], v[202:205], v[116:119]
	v_mfma_f32_16x16x32_bf16 v[120:123], v[226:229], v[218:221], v[120:123]
	v_mfma_f32_16x16x32_bf16 v[124:127], v[234:237], v[218:221], v[124:127]
	v_mfma_f32_16x16x32_bf16 v[96:99], v[230:233], v[190:193], v[96:99]
	v_mfma_f32_16x16x32_bf16 v[100:103], v[238:241], v[190:193], v[100:103]
	v_mfma_f32_16x16x32_bf16 v[104:107], v[230:233], v[198:201], v[104:107]
	v_mfma_f32_16x16x32_bf16 v[108:111], v[238:241], v[198:201], v[108:111]
	v_mfma_f32_16x16x32_bf16 v[112:115], v[230:233], v[208:211], v[112:115]
	v_mfma_f32_16x16x32_bf16 v[116:119], v[238:241], v[208:211], v[116:119]
	v_mfma_f32_16x16x32_bf16 v[120:123], v[230:233], v[222:225], v[120:123]
	v_mfma_f32_16x16x32_bf16 v[124:127], v[238:241], v[222:225], v[124:127]
	s_barrier
	ds_read_b128 v[136:139], v166
	ds_read_b128 v[174:177], v166 offset:1024
	ds_read_b128 v[178:181], v166 offset:2048
	ds_read_b128 v[182:185], v166 offset:3072
	ds_read_b128 v[186:189], v163 offset:32768
	ds_read_b128 v[190:193], v163 offset:33792
	ds_read_b128 v[194:197], v162 offset:32768
	ds_read_b128 v[198:201], v162 offset:33792
	ds_read_b128 v[202:205], v161 offset:32768
	ds_read_b128 v[208:211], v161 offset:33792
	ds_read_b128 v[218:221], v160 offset:32768
	ds_read_b128 v[222:225], v160 offset:33792
	v_add_u32_e32 v134, 0x4000, v158
	v_lshl_add_u64 v[226:227], v[214:215], 0, s[12:13]
	v_readfirstlane_b32 s56, v134
	v_add_u32_e32 v134, 0x6000, v158
	s_mov_b32 m0, s56
	v_readfirstlane_b32 s56, v134
	global_load_lds_dwordx4 v[226:227], off
	v_lshl_add_u64 v[226:227], v[216:217], 0, s[12:13]
	s_mov_b32 m0, s56
	s_nop 0
	global_load_lds_dwordx4 v[226:227], off
	s_waitcnt lgkmcnt(8)
	s_barrier
	s_waitcnt lgkmcnt(0)
	v_mfma_f32_16x16x32_bf16 v[0:3], v[136:139], v[186:189], v[0:3]
	v_mfma_f32_16x16x32_bf16 v[4:7], v[178:181], v[186:189], v[4:7]
	v_mfma_f32_16x16x32_bf16 v[8:11], v[136:139], v[194:197], v[8:11]
	v_mfma_f32_16x16x32_bf16 v[16:19], v[178:181], v[194:197], v[16:19]
	v_mfma_f32_16x16x32_bf16 v[28:31], v[136:139], v[202:205], v[28:31]
	v_mfma_f32_16x16x32_bf16 v[40:43], v[178:181], v[202:205], v[40:43]
	v_mfma_f32_16x16x32_bf16 v[52:55], v[136:139], v[218:221], v[52:55]
	v_mfma_f32_16x16x32_bf16 v[64:67], v[178:181], v[218:221], v[64:67]
	v_mfma_f32_16x16x32_bf16 v[0:3], v[174:177], v[190:193], v[0:3]
	v_mfma_f32_16x16x32_bf16 v[4:7], v[182:185], v[190:193], v[4:7]
	v_mfma_f32_16x16x32_bf16 v[8:11], v[174:177], v[198:201], v[8:11]
	v_mfma_f32_16x16x32_bf16 v[16:19], v[182:185], v[198:201], v[16:19]
	v_mfma_f32_16x16x32_bf16 v[28:31], v[174:177], v[208:211], v[28:31]
	v_mfma_f32_16x16x32_bf16 v[40:43], v[182:185], v[208:211], v[40:43]
	v_mfma_f32_16x16x32_bf16 v[52:55], v[174:177], v[222:225], v[52:55]
	v_mfma_f32_16x16x32_bf16 v[64:67], v[182:185], v[222:225], v[64:67]
	s_barrier
	ds_read_b128 v[226:229], v164
	ds_read_b128 v[230:233], v164 offset:1024
	ds_read_b128 v[234:237], v164 offset:2048
	ds_read_b128 v[238:241], v164 offset:3072
	v_readfirstlane_b32 s56, v165
	v_add_u32_e32 v134, 0x2000, v165
	v_lshl_add_u64 v[246:247], v[242:243], 0, s[80:81]
	s_mov_b32 m0, s56
	v_readfirstlane_b32 s56, v134
	global_load_lds_dwordx4 v[246:247], off
	v_lshl_add_u64 v[246:247], v[244:245], 0, s[80:81]
	s_mov_b32 m0, s56
	s_nop 0
	global_load_lds_dwordx4 v[246:247], off
	s_barrier
	s_waitcnt lgkmcnt(0)
	v_mfma_f32_16x16x32_bf16 v[12:15], v[226:229], v[186:189], v[12:15]
	v_mfma_f32_16x16x32_bf16 v[24:27], v[234:237], v[186:189], v[24:27]
	v_mfma_f32_16x16x32_bf16 v[36:39], v[226:229], v[194:197], v[36:39]
	v_mfma_f32_16x16x32_bf16 v[48:51], v[234:237], v[194:197], v[48:51]
	v_mfma_f32_16x16x32_bf16 v[60:63], v[226:229], v[202:205], v[60:63]
	v_mfma_f32_16x16x32_bf16 v[72:75], v[234:237], v[202:205], v[72:75]
	v_mfma_f32_16x16x32_bf16 v[80:83], v[226:229], v[218:221], v[80:83]
	v_mfma_f32_16x16x32_bf16 v[88:91], v[234:237], v[218:221], v[88:91]
	v_mfma_f32_16x16x32_bf16 v[12:15], v[230:233], v[190:193], v[12:15]
	v_mfma_f32_16x16x32_bf16 v[24:27], v[238:241], v[190:193], v[24:27]
	v_mfma_f32_16x16x32_bf16 v[36:39], v[230:233], v[198:201], v[36:39]
	v_mfma_f32_16x16x32_bf16 v[48:51], v[238:241], v[198:201], v[48:51]
	v_mfma_f32_16x16x32_bf16 v[60:63], v[230:233], v[208:211], v[60:63]
	v_mfma_f32_16x16x32_bf16 v[72:75], v[238:241], v[208:211], v[72:75]
	v_mfma_f32_16x16x32_bf16 v[80:83], v[230:233], v[222:225], v[80:83]
	v_mfma_f32_16x16x32_bf16 v[88:91], v[238:241], v[222:225], v[88:91]
	v_readfirstlane_b32 s56, v167
	v_lshl_add_u64 v[214:215], v[214:215], 0, s[16:17]
	s_mov_b32 m0, s56
	v_readfirstlane_b32 s56, v168
	s_barrier
	ds_read_b128 v[186:189], v163 offset:49152
	ds_read_b128 v[190:193], v163 offset:50176
	ds_read_b128 v[194:197], v162 offset:49152
	ds_read_b128 v[198:201], v162 offset:50176
	ds_read_b128 v[202:205], v161 offset:49152
	ds_read_b128 v[208:211], v161 offset:50176
	ds_read_b128 v[218:221], v160 offset:49152
	ds_read_b128 v[222:225], v160 offset:50176
	global_load_lds_dwordx4 v[214:215], off
	v_lshl_add_u64 v[214:215], v[216:217], 0, s[16:17]
	s_mov_b32 m0, s56
	s_nop 0
	global_load_lds_dwordx4 v[214:215], off
	s_barrier
; #define STAGE(P, BASE, br, kt) STAGET(tid_, P, BASE, br, kt)
; #define LDA(dst, b, h) UFOR(m, 4) UFOR(k, 2) \
;     dst[m][k] = *reinterpret_cast<const bf16x8*>((char*)SA(b, h) + lds_byte(wr * 64 + m * 16 + fr, k * 32 + fq * 8))
; #define LDB(dst, b, h) UFOR(n, 2) UFOR(k, 2) \
;     dst[n][k] = *reinterpret_cast<const bf16x8*>((char*)SB(b, h) + lds_byte(wc * 32 + n * 16 + fr, k * 32 + fq * 8))
; #define MMA(ai, bj, At, Bq) do { __builtin_amdgcn_s_setprio(1); \
;     UFOR(m, 4) UFOR(n, 2) UFOR(k, 2) \
;       acc[ai][bj][m][n] = __builtin_amdgcn_mfma_f32_16x16x32_bf16(Bq[n][k], At[m][k], acc[ai][bj][m][n], 0, 0, 0); \
;     __builtin_amdgcn_s_setprio(0); } while (0)
; #define WAIT_V(n) asm volatile("s_waitcnt vmcnt(" #n ")" ::: "memory")
; #define WAIT_L(n) asm volatile("s_waitcnt lgkmcnt(" #n ")" ::: "memory")
; #define BAR __builtin_amdgcn_s_barrier()
; #define SCHED __builtin_amdgcn_sched_barrier(0)
; template <int EPI, int K, int KL> ...
;     ...
;     LDA(At, 1, 1); STAGE(SA(1, 0), A, brow, t + 3);
;     BAR; WAIT_L(0); MMA(1, 0, At, B0); BAR; SCHED;
;     STAGE(SB(1, 1), Bt, bcol + HALF, t + 3);
;     WAIT_V(6); BAR; MMA(1, 1, At, B1); BAR;
;   }
;   { LDB(B0, 0, 0); LDA(At, 0, 0); STAGE(SA(1, 1), A, brow + HALF, nt - 1);
;     BAR; WAIT_L(0); MMA(0, 0, At, B0); BAR;
	s_waitcnt lgkmcnt(0)
	v_mfma_f32_16x16x32_bf16 v[20:23], v[136:139], v[186:189], v[20:23]
	v_mfma_f32_16x16x32_bf16 v[32:35], v[178:181], v[186:189], v[32:35]
	v_mfma_f32_16x16x32_bf16 v[44:47], v[136:139], v[194:197], v[44:47]
	v_mfma_f32_16x16x32_bf16 v[56:59], v[178:181], v[194:197], v[56:59]
	v_mfma_f32_16x16x32_bf16 v[68:71], v[136:139], v[202:205], v[68:71]
	v_mfma_f32_16x16x32_bf16 v[76:79], v[178:181], v[202:205], v[76:79]
	v_mfma_f32_16x16x32_bf16 v[84:87], v[136:139], v[218:221], v[84:87]
	v_mfma_f32_16x16x32_bf16 v[92:95], v[178:181], v[218:221], v[92:95]
	v_mfma_f32_16x16x32_bf16 v[20:23], v[174:177], v[190:193], v[20:23]
	v_mfma_f32_16x16x32_bf16 v[32:35], v[182:185], v[190:193], v[32:35]
	v_mfma_f32_16x16x32_bf16 v[44:47], v[174:177], v[198:201], v[44:47]
	v_mfma_f32_16x16x32_bf16 v[56:59], v[182:185], v[198:201], v[56:59]
	v_mfma_f32_16x16x32_bf16 v[68:71], v[174:177], v[208:211], v[68:71]
	v_mfma_f32_16x16x32_bf16 v[76:79], v[182:185], v[208:211], v[76:79]
	v_mfma_f32_16x16x32_bf16 v[84:87], v[174:177], v[222:225], v[84:87]
	v_mfma_f32_16x16x32_bf16 v[92:95], v[182:185], v[222:225], v[92:95]
	s_barrier
	v_readfirstlane_b32 s56, v170
	v_add_u32_e32 v134, 0x2000, v170
	v_lshl_add_u64 v[136:137], v[242:243], 0, s[90:91]
	s_mov_b32 m0, s56
	v_readfirstlane_b32 s56, v134
	global_load_lds_dwordx4 v[136:137], off
	v_lshl_add_u64 v[136:137], v[244:245], 0, s[90:91]
	s_mov_b32 m0, s56
	s_nop 0
	global_load_lds_dwordx4 v[136:137], off
	s_waitcnt vmcnt(6)
	s_barrier
	v_mfma_f32_16x16x32_bf16 v[96:99], v[226:229], v[186:189], v[96:99]
	v_mfma_f32_16x16x32_bf16 v[100:103], v[234:237], v[186:189], v[100:103]
	v_mfma_f32_16x16x32_bf16 v[104:107], v[226:229], v[194:197], v[104:107]
	v_mfma_f32_16x16x32_bf16 v[108:111], v[234:237], v[194:197], v[108:111]
	v_mfma_f32_16x16x32_bf16 v[112:115], v[226:229], v[202:205], v[112:115]
	v_mfma_f32_16x16x32_bf16 v[116:119], v[234:237], v[202:205], v[116:119]
	v_mfma_f32_16x16x32_bf16 v[120:123], v[226:229], v[218:221], v[120:123]
	v_mfma_f32_16x16x32_bf16 v[124:127], v[234:237], v[218:221], v[124:127]
	v_mfma_f32_16x16x32_bf16 v[96:99], v[230:233], v[190:193], v[96:99]
	v_mfma_f32_16x16x32_bf16 v[100:103], v[238:241], v[190:193], v[100:103]
	v_mfma_f32_16x16x32_bf16 v[104:107], v[230:233], v[198:201], v[104:107]
	v_mfma_f32_16x16x32_bf16 v[108:111], v[238:241], v[198:201], v[108:111]
	v_mfma_f32_16x16x32_bf16 v[112:115], v[230:233], v[208:211], v[112:115]
	v_mfma_f32_16x16x32_bf16 v[116:119], v[238:241], v[208:211], v[116:119]
	v_mfma_f32_16x16x32_bf16 v[120:123], v[230:233], v[222:225], v[120:123]
	v_mfma_f32_16x16x32_bf16 v[124:127], v[238:241], v[222:225], v[124:127]
	s_add_i32 s53, s53, 2
	v_lshl_add_u64 v[144:145], v[144:145], 0, s[20:21]
	v_lshl_add_u64 v[146:147], v[146:147], 0, s[20:21]
	v_lshl_add_u64 v[148:149], v[148:149], 0, s[20:21]
	s_cmp_lt_u32 s53, 28
	v_lshl_add_u64 v[150:151], v[150:151], 0, s[20:21]
	s_cbranch_scc1 .Lkrot_1107
	s_barrier
	s_add_u32 s40, s40, 0x80f80
	s_addc_u32 s41, s41, 0
	v_lshl_add_u64 v[130:131], s[40:41], 0, v[130:131]
	v_readfirstlane_b32 s53, v172
	v_lshl_add_u64 v[128:129], v[128:129], 1, v[130:131]
	s_mov_b32 m0, s53
	ds_read_b128 v[136:139], v171
	ds_read_b128 v[144:147], v171 offset:1024
	ds_read_b128 v[148:151], v171 offset:2048
	ds_read_b128 v[174:177], v171 offset:3072
	ds_read_b128 v[178:181], v163
	ds_read_b128 v[182:185], v163 offset:1024
	ds_read_b128 v[186:189], v162
	ds_read_b128 v[190:193], v162 offset:1024
	ds_read_b128 v[194:197], v161
	ds_read_b128 v[198:201], v161 offset:1024
	ds_read_b128 v[202:205], v160
	ds_read_b128 v[208:211], v160 offset:1024
	global_load_lds_dwordx4 v[128:129], off
	v_lshl_add_u64 v[128:129], s[40:41], 0, v[142:143]
	v_readfirstlane_b32 s40, v173
	v_lshl_add_u64 v[128:129], v[140:141], 1, v[128:129]
	s_mov_b32 m0, s40
	s_nop 0
	global_load_lds_dwordx4 v[128:129], off
	s_barrier
	s_waitcnt lgkmcnt(0)
	s_waitcnt lgkmcnt(0)
	v_mfma_f32_16x16x32_bf16 v[0:3], v[136:139], v[178:181], v[0:3]
	v_mfma_f32_16x16x32_bf16 v[4:7], v[148:151], v[178:181], v[4:7]
	v_mfma_f32_16x16x32_bf16 v[8:11], v[136:139], v[186:189], v[8:11]
	v_mfma_f32_16x16x32_bf16 v[16:19], v[148:151], v[186:189], v[16:19]
	v_mfma_f32_16x16x32_bf16 v[28:31], v[136:139], v[194:197], v[28:31]
	v_mfma_f32_16x16x32_bf16 v[40:43], v[148:151], v[194:197], v[40:43]
	v_mfma_f32_16x16x32_bf16 v[52:55], v[136:139], v[202:205], v[52:55]
	v_mfma_f32_16x16x32_bf16 v[64:67], v[148:151], v[202:205], v[64:67]
	v_mfma_f32_16x16x32_bf16 v[0:3], v[144:147], v[182:185], v[0:3]
	v_mfma_f32_16x16x32_bf16 v[4:7], v[174:177], v[182:185], v[4:7]
	v_mfma_f32_16x16x32_bf16 v[8:11], v[144:147], v[190:193], v[8:11]
	v_mfma_f32_16x16x32_bf16 v[16:19], v[174:177], v[190:193], v[16:19]
	v_mfma_f32_16x16x32_bf16 v[28:31], v[144:147], v[198:201], v[28:31]
	v_mfma_f32_16x16x32_bf16 v[40:43], v[174:177], v[198:201], v[40:43]
	v_mfma_f32_16x16x32_bf16 v[52:55], v[144:147], v[208:211], v[52:55]
	v_mfma_f32_16x16x32_bf16 v[64:67], v[174:177], v[208:211], v[64:67]
	s_barrier
	ds_read_b128 v[128:131], v169
	ds_read_b128 v[140:143], v169 offset:1024
	ds_read_b128 v[170:173], v169 offset:2048
	ds_read_b128 v[218:221], v169 offset:3072
	s_barrier
; #define STAGE(P, BASE, br, kt) STAGET(tid_, P, BASE, br, kt)
; #define LDA(dst, b, h) UFOR(m, 4) UFOR(k, 2) \
;     dst[m][k] = *reinterpret_cast<const bf16x8*>((char*)SA(b, h) + lds_byte(wr * 64 + m * 16 + fr, k * 32 + fq * 8))
; #define LDB(dst, b, h) UFOR(n, 2) UFOR(k, 2) \
;     dst[n][k] = *reinterpret_cast<const bf16x8*>((char*)SB(b, h) + lds_byte(wc * 32 + n * 16 + fr, k * 32 + fq * 8))
; #define MMA(ai, bj, At, Bq) do { __builtin_amdgcn_s_setprio(1); \
;     UFOR(m, 4) UFOR(n, 2) UFOR(k, 2) \
;       acc[ai][bj][m][n] = __builtin_amdgcn_mfma_f32_16x16x32_bf16(Bq[n][k], At[m][k], acc[ai][bj][m][n], 0, 0, 0); \
;     __builtin_amdgcn_s_setprio(0); } while (0)
; #define WAIT_V(n) asm volatile("s_waitcnt vmcnt(" #n ")" ::: "memory")
; #define WAIT_L(n) asm volatile("s_waitcnt lgkmcnt(" #n ")" ::: "memory")
; #define BAR __builtin_amdgcn_s_barrier()
; template <int EPI, int K, int KL> ...
;     ...
;   { LDB(B0, 0, 0); LDA(At, 0, 0); STAGE(SA(1, 1), A, brow + HALF, nt - 1);
;     BAR; WAIT_L(0); MMA(0, 0, At, B0); BAR;
;     LDB(B1, 0, 1); BAR; WAIT_L(0); MMA(0, 1, At, B1); BAR;
;     LDA(At, 0, 1); WAIT_V(4); BAR; WAIT_L(0); MMA(1, 0, At, B0); MMA(1, 1, At, B1); BAR; }
;   { LDB(B0, 1, 0); LDA(At, 1, 0); WAIT_V(2); BAR; WAIT_L(0); MMA(0, 0, At, B0); BAR;
	s_waitcnt lgkmcnt(0)
	s_waitcnt lgkmcnt(0)
	v_mfma_f32_16x16x32_bf16 v[12:15], v[128:131], v[178:181], v[12:15]
	v_mfma_f32_16x16x32_bf16 v[24:27], v[170:173], v[178:181], v[24:27]
	v_mfma_f32_16x16x32_bf16 v[36:39], v[128:131], v[186:189], v[36:39]
	v_mfma_f32_16x16x32_bf16 v[48:51], v[170:173], v[186:189], v[48:51]
	v_mfma_f32_16x16x32_bf16 v[60:63], v[128:131], v[194:197], v[60:63]
	v_mfma_f32_16x16x32_bf16 v[72:75], v[170:173], v[194:197], v[72:75]
	v_mfma_f32_16x16x32_bf16 v[80:83], v[128:131], v[202:205], v[80:83]
	v_mfma_f32_16x16x32_bf16 v[12:15], v[140:143], v[182:185], v[12:15]
	v_mfma_f32_16x16x32_bf16 v[24:27], v[218:221], v[182:185], v[24:27]
	v_mfma_f32_16x16x32_bf16 v[36:39], v[140:143], v[190:193], v[36:39]
	v_mfma_f32_16x16x32_bf16 v[48:51], v[218:221], v[190:193], v[48:51]
	v_mfma_f32_16x16x32_bf16 v[60:63], v[140:143], v[198:201], v[60:63]
	v_mfma_f32_16x16x32_bf16 v[72:75], v[218:221], v[198:201], v[72:75]
	v_mfma_f32_16x16x32_bf16 v[178:181], v[140:143], v[208:211], v[80:83]
	v_mfma_f32_16x16x32_bf16 v[80:83], v[170:173], v[202:205], v[88:91]
	v_mfma_f32_16x16x32_bf16 v[182:185], v[218:221], v[208:211], v[80:83]
	s_barrier
	s_nop 5
	ds_read_b128 v[80:83], v163 offset:16384
	ds_read_b128 v[88:91], v163 offset:17408
	ds_read_b128 v[186:189], v162 offset:16384
	ds_read_b128 v[190:193], v162 offset:17408
	ds_read_b128 v[194:197], v161 offset:16384
	ds_read_b128 v[198:201], v161 offset:17408
	ds_read_b128 v[202:205], v160 offset:16384
	ds_read_b128 v[208:211], v160 offset:17408
	s_waitcnt vmcnt(4)
	s_barrier
	s_waitcnt lgkmcnt(0)
	s_waitcnt lgkmcnt(0)
	v_mfma_f32_16x16x32_bf16 v[56:59], v[148:151], v[186:189], v[56:59]
	v_mfma_f32_16x16x32_bf16 v[222:225], v[174:177], v[190:193], v[56:59]
	v_mfma_f32_16x16x32_bf16 v[56:59], v[136:139], v[194:197], v[68:71]
	v_mfma_f32_16x16x32_bf16 v[226:229], v[144:147], v[198:201], v[56:59]
	v_mfma_f32_16x16x32_bf16 v[56:59], v[148:151], v[194:197], v[76:79]
	v_mfma_f32_16x16x32_bf16 v[20:23], v[136:139], v[80:83], v[20:23]
	v_mfma_f32_16x16x32_bf16 v[32:35], v[148:151], v[80:83], v[32:35]
	v_mfma_f32_16x16x32_bf16 v[44:47], v[136:139], v[186:189], v[44:47]
	v_mfma_f32_16x16x32_bf16 v[230:233], v[174:177], v[198:201], v[56:59]
	v_mfma_f32_16x16x32_bf16 v[56:59], v[136:139], v[202:205], v[84:87]
	v_mfma_f32_16x16x32_bf16 v[20:23], v[144:147], v[88:91], v[20:23]
	v_mfma_f32_16x16x32_bf16 v[32:35], v[174:177], v[88:91], v[32:35]
	v_mfma_f32_16x16x32_bf16 v[44:47], v[144:147], v[190:193], v[44:47]
	v_mfma_f32_16x16x32_bf16 v[136:139], v[144:147], v[208:211], v[56:59]
	v_mfma_f32_16x16x32_bf16 v[56:59], v[148:151], v[202:205], v[92:95]
	v_mfma_f32_16x16x32_bf16 v[144:147], v[174:177], v[208:211], v[56:59]
	v_mfma_f32_16x16x32_bf16 v[56:59], v[128:131], v[80:83], v[96:99]
	v_mfma_f32_16x16x32_bf16 v[148:151], v[140:143], v[88:91], v[56:59]
	v_mfma_f32_16x16x32_bf16 v[56:59], v[170:173], v[80:83], v[100:103]
	v_mfma_f32_16x16x32_bf16 v[174:177], v[218:221], v[88:91], v[56:59]
	v_mfma_f32_16x16x32_bf16 v[56:59], v[128:131], v[186:189], v[104:107]
	v_mfma_f32_16x16x32_bf16 v[234:237], v[140:143], v[190:193], v[56:59]
	v_mfma_f32_16x16x32_bf16 v[56:59], v[170:173], v[186:189], v[108:111]
	v_mfma_f32_16x16x32_bf16 v[186:189], v[218:221], v[190:193], v[56:59]
	v_mfma_f32_16x16x32_bf16 v[56:59], v[128:131], v[194:197], v[112:115]
	v_mfma_f32_16x16x32_bf16 v[190:193], v[140:143], v[198:201], v[56:59]
	v_mfma_f32_16x16x32_bf16 v[56:59], v[170:173], v[194:197], v[116:119]
	v_mfma_f32_16x16x32_bf16 v[194:197], v[218:221], v[198:201], v[56:59]
	v_mfma_f32_16x16x32_bf16 v[56:59], v[128:131], v[202:205], v[120:123]
	v_mfma_f32_16x16x32_bf16 v[128:131], v[140:143], v[208:211], v[56:59]
	v_mfma_f32_16x16x32_bf16 v[56:59], v[170:173], v[202:205], v[124:127]
	v_mfma_f32_16x16x32_bf16 v[140:143], v[218:221], v[208:211], v[56:59]
	s_barrier
	ds_read_b128 v[168:171], v166
	ds_read_b128 v[198:201], v166 offset:1024
	ds_read_b128 v[202:205], v166 offset:2048
	ds_read_b128 v[208:211], v166 offset:3072
	s_nop 1
	ds_read_b128 v[56:59], v163 offset:32768
	ds_read_b128 v[68:71], v163 offset:33792
	ds_read_b128 v[76:79], v162 offset:32768
	ds_read_b128 v[80:83], v162 offset:33792
	ds_read_b128 v[218:221], v161 offset:32768
	ds_read_b128 v[238:241], v161 offset:33792
	ds_read_b128 v[242:245], v160 offset:32768
	ds_read_b128 v[246:249], v160 offset:33792
	s_waitcnt vmcnt(2)
	s_barrier
	s_waitcnt lgkmcnt(0)
	s_waitcnt lgkmcnt(0)
	v_mfma_f32_16x16x32_bf16 v[0:3], v[168:171], v[56:59], v[0:3]
	v_mfma_f32_16x16x32_bf16 v[124:127], v[198:201], v[68:71], v[0:3]
	v_mfma_f32_16x16x32_bf16 v[0:3], v[202:205], v[56:59], v[4:7]
	v_mfma_f32_16x16x32_bf16 v[120:123], v[208:211], v[68:71], v[0:3]
	v_mfma_f32_16x16x32_bf16 v[0:3], v[168:171], v[76:79], v[8:11]
	v_mfma_f32_16x16x32_bf16 v[116:119], v[198:201], v[80:83], v[0:3]
	v_mfma_f32_16x16x32_bf16 v[0:3], v[202:205], v[76:79], v[16:19]
	v_mfma_f32_16x16x32_bf16 v[112:115], v[208:211], v[80:83], v[0:3]
	v_mfma_f32_16x16x32_bf16 v[0:3], v[168:171], v[218:221], v[28:31]
	v_mfma_f32_16x16x32_bf16 v[108:111], v[198:201], v[238:241], v[0:3]
	v_mfma_f32_16x16x32_bf16 v[0:3], v[202:205], v[218:221], v[40:43]
	v_mfma_f32_16x16x32_bf16 v[104:107], v[208:211], v[238:241], v[0:3]
	v_mfma_f32_16x16x32_bf16 v[0:3], v[168:171], v[242:245], v[52:55]
	v_mfma_f32_16x16x32_bf16 v[100:103], v[198:201], v[246:249], v[0:3]
	v_mfma_f32_16x16x32_bf16 v[0:3], v[202:205], v[242:245], v[64:67]
	v_mfma_f32_16x16x32_bf16 v[96:99], v[208:211], v[246:249], v[0:3]
	s_barrier
; #define UFOR(v, n) _Pragma("unroll") for (int v = 0; v < (n); ++v)
; #define LDA(dst, b, h) UFOR(m, 4) UFOR(k, 2) \
;     dst[m][k] = *reinterpret_cast<const bf16x8*>((char*)SA(b, h) + lds_byte(wr * 64 + m * 16 + fr, k * 32 + fq * 8))
; #define LDB(dst, b, h) UFOR(n, 2) UFOR(k, 2) \
;     dst[n][k] = *reinterpret_cast<const bf16x8*>((char*)SB(b, h) + lds_byte(wc * 32 + n * 16 + fr, k * 32 + fq * 8))
; #define MMA(ai, bj, At, Bq) do { __builtin_amdgcn_s_setprio(1); \
;     UFOR(m, 4) UFOR(n, 2) UFOR(k, 2) \
;       acc[ai][bj][m][n] = __builtin_amdgcn_mfma_f32_16x16x32_bf16(Bq[n][k], At[m][k], acc[ai][bj][m][n], 0, 0, 0); \
;     __builtin_amdgcn_s_setprio(0); } while (0)
; #define WAIT_V(n) asm volatile("s_waitcnt vmcnt(" #n ")" ::: "memory")
; #define WAIT_L(n) asm volatile("s_waitcnt lgkmcnt(" #n ")" ::: "memory")
; #define BAR __builtin_amdgcn_s_barrier()
; template <int EPI, int K, int KL> ...
;     ...
;   { LDB(B0, 1, 0); LDA(At, 1, 0); WAIT_V(2); BAR; WAIT_L(0); MMA(0, 0, At, B0); BAR;
;     LDB(B1, 1, 1); WAIT_V(0); BAR; WAIT_L(0); MMA(0, 1, At, B1); BAR;
;     LDA(At, 1, 1); BAR; WAIT_L(0); MMA(1, 0, At, B0); MMA(1, 1, At, B1); BAR; }
;   if (wr == 0) BAR;
;     ...
;       const int c4 = (tid_ & 31) * 4, rb = tid_ >> 5;
;       const int gc = pn * 128 + c4;
;       float wg[4][3], wv[4][3];
;       UFOR(q, 4) UFOR(x, 3) { wg[q][x] = e.cw[(size_t)(gc + q) * 3 + x]; wv[q][x] = e.cw[(size_t)(DFF + gc + q) * 3 + x]; }
	s_nop 5
	ds_read_b128 v[0:3], v164
	ds_read_b128 v[4:7], v164 offset:1024
	ds_read_b128 v[214:217], v164 offset:2048
	ds_read_b128 v[164:167], v164 offset:3072
	s_waitcnt vmcnt(0)
	s_barrier
	s_waitcnt lgkmcnt(0)
	s_waitcnt lgkmcnt(0)
	v_mfma_f32_16x16x32_bf16 v[8:11], v[0:3], v[56:59], v[12:15]
	v_mfma_f32_16x16x32_bf16 v[92:95], v[4:7], v[68:71], v[8:11]
	v_mfma_f32_16x16x32_bf16 v[8:11], v[214:217], v[56:59], v[24:27]
	v_mfma_f32_16x16x32_bf16 v[88:91], v[164:167], v[68:71], v[8:11]
	v_mfma_f32_16x16x32_bf16 v[8:11], v[0:3], v[76:79], v[36:39]
	v_mfma_f32_16x16x32_bf16 v[84:87], v[4:7], v[80:83], v[8:11]
	v_mfma_f32_16x16x32_bf16 v[8:11], v[214:217], v[76:79], v[48:51]
	v_mfma_f32_16x16x32_bf16 v[80:83], v[164:167], v[80:83], v[8:11]
	v_mfma_f32_16x16x32_bf16 v[8:11], v[0:3], v[218:221], v[60:63]
	v_mfma_f32_16x16x32_bf16 v[76:79], v[4:7], v[238:241], v[8:11]
	v_mfma_f32_16x16x32_bf16 v[8:11], v[214:217], v[218:221], v[72:75]
	v_mfma_f32_16x16x32_bf16 v[72:75], v[164:167], v[238:241], v[8:11]
	v_mfma_f32_16x16x32_bf16 v[8:11], v[0:3], v[242:245], v[178:181]
	v_mfma_f32_16x16x32_bf16 v[68:71], v[4:7], v[246:249], v[8:11]
	v_mfma_f32_16x16x32_bf16 v[8:11], v[214:217], v[242:245], v[182:185]
	v_mfma_f32_16x16x32_bf16 v[64:67], v[164:167], v[246:249], v[8:11]
	s_barrier
	s_nop 5
	ds_read_b128 v[8:11], v163 offset:49152
	ds_read_b128 v[12:15], v163 offset:50176
	ds_read_b128 v[16:19], v162 offset:49152
	ds_read_b128 v[178:181], v162 offset:50176
	ds_read_b128 v[182:185], v161 offset:49152
	ds_read_b128 v[218:221], v161 offset:50176
	ds_read_b128 v[238:241], v160 offset:49152
	ds_read_b128 v[158:161], v160 offset:50176
	s_barrier
	s_waitcnt lgkmcnt(0)
	s_waitcnt lgkmcnt(0)
	v_mfma_f32_16x16x32_bf16 v[20:23], v[168:171], v[8:11], v[20:23]
	v_mfma_f32_16x16x32_bf16 v[60:63], v[198:201], v[12:15], v[20:23]
	v_mfma_f32_16x16x32_bf16 v[20:23], v[202:205], v[8:11], v[32:35]
	v_mfma_f32_16x16x32_bf16 v[56:59], v[208:211], v[12:15], v[20:23]
	v_mfma_f32_16x16x32_bf16 v[20:23], v[168:171], v[16:19], v[44:47]
	v_mfma_f32_16x16x32_bf16 v[52:55], v[198:201], v[178:181], v[20:23]
	v_mfma_f32_16x16x32_bf16 v[20:23], v[202:205], v[16:19], v[222:225]
	v_mfma_f32_16x16x32_bf16 v[48:51], v[208:211], v[178:181], v[20:23]
	v_mfma_f32_16x16x32_bf16 v[20:23], v[168:171], v[182:185], v[226:229]
	v_mfma_f32_16x16x32_bf16 v[44:47], v[198:201], v[218:221], v[20:23]
	v_mfma_f32_16x16x32_bf16 v[20:23], v[202:205], v[182:185], v[230:233]
	v_mfma_f32_16x16x32_bf16 v[40:43], v[208:211], v[218:221], v[20:23]
	v_mfma_f32_16x16x32_bf16 v[20:23], v[168:171], v[238:241], v[136:139]
	v_mfma_f32_16x16x32_bf16 v[36:39], v[198:201], v[158:161], v[20:23]
	v_mfma_f32_16x16x32_bf16 v[20:23], v[202:205], v[238:241], v[144:147]
	v_mfma_f32_16x16x32_bf16 v[32:35], v[208:211], v[158:161], v[20:23]
	v_mfma_f32_16x16x32_bf16 v[20:23], v[0:3], v[8:11], v[148:151]
	v_mfma_f32_16x16x32_bf16 v[8:11], v[214:217], v[8:11], v[174:177]
	v_mfma_f32_16x16x32_bf16 v[24:27], v[164:167], v[12:15], v[8:11]
	v_mfma_f32_16x16x32_bf16 v[8:11], v[0:3], v[16:19], v[234:237]
	v_mfma_f32_16x16x32_bf16 v[28:31], v[4:7], v[12:15], v[20:23]
	v_mfma_f32_16x16x32_bf16 v[20:23], v[4:7], v[178:181], v[8:11]
	v_mfma_f32_16x16x32_bf16 v[8:11], v[214:217], v[16:19], v[186:189]
	v_mfma_f32_16x16x32_bf16 v[16:19], v[164:167], v[178:181], v[8:11]
	v_mfma_f32_16x16x32_bf16 v[8:11], v[0:3], v[182:185], v[190:193]
	v_mfma_f32_16x16x32_bf16 v[0:3], v[0:3], v[238:241], v[128:131]
	v_mfma_f32_16x16x32_bf16 v[12:15], v[4:7], v[218:221], v[8:11]
	v_mfma_f32_16x16x32_bf16 v[8:11], v[214:217], v[182:185], v[194:197]
	v_mfma_f32_16x16x32_bf16 v[4:7], v[4:7], v[158:161], v[0:3]
	v_mfma_f32_16x16x32_bf16 v[0:3], v[214:217], v[238:241], v[140:143]
	v_mfma_f32_16x16x32_bf16 v[8:11], v[164:167], v[218:221], v[8:11]
	v_mfma_f32_16x16x32_bf16 v[0:3], v[164:167], v[158:161], v[0:3]
	v_lshlrev_b32_e32 v242, 2, v152
	v_and_b32_e32 v242, 0x7c, v242
	v_lshl_or_b32 v242, s51, 7, v242
	v_add_u32_e32 v243, 0x1600, v242
	v_mad_i64_i32 v[244:245], vcc, v243, 12, s[46:47]
	v_mad_i64_i32 v[246:247], vcc, v242, 12, s[46:47]
	global_load_dwordx4 v[218:221], v[244:245], off offset:16
	global_load_dwordx4 v[222:225], v[244:245], off offset:32
	global_load_dwordx4 v[226:229], v[244:245], off
	global_load_dwordx4 v[230:233], v[246:247], off offset:16
	global_load_dwordx4 v[234:237], v[246:247], off offset:32
	global_load_dwordx4 v[238:241], v[246:247], off
	s_movk_i32 s40, 0x100
	v_cmp_gt_u32_e32 vcc, s40, v152
	s_barrier
	s_and_saveexec_b64 s[40:41], vcc
	s_cbranch_execz .LBB0_1110
	s_barrier

; #define STAGE(P, BASE, br, kt) STAGET(tid_, P, BASE, br, kt)
; #define LDA(dst, b, h) UFOR(m, 4) UFOR(k, 2) \
;     dst[m][k] = *reinterpret_cast<const bf16x8*>((char*)SA(b, h) + lds_byte(wr * 64 + m * 16 + fr, k * 32 + fq * 8))
; #define LDB(dst, b, h) UFOR(n, 2) UFOR(k, 2) \
;     dst[n][k] = *reinterpret_cast<const bf16x8*>((char*)SB(b, h) + lds_byte(wc * 32 + n * 16 + fr, k * 32 + fq * 8))
; #define MMA(ai, bj, At, Bq) do { __builtin_amdgcn_s_setprio(1); \
;     UFOR(m, 4) UFOR(n, 2) UFOR(k, 2) \
;       acc[ai][bj][m][n] = __builtin_amdgcn_mfma_f32_16x16x32_bf16(Bq[n][k], At[m][k], acc[ai][bj][m][n], 0, 0, 0); \
;     __builtin_amdgcn_s_setprio(0); } while (0)
; #define WAIT_L(n) asm volatile("s_waitcnt lgkmcnt(" #n ")" ::: "memory")
; #define BAR __builtin_amdgcn_s_barrier()
; #define SCHED __builtin_amdgcn_sched_barrier(0)
; template <int EPI, int K, int KL> ...
;     ...
;   for (int t = 0; t < nt - 2; t += 2) {
;     LDB(B0, 0, 0); SCHED; LDA(At, 0, 0); STAGE(SA(1, 1), A, brow + HALF, t + 1);
;     WAIT_L(8); BAR; WAIT_L(0); MMA(0, 0, At, B0); BAR; SCHED;
;     LDB(B1, 0, 1); STAGE(SB(0, 0), Bt, bcol, t + 2);
;     BAR; WAIT_L(0); MMA(0, 1, At, B1); BAR;
;     LDA(At, 0, 1); STAGE(SA(0, 0), A, brow, t + 2);
;     BAR; WAIT_L(0); MMA(1, 0, At, B0); BAR; SCHED;
.LBB0_1184:
	ds_read_b128 v[136:139], v170
	ds_read_b128 v[174:177], v170 offset:1024
	ds_read_b128 v[178:181], v170 offset:2048
	ds_read_b128 v[182:185], v170 offset:3072
	ds_read_b128 v[186:189], v162
	ds_read_b128 v[190:193], v162 offset:1024
	ds_read_b128 v[194:197], v161
	ds_read_b128 v[198:201], v161 offset:1024
	ds_read_b128 v[202:205], v160
	ds_read_b128 v[208:211], v160 offset:1024
	ds_read_b128 v[214:217], v159
	ds_read_b128 v[218:221], v159 offset:1024
	v_add_u32_e32 v171, 0xc000, v157
	v_lshl_add_u64 v[238:239], s[92:93], 0, v[148:149]
	v_readfirstlane_b32 s54, v171
	v_lshl_add_u64 v[172:173], v[238:239], 0, s[86:87]
	s_mov_b32 m0, s54
	s_nop 0
	global_load_lds_dwordx4 v[172:173], off
	v_add_u32_e32 v172, 0xe000, v157
	v_lshl_add_u64 v[240:241], s[92:93], 0, v[150:151]
	v_readfirstlane_b32 s54, v172
	v_lshl_add_u64 v[222:223], v[240:241], 0, s[86:87]
	s_mov_b32 m0, s54
	s_nop 0
	global_load_lds_dwordx4 v[222:223], off
	s_waitcnt lgkmcnt(8)
	s_barrier
	s_waitcnt lgkmcnt(0)
	v_mfma_f32_16x16x32_bf16 v[124:127], v[136:139], v[186:189], v[124:127]
	v_mfma_f32_16x16x32_bf16 v[120:123], v[178:181], v[186:189], v[120:123]
	v_mfma_f32_16x16x32_bf16 v[116:119], v[136:139], v[194:197], v[116:119]
	v_mfma_f32_16x16x32_bf16 v[112:115], v[178:181], v[194:197], v[112:115]
	v_mfma_f32_16x16x32_bf16 v[108:111], v[136:139], v[202:205], v[108:111]
	v_mfma_f32_16x16x32_bf16 v[104:107], v[178:181], v[202:205], v[104:107]
	v_mfma_f32_16x16x32_bf16 v[100:103], v[136:139], v[214:217], v[100:103]
	v_mfma_f32_16x16x32_bf16 v[96:99], v[178:181], v[214:217], v[96:99]
	v_mfma_f32_16x16x32_bf16 v[124:127], v[174:177], v[190:193], v[124:127]
	v_mfma_f32_16x16x32_bf16 v[120:123], v[182:185], v[190:193], v[120:123]
	v_mfma_f32_16x16x32_bf16 v[116:119], v[174:177], v[198:201], v[116:119]
	v_mfma_f32_16x16x32_bf16 v[112:115], v[182:185], v[198:201], v[112:115]
	v_mfma_f32_16x16x32_bf16 v[108:111], v[174:177], v[208:211], v[108:111]
	v_mfma_f32_16x16x32_bf16 v[104:107], v[182:185], v[208:211], v[104:107]
	v_mfma_f32_16x16x32_bf16 v[100:103], v[174:177], v[218:221], v[100:103]
	v_mfma_f32_16x16x32_bf16 v[96:99], v[182:185], v[218:221], v[96:99]
	s_barrier
	ds_read_b128 v[222:225], v169
	ds_read_b128 v[226:229], v169 offset:1024
	ds_read_b128 v[230:233], v169 offset:2048
	ds_read_b128 v[234:237], v169 offset:3072
	v_lshl_add_u64 v[242:243], s[92:93], 0, v[144:145]
	v_readfirstlane_b32 s54, v156
	v_lshl_add_u64 v[244:245], v[242:243], 0, s[22:23]
	s_mov_b32 m0, s54
	v_add_u32_e32 v134, 0x2000, v156
	global_load_lds_dwordx4 v[244:245], off
	v_lshl_add_u64 v[244:245], s[92:93], 0, v[146:147]
	v_readfirstlane_b32 s54, v134
	v_lshl_add_u64 v[246:247], v[244:245], 0, s[22:23]
	s_mov_b32 m0, s54
	s_nop 0
	global_load_lds_dwordx4 v[246:247], off
	s_barrier
	s_waitcnt lgkmcnt(0)
	v_mfma_f32_16x16x32_bf16 v[92:95], v[222:225], v[186:189], v[92:95]
	v_mfma_f32_16x16x32_bf16 v[88:91], v[230:233], v[186:189], v[88:91]
	v_mfma_f32_16x16x32_bf16 v[84:87], v[222:225], v[194:197], v[84:87]
	v_mfma_f32_16x16x32_bf16 v[80:83], v[230:233], v[194:197], v[80:83]
	v_mfma_f32_16x16x32_bf16 v[76:79], v[222:225], v[202:205], v[76:79]
	v_mfma_f32_16x16x32_bf16 v[72:75], v[230:233], v[202:205], v[72:75]
	v_mfma_f32_16x16x32_bf16 v[68:71], v[222:225], v[214:217], v[68:71]
	v_mfma_f32_16x16x32_bf16 v[64:67], v[230:233], v[214:217], v[64:67]
	v_mfma_f32_16x16x32_bf16 v[92:95], v[226:229], v[190:193], v[92:95]
	v_mfma_f32_16x16x32_bf16 v[88:91], v[234:237], v[190:193], v[88:91]
	v_mfma_f32_16x16x32_bf16 v[84:87], v[226:229], v[198:201], v[84:87]
	v_mfma_f32_16x16x32_bf16 v[80:83], v[234:237], v[198:201], v[80:83]
	v_mfma_f32_16x16x32_bf16 v[76:79], v[226:229], v[208:211], v[76:79]
	v_mfma_f32_16x16x32_bf16 v[72:75], v[234:237], v[208:211], v[72:75]
	v_mfma_f32_16x16x32_bf16 v[68:71], v[226:229], v[218:221], v[68:71]
	v_mfma_f32_16x16x32_bf16 v[64:67], v[234:237], v[218:221], v[64:67]
	v_readfirstlane_b32 s54, v157
	v_add_u32_e32 v134, 0x2000, v157
	v_lshl_add_u64 v[246:247], v[238:239], 0, s[34:35]
	s_mov_b32 m0, s54
	v_readfirstlane_b32 s54, v134
	s_barrier
	ds_read_b128 v[186:189], v162 offset:16384
	ds_read_b128 v[190:193], v162 offset:17408
	ds_read_b128 v[194:197], v161 offset:16384
	ds_read_b128 v[198:201], v161 offset:17408
	ds_read_b128 v[202:205], v160 offset:16384
	ds_read_b128 v[208:211], v160 offset:17408
	ds_read_b128 v[214:217], v159 offset:16384
	ds_read_b128 v[218:221], v159 offset:17408
	global_load_lds_dwordx4 v[246:247], off
	v_lshl_add_u64 v[246:247], v[240:241], 0, s[34:35]
	s_mov_b32 m0, s54
	s_nop 0
	global_load_lds_dwordx4 v[246:247], off
	s_barrier
	s_waitcnt lgkmcnt(0)
	v_mfma_f32_16x16x32_bf16 v[60:63], v[136:139], v[186:189], v[60:63]
	v_mfma_f32_16x16x32_bf16 v[56:59], v[178:181], v[186:189], v[56:59]
	v_mfma_f32_16x16x32_bf16 v[52:55], v[136:139], v[194:197], v[52:55]
	v_mfma_f32_16x16x32_bf16 v[48:51], v[178:181], v[194:197], v[48:51]
	v_mfma_f32_16x16x32_bf16 v[44:47], v[136:139], v[202:205], v[44:47]
	v_mfma_f32_16x16x32_bf16 v[40:43], v[178:181], v[202:205], v[40:43]
	v_mfma_f32_16x16x32_bf16 v[36:39], v[136:139], v[214:217], v[36:39]
	v_mfma_f32_16x16x32_bf16 v[32:35], v[178:181], v[214:217], v[32:35]
	v_mfma_f32_16x16x32_bf16 v[60:63], v[174:177], v[190:193], v[60:63]
	v_mfma_f32_16x16x32_bf16 v[56:59], v[182:185], v[190:193], v[56:59]
	v_mfma_f32_16x16x32_bf16 v[52:55], v[174:177], v[198:201], v[52:55]
	v_mfma_f32_16x16x32_bf16 v[48:51], v[182:185], v[198:201], v[48:51]
	v_mfma_f32_16x16x32_bf16 v[44:47], v[174:177], v[208:211], v[44:47]
	v_mfma_f32_16x16x32_bf16 v[40:43], v[182:185], v[208:211], v[40:43]
	v_mfma_f32_16x16x32_bf16 v[36:39], v[174:177], v[218:221], v[36:39]
	v_mfma_f32_16x16x32_bf16 v[32:35], v[182:185], v[218:221], v[32:35]
	s_barrier
; #define STAGE(P, BASE, br, kt) STAGET(tid_, P, BASE, br, kt)
; #define LDA(dst, b, h) UFOR(m, 4) UFOR(k, 2) \
;     dst[m][k] = *reinterpret_cast<const bf16x8*>((char*)SA(b, h) + lds_byte(wr * 64 + m * 16 + fr, k * 32 + fq * 8))
; #define LDB(dst, b, h) UFOR(n, 2) UFOR(k, 2) \
;     dst[n][k] = *reinterpret_cast<const bf16x8*>((char*)SB(b, h) + lds_byte(wc * 32 + n * 16 + fr, k * 32 + fq * 8))
; #define MMA(ai, bj, At, Bq) do { __builtin_amdgcn_s_setprio(1); \
;     UFOR(m, 4) UFOR(n, 2) UFOR(k, 2) \
;       acc[ai][bj][m][n] = __builtin_amdgcn_mfma_f32_16x16x32_bf16(Bq[n][k], At[m][k], acc[ai][bj][m][n], 0, 0, 0); \
;     __builtin_amdgcn_s_setprio(0); } while (0)
; #define WAIT_V(n) asm volatile("s_waitcnt vmcnt(" #n ")" ::: "memory")
; #define WAIT_L(n) asm volatile("s_waitcnt lgkmcnt(" #n ")" ::: "memory")
; #define BAR __builtin_amdgcn_s_barrier()
; #define SCHED __builtin_amdgcn_sched_barrier(0)
; template <int EPI, int K, int KL> ...
;     ...
;     BAR; WAIT_L(0); MMA(1, 0, At, B0); BAR; SCHED;
;     STAGE(SB(0, 1), Bt, bcol + HALF, t + 2);
;     WAIT_V(6); BAR; MMA(1, 1, At, B1); BAR;
;     LDB(B0, 1, 0); SCHED; LDA(At, 1, 0); STAGE(SA(0, 1), A, brow + HALF, t + 2);
;     WAIT_L(8); BAR; WAIT_L(0); MMA(0, 0, At, B0); BAR; SCHED;
;     LDB(B1, 1, 1); STAGE(SB(1, 0), Bt, bcol, t + 3);
;     BAR; WAIT_L(0); MMA(0, 1, At, B1); BAR;
;     LDA(At, 1, 1); STAGE(SA(1, 0), A, brow, t + 3);
	v_readfirstlane_b32 s54, v158
	v_add_u32_e32 v134, 0x2000, v158
	v_lshl_add_u64 v[136:137], v[242:243], 0, s[24:25]
	s_mov_b32 m0, s54
	v_readfirstlane_b32 s54, v134
	global_load_lds_dwordx4 v[136:137], off
	v_lshl_add_u64 v[136:137], v[244:245], 0, s[24:25]
	s_mov_b32 m0, s54
	s_nop 0
	global_load_lds_dwordx4 v[136:137], off
	s_waitcnt vmcnt(6)
	s_barrier
	v_mfma_f32_16x16x32_bf16 v[28:31], v[222:225], v[186:189], v[28:31]
	v_mfma_f32_16x16x32_bf16 v[24:27], v[230:233], v[186:189], v[24:27]
	v_mfma_f32_16x16x32_bf16 v[20:23], v[222:225], v[194:197], v[20:23]
	v_mfma_f32_16x16x32_bf16 v[16:19], v[230:233], v[194:197], v[16:19]
	v_mfma_f32_16x16x32_bf16 v[12:15], v[222:225], v[202:205], v[12:15]
	v_mfma_f32_16x16x32_bf16 v[8:11], v[230:233], v[202:205], v[8:11]
	v_mfma_f32_16x16x32_bf16 v[4:7], v[222:225], v[214:217], v[4:7]
	v_mfma_f32_16x16x32_bf16 v[0:3], v[230:233], v[214:217], v[0:3]
	v_mfma_f32_16x16x32_bf16 v[28:31], v[226:229], v[190:193], v[28:31]
	v_mfma_f32_16x16x32_bf16 v[24:27], v[234:237], v[190:193], v[24:27]
	v_mfma_f32_16x16x32_bf16 v[20:23], v[226:229], v[198:201], v[20:23]
	v_mfma_f32_16x16x32_bf16 v[16:19], v[234:237], v[198:201], v[16:19]
	v_mfma_f32_16x16x32_bf16 v[12:15], v[226:229], v[208:211], v[12:15]
	v_mfma_f32_16x16x32_bf16 v[8:11], v[234:237], v[208:211], v[8:11]
	v_mfma_f32_16x16x32_bf16 v[4:7], v[226:229], v[218:221], v[4:7]
	v_mfma_f32_16x16x32_bf16 v[0:3], v[234:237], v[218:221], v[0:3]
	s_barrier
	ds_read_b128 v[136:139], v165
	ds_read_b128 v[174:177], v165 offset:1024
	ds_read_b128 v[178:181], v165 offset:2048
	ds_read_b128 v[182:185], v165 offset:3072
	ds_read_b128 v[186:189], v162 offset:32768
	ds_read_b128 v[190:193], v162 offset:33792
	ds_read_b128 v[194:197], v161 offset:32768
	ds_read_b128 v[198:201], v161 offset:33792
	ds_read_b128 v[202:205], v160 offset:32768
	ds_read_b128 v[208:211], v160 offset:33792
	ds_read_b128 v[214:217], v159 offset:32768
	ds_read_b128 v[218:221], v159 offset:33792
	v_add_u32_e32 v134, 0x4000, v157
	v_lshl_add_u64 v[222:223], v[238:239], 0, s[28:29]
	v_readfirstlane_b32 s54, v134
	v_add_u32_e32 v134, 0x6000, v157
	s_mov_b32 m0, s54
	v_readfirstlane_b32 s54, v134
	global_load_lds_dwordx4 v[222:223], off
	v_lshl_add_u64 v[222:223], v[240:241], 0, s[28:29]
	s_mov_b32 m0, s54
	s_nop 0
	global_load_lds_dwordx4 v[222:223], off
	s_waitcnt lgkmcnt(8)
	s_barrier
	s_waitcnt lgkmcnt(0)
	v_mfma_f32_16x16x32_bf16 v[124:127], v[136:139], v[186:189], v[124:127]
	v_mfma_f32_16x16x32_bf16 v[120:123], v[178:181], v[186:189], v[120:123]
	v_mfma_f32_16x16x32_bf16 v[116:119], v[136:139], v[194:197], v[116:119]
	v_mfma_f32_16x16x32_bf16 v[112:115], v[178:181], v[194:197], v[112:115]
	v_mfma_f32_16x16x32_bf16 v[108:111], v[136:139], v[202:205], v[108:111]
	v_mfma_f32_16x16x32_bf16 v[104:107], v[178:181], v[202:205], v[104:107]
	v_mfma_f32_16x16x32_bf16 v[100:103], v[136:139], v[214:217], v[100:103]
	v_mfma_f32_16x16x32_bf16 v[96:99], v[178:181], v[214:217], v[96:99]
	v_mfma_f32_16x16x32_bf16 v[124:127], v[174:177], v[190:193], v[124:127]
	v_mfma_f32_16x16x32_bf16 v[120:123], v[182:185], v[190:193], v[120:123]
	v_mfma_f32_16x16x32_bf16 v[116:119], v[174:177], v[198:201], v[116:119]
	v_mfma_f32_16x16x32_bf16 v[112:115], v[182:185], v[198:201], v[112:115]
	v_mfma_f32_16x16x32_bf16 v[108:111], v[174:177], v[208:211], v[108:111]
	v_mfma_f32_16x16x32_bf16 v[104:107], v[182:185], v[208:211], v[104:107]
	v_mfma_f32_16x16x32_bf16 v[100:103], v[174:177], v[218:221], v[100:103]
	v_mfma_f32_16x16x32_bf16 v[96:99], v[182:185], v[218:221], v[96:99]
	s_barrier
	ds_read_b128 v[222:225], v163
	ds_read_b128 v[226:229], v163 offset:1024
	ds_read_b128 v[230:233], v163 offset:2048
	ds_read_b128 v[234:237], v163 offset:3072
	v_readfirstlane_b32 s54, v164
	v_add_u32_e32 v134, 0x2000, v164
	v_lshl_add_u64 v[246:247], v[242:243], 0, s[94:95]
	s_mov_b32 m0, s54
	v_readfirstlane_b32 s54, v134
	global_load_lds_dwordx4 v[246:247], off
	v_lshl_add_u64 v[246:247], v[244:245], 0, s[94:95]
	s_mov_b32 m0, s54
	s_nop 0
	global_load_lds_dwordx4 v[246:247], off
	s_barrier
	s_waitcnt lgkmcnt(0)
	v_mfma_f32_16x16x32_bf16 v[92:95], v[222:225], v[186:189], v[92:95]
	v_mfma_f32_16x16x32_bf16 v[88:91], v[230:233], v[186:189], v[88:91]
	v_mfma_f32_16x16x32_bf16 v[84:87], v[222:225], v[194:197], v[84:87]
	v_mfma_f32_16x16x32_bf16 v[80:83], v[230:233], v[194:197], v[80:83]
	v_mfma_f32_16x16x32_bf16 v[76:79], v[222:225], v[202:205], v[76:79]
	v_mfma_f32_16x16x32_bf16 v[72:75], v[230:233], v[202:205], v[72:75]
	v_mfma_f32_16x16x32_bf16 v[68:71], v[222:225], v[214:217], v[68:71]
	v_mfma_f32_16x16x32_bf16 v[64:67], v[230:233], v[214:217], v[64:67]
	v_mfma_f32_16x16x32_bf16 v[92:95], v[226:229], v[190:193], v[92:95]
	v_mfma_f32_16x16x32_bf16 v[88:91], v[234:237], v[190:193], v[88:91]
	v_mfma_f32_16x16x32_bf16 v[84:87], v[226:229], v[198:201], v[84:87]
	v_mfma_f32_16x16x32_bf16 v[80:83], v[234:237], v[198:201], v[80:83]
	v_mfma_f32_16x16x32_bf16 v[76:79], v[226:229], v[208:211], v[76:79]
	v_mfma_f32_16x16x32_bf16 v[72:75], v[234:237], v[208:211], v[72:75]
	v_mfma_f32_16x16x32_bf16 v[68:71], v[226:229], v[218:221], v[68:71]
	v_mfma_f32_16x16x32_bf16 v[64:67], v[234:237], v[218:221], v[64:67]
	v_readfirstlane_b32 s54, v166
	v_lshl_add_u64 v[238:239], v[238:239], 0, s[4:5]
	s_mov_b32 m0, s54
	v_readfirstlane_b32 s54, v167
	s_barrier
	ds_read_b128 v[186:189], v162 offset:49152
	ds_read_b128 v[190:193], v162 offset:50176
	ds_read_b128 v[194:197], v161 offset:49152
	ds_read_b128 v[198:201], v161 offset:50176
	ds_read_b128 v[202:205], v160 offset:49152
	ds_read_b128 v[208:211], v160 offset:50176
	ds_read_b128 v[214:217], v159 offset:49152
	ds_read_b128 v[218:221], v159 offset:50176
	global_load_lds_dwordx4 v[238:239], off
	v_lshl_add_u64 v[238:239], v[240:241], 0, s[4:5]
	s_mov_b32 m0, s54
	s_nop 0
	global_load_lds_dwordx4 v[238:239], off
	s_barrier
; #define STAGE(P, BASE, br, kt) STAGET(tid_, P, BASE, br, kt)
; #define LDA(dst, b, h) UFOR(m, 4) UFOR(k, 2) \
;     dst[m][k] = *reinterpret_cast<const bf16x8*>((char*)SA(b, h) + lds_byte(wr * 64 + m * 16 + fr, k * 32 + fq * 8))
; #define LDB(dst, b, h) UFOR(n, 2) UFOR(k, 2) \
;     dst[n][k] = *reinterpret_cast<const bf16x8*>((char*)SB(b, h) + lds_byte(wc * 32 + n * 16 + fr, k * 32 + fq * 8))
; #define MMA(ai, bj, At, Bq) do { __builtin_amdgcn_s_setprio(1); \
;     UFOR(m, 4) UFOR(n, 2) UFOR(k, 2) \
;       acc[ai][bj][m][n] = __builtin_amdgcn_mfma_f32_16x16x32_bf16(Bq[n][k], At[m][k], acc[ai][bj][m][n], 0, 0, 0); \
;     __builtin_amdgcn_s_setprio(0); } while (0)
; #define WAIT_V(n) asm volatile("s_waitcnt vmcnt(" #n ")" ::: "memory")
; #define WAIT_L(n) asm volatile("s_waitcnt lgkmcnt(" #n ")" ::: "memory")
; #define BAR __builtin_amdgcn_s_barrier()
; #define SCHED __builtin_amdgcn_sched_barrier(0)
; template <int EPI, int K, int KL> ...
;     ...
;     LDA(At, 1, 1); STAGE(SA(1, 0), A, brow, t + 3);
;     BAR; WAIT_L(0); MMA(1, 0, At, B0); BAR; SCHED;
;     STAGE(SB(1, 1), Bt, bcol + HALF, t + 3);
;     WAIT_V(6); BAR; MMA(1, 1, At, B1); BAR;
;   }
;   { LDB(B0, 0, 0); LDA(At, 0, 0); STAGE(SA(1, 1), A, brow + HALF, nt - 1);
;     BAR; WAIT_L(0); MMA(0, 0, At, B0); BAR;
	s_waitcnt lgkmcnt(0)
	v_mfma_f32_16x16x32_bf16 v[60:63], v[136:139], v[186:189], v[60:63]
	v_mfma_f32_16x16x32_bf16 v[56:59], v[178:181], v[186:189], v[56:59]
	v_mfma_f32_16x16x32_bf16 v[52:55], v[136:139], v[194:197], v[52:55]
	v_mfma_f32_16x16x32_bf16 v[48:51], v[178:181], v[194:197], v[48:51]
	v_mfma_f32_16x16x32_bf16 v[44:47], v[136:139], v[202:205], v[44:47]
	v_mfma_f32_16x16x32_bf16 v[40:43], v[178:181], v[202:205], v[40:43]
	v_mfma_f32_16x16x32_bf16 v[36:39], v[136:139], v[214:217], v[36:39]
	v_mfma_f32_16x16x32_bf16 v[32:35], v[178:181], v[214:217], v[32:35]
	v_mfma_f32_16x16x32_bf16 v[60:63], v[174:177], v[190:193], v[60:63]
	v_mfma_f32_16x16x32_bf16 v[56:59], v[182:185], v[190:193], v[56:59]
	v_mfma_f32_16x16x32_bf16 v[52:55], v[174:177], v[198:201], v[52:55]
	v_mfma_f32_16x16x32_bf16 v[48:51], v[182:185], v[198:201], v[48:51]
	v_mfma_f32_16x16x32_bf16 v[44:47], v[174:177], v[208:211], v[44:47]
	v_mfma_f32_16x16x32_bf16 v[40:43], v[182:185], v[208:211], v[40:43]
	v_mfma_f32_16x16x32_bf16 v[36:39], v[174:177], v[218:221], v[36:39]
	v_mfma_f32_16x16x32_bf16 v[32:35], v[182:185], v[218:221], v[32:35]
	s_barrier
	v_readfirstlane_b32 s54, v168
	v_add_u32_e32 v134, 0x2000, v168
	v_lshl_add_u64 v[136:137], v[242:243], 0, s[10:11]
	s_mov_b32 m0, s54
	v_readfirstlane_b32 s54, v134
	global_load_lds_dwordx4 v[136:137], off
	v_lshl_add_u64 v[136:137], v[244:245], 0, s[10:11]
	s_mov_b32 m0, s54
	s_nop 0
	global_load_lds_dwordx4 v[136:137], off
	s_waitcnt vmcnt(6)
	s_barrier
	v_mfma_f32_16x16x32_bf16 v[28:31], v[222:225], v[186:189], v[28:31]
	v_mfma_f32_16x16x32_bf16 v[24:27], v[230:233], v[186:189], v[24:27]
	v_mfma_f32_16x16x32_bf16 v[20:23], v[222:225], v[194:197], v[20:23]
	v_mfma_f32_16x16x32_bf16 v[16:19], v[230:233], v[194:197], v[16:19]
	v_mfma_f32_16x16x32_bf16 v[12:15], v[222:225], v[202:205], v[12:15]
	v_mfma_f32_16x16x32_bf16 v[8:11], v[230:233], v[202:205], v[8:11]
	v_mfma_f32_16x16x32_bf16 v[4:7], v[222:225], v[214:217], v[4:7]
	v_mfma_f32_16x16x32_bf16 v[0:3], v[230:233], v[214:217], v[0:3]
	v_mfma_f32_16x16x32_bf16 v[28:31], v[226:229], v[190:193], v[28:31]
	v_mfma_f32_16x16x32_bf16 v[24:27], v[234:237], v[190:193], v[24:27]
	v_mfma_f32_16x16x32_bf16 v[20:23], v[226:229], v[198:201], v[20:23]
	v_mfma_f32_16x16x32_bf16 v[16:19], v[234:237], v[198:201], v[16:19]
	v_mfma_f32_16x16x32_bf16 v[12:15], v[226:229], v[208:211], v[12:15]
	v_mfma_f32_16x16x32_bf16 v[8:11], v[234:237], v[208:211], v[8:11]
	v_mfma_f32_16x16x32_bf16 v[4:7], v[226:229], v[218:221], v[4:7]
	v_mfma_f32_16x16x32_bf16 v[0:3], v[234:237], v[218:221], v[0:3]
	s_add_i32 s19, s19, 2
	v_lshl_add_u64 v[144:145], v[144:145], 0, s[20:21]
	v_lshl_add_u64 v[146:147], v[146:147], 0, s[20:21]
	v_lshl_add_u64 v[148:149], v[148:149], 0, s[20:21]
	s_cmpk_lt_u32 s19, 0x54
	v_lshl_add_u64 v[150:151], v[150:151], 0, s[20:21]
	s_cbranch_scc1 .Lkrot_1184
	s_barrier
	s_add_u32 s52, s52, 0x162b80
	s_addc_u32 s53, s53, 0
	v_lshl_add_u64 v[130:131], s[52:53], 0, v[130:131]
	v_readfirstlane_b32 s19, v171
	v_lshl_add_u64 v[128:129], v[128:129], 1, v[130:131]
	s_mov_b32 m0, s19
	ds_read_b128 v[136:139], v170
	ds_read_b128 v[144:147], v170 offset:1024
	ds_read_b128 v[148:151], v170 offset:2048
	ds_read_b128 v[174:177], v170 offset:3072
	ds_read_b128 v[178:181], v162
	ds_read_b128 v[182:185], v162 offset:1024
	ds_read_b128 v[186:189], v161
	ds_read_b128 v[190:193], v161 offset:1024
	ds_read_b128 v[194:197], v160
	ds_read_b128 v[198:201], v160 offset:1024
	ds_read_b128 v[202:205], v159
	ds_read_b128 v[208:211], v159 offset:1024
	global_load_lds_dwordx4 v[128:129], off
	v_lshl_add_u64 v[128:129], s[52:53], 0, v[142:143]
	v_readfirstlane_b32 s19, v172
	v_lshl_add_u64 v[128:129], v[140:141], 1, v[128:129]
	s_mov_b32 m0, s19
	s_nop 0
	global_load_lds_dwordx4 v[128:129], off
	s_barrier
	s_waitcnt lgkmcnt(0)
	s_waitcnt lgkmcnt(0)
	v_mfma_f32_16x16x32_bf16 v[120:123], v[148:151], v[178:181], v[120:123]
	v_mfma_f32_16x16x32_bf16 v[116:119], v[136:139], v[186:189], v[116:119]
	v_mfma_f32_16x16x32_bf16 v[112:115], v[148:151], v[186:189], v[112:115]
	v_mfma_f32_16x16x32_bf16 v[108:111], v[136:139], v[194:197], v[108:111]
	v_mfma_f32_16x16x32_bf16 v[104:107], v[148:151], v[194:197], v[104:107]
	v_mfma_f32_16x16x32_bf16 v[100:103], v[136:139], v[202:205], v[100:103]
	v_mfma_f32_16x16x32_bf16 v[96:99], v[148:151], v[202:205], v[96:99]
	v_mfma_f32_16x16x32_bf16 v[124:127], v[136:139], v[178:181], v[124:127]
	v_mfma_f32_16x16x32_bf16 v[120:123], v[174:177], v[182:185], v[120:123]
	v_mfma_f32_16x16x32_bf16 v[116:119], v[144:147], v[190:193], v[116:119]
	v_mfma_f32_16x16x32_bf16 v[112:115], v[174:177], v[190:193], v[112:115]
	v_mfma_f32_16x16x32_bf16 v[108:111], v[144:147], v[198:201], v[108:111]
	v_mfma_f32_16x16x32_bf16 v[104:107], v[174:177], v[198:201], v[104:107]
	v_mfma_f32_16x16x32_bf16 v[100:103], v[144:147], v[208:211], v[100:103]
	v_mfma_f32_16x16x32_bf16 v[96:99], v[174:177], v[208:211], v[96:99]
	v_mfma_f32_16x16x32_bf16 v[124:127], v[144:147], v[182:185], v[124:127]
	s_barrier
	ds_read_b128 v[128:131], v169
	ds_read_b128 v[140:143], v169 offset:1024
	ds_read_b128 v[170:173], v169 offset:2048
	ds_read_b128 v[166:169], v169 offset:3072
	s_barrier
; #define STAGE(P, BASE, br, kt) STAGET(tid_, P, BASE, br, kt)
; #define LDA(dst, b, h) UFOR(m, 4) UFOR(k, 2) \
;     dst[m][k] = *reinterpret_cast<const bf16x8*>((char*)SA(b, h) + lds_byte(wr * 64 + m * 16 + fr, k * 32 + fq * 8))
; #define LDB(dst, b, h) UFOR(n, 2) UFOR(k, 2) \
;     dst[n][k] = *reinterpret_cast<const bf16x8*>((char*)SB(b, h) + lds_byte(wc * 32 + n * 16 + fr, k * 32 + fq * 8))
; #define MMA(ai, bj, At, Bq) do { __builtin_amdgcn_s_setprio(1); \
;     UFOR(m, 4) UFOR(n, 2) UFOR(k, 2) \
;       acc[ai][bj][m][n] = __builtin_amdgcn_mfma_f32_16x16x32_bf16(Bq[n][k], At[m][k], acc[ai][bj][m][n], 0, 0, 0); \
;     __builtin_amdgcn_s_setprio(0); } while (0)
; #define WAIT_V(n) asm volatile("s_waitcnt vmcnt(" #n ")" ::: "memory")
; #define WAIT_L(n) asm volatile("s_waitcnt lgkmcnt(" #n ")" ::: "memory")
; #define BAR __builtin_amdgcn_s_barrier()
; template <int EPI, int K, int KL> ...
;     ...
;   { LDB(B0, 0, 0); LDA(At, 0, 0); STAGE(SA(1, 1), A, brow + HALF, nt - 1);
;     BAR; WAIT_L(0); MMA(0, 0, At, B0); BAR;
;     LDB(B1, 0, 1); BAR; WAIT_L(0); MMA(0, 1, At, B1); BAR;
;     LDA(At, 0, 1); WAIT_V(4); BAR; WAIT_L(0); MMA(1, 0, At, B0); MMA(1, 1, At, B1); BAR; }
;   { LDB(B0, 1, 0); LDA(At, 1, 0); WAIT_V(2); BAR; WAIT_L(0); MMA(0, 0, At, B0); BAR;
	s_waitcnt lgkmcnt(0)
	s_waitcnt lgkmcnt(0)
	v_mfma_f32_16x16x32_bf16 v[80:83], v[170:173], v[186:189], v[80:83]
	v_mfma_f32_16x16x32_bf16 v[76:79], v[128:131], v[194:197], v[76:79]
	v_mfma_f32_16x16x32_bf16 v[68:71], v[128:131], v[202:205], v[68:71]
	v_mfma_f32_16x16x32_bf16 v[64:67], v[170:173], v[202:205], v[64:67]
	v_mfma_f32_16x16x32_bf16 v[92:95], v[128:131], v[178:181], v[92:95]
	v_mfma_f32_16x16x32_bf16 v[88:91], v[170:173], v[178:181], v[88:91]
	v_mfma_f32_16x16x32_bf16 v[84:87], v[128:131], v[186:189], v[84:87]
	v_mfma_f32_16x16x32_bf16 v[80:83], v[166:169], v[190:193], v[80:83]
	v_mfma_f32_16x16x32_bf16 v[76:79], v[140:143], v[198:201], v[76:79]
	v_mfma_f32_16x16x32_bf16 v[72:75], v[170:173], v[194:197], v[72:75]
	v_mfma_f32_16x16x32_bf16 v[68:71], v[140:143], v[208:211], v[68:71]
	v_mfma_f32_16x16x32_bf16 v[64:67], v[166:169], v[208:211], v[64:67]
	v_mfma_f32_16x16x32_bf16 v[214:217], v[140:143], v[182:185], v[92:95]
	v_mfma_f32_16x16x32_bf16 v[178:181], v[166:169], v[182:185], v[88:91]
	v_mfma_f32_16x16x32_bf16 v[182:185], v[140:143], v[190:193], v[84:87]
	v_mfma_f32_16x16x32_bf16 v[186:189], v[166:169], v[198:201], v[72:75]
	s_barrier
	s_nop 0
	ds_read_b128 v[72:75], v162 offset:16384
	ds_read_b128 v[84:87], v162 offset:17408
	ds_read_b128 v[88:91], v161 offset:16384
	ds_read_b128 v[92:95], v161 offset:17408
	ds_read_b128 v[190:193], v160 offset:16384
	ds_read_b128 v[194:197], v160 offset:17408
	ds_read_b128 v[198:201], v159 offset:16384
	ds_read_b128 v[202:205], v159 offset:17408
	s_waitcnt vmcnt(4)
	s_barrier
	s_waitcnt lgkmcnt(0)
	s_waitcnt lgkmcnt(0)
	v_mfma_f32_16x16x32_bf16 v[48:51], v[148:151], v[88:91], v[48:51]
	v_mfma_f32_16x16x32_bf16 v[40:43], v[148:151], v[190:193], v[40:43]
	v_mfma_f32_16x16x32_bf16 v[36:39], v[136:139], v[198:201], v[36:39]
	v_mfma_f32_16x16x32_bf16 v[32:35], v[148:151], v[198:201], v[32:35]
	v_mfma_f32_16x16x32_bf16 v[60:63], v[136:139], v[72:75], v[60:63]
	v_mfma_f32_16x16x32_bf16 v[56:59], v[148:151], v[72:75], v[56:59]
	v_mfma_f32_16x16x32_bf16 v[52:55], v[136:139], v[88:91], v[52:55]
	v_mfma_f32_16x16x32_bf16 v[48:51], v[174:177], v[92:95], v[48:51]
	v_mfma_f32_16x16x32_bf16 v[44:47], v[136:139], v[190:193], v[44:47]
	v_mfma_f32_16x16x32_bf16 v[40:43], v[174:177], v[194:197], v[40:43]
	v_mfma_f32_16x16x32_bf16 v[36:39], v[144:147], v[202:205], v[36:39]
	v_mfma_f32_16x16x32_bf16 v[32:35], v[174:177], v[202:205], v[32:35]
	v_mfma_f32_16x16x32_bf16 v[208:211], v[144:147], v[84:87], v[60:63]
	v_mfma_f32_16x16x32_bf16 v[218:221], v[174:177], v[84:87], v[56:59]
	v_mfma_f32_16x16x32_bf16 v[222:225], v[144:147], v[92:95], v[52:55]
	v_mfma_f32_16x16x32_bf16 v[226:229], v[144:147], v[194:197], v[44:47]
	v_mfma_f32_16x16x32_bf16 v[0:3], v[170:173], v[198:201], v[0:3]
	v_mfma_f32_16x16x32_bf16 v[28:31], v[128:131], v[72:75], v[28:31]
	v_mfma_f32_16x16x32_bf16 v[24:27], v[170:173], v[72:75], v[24:27]
	v_mfma_f32_16x16x32_bf16 v[20:23], v[128:131], v[88:91], v[20:23]
	v_mfma_f32_16x16x32_bf16 v[16:19], v[170:173], v[88:91], v[16:19]
	v_mfma_f32_16x16x32_bf16 v[12:15], v[128:131], v[190:193], v[12:15]
	v_mfma_f32_16x16x32_bf16 v[8:11], v[170:173], v[190:193], v[8:11]
	v_mfma_f32_16x16x32_bf16 v[4:7], v[128:131], v[198:201], v[4:7]
	v_mfma_f32_16x16x32_bf16 v[0:3], v[166:169], v[202:205], v[0:3]
	v_mfma_f32_16x16x32_bf16 v[136:139], v[140:143], v[84:87], v[28:31]
	v_mfma_f32_16x16x32_bf16 v[144:147], v[166:169], v[84:87], v[24:27]
	v_mfma_f32_16x16x32_bf16 v[148:151], v[140:143], v[92:95], v[20:23]
	v_mfma_f32_16x16x32_bf16 v[174:177], v[166:169], v[92:95], v[16:19]
	v_mfma_f32_16x16x32_bf16 v[230:233], v[140:143], v[194:197], v[12:15]
	v_mfma_f32_16x16x32_bf16 v[190:193], v[166:169], v[194:197], v[8:11]
	v_mfma_f32_16x16x32_bf16 v[140:143], v[140:143], v[202:205], v[4:7]
	s_barrier
	s_nop 0
	ds_read_b128 v[4:7], v165
	ds_read_b128 v[8:11], v165 offset:1024
	ds_read_b128 v[16:19], v165 offset:2048
	ds_read_b128 v[164:167], v165 offset:3072
	ds_read_b128 v[12:15], v162 offset:32768
	ds_read_b128 v[20:23], v162 offset:33792
	ds_read_b128 v[24:27], v161 offset:32768
	ds_read_b128 v[44:47], v161 offset:33792
	ds_read_b128 v[168:171], v160 offset:32768
	ds_read_b128 v[194:197], v160 offset:33792
	ds_read_b128 v[198:201], v159 offset:32768
	ds_read_b128 v[202:205], v159 offset:33792
	s_waitcnt vmcnt(2)
	s_barrier
; #define LDA(dst, b, h) UFOR(m, 4) UFOR(k, 2) \
;     dst[m][k] = *reinterpret_cast<const bf16x8*>((char*)SA(b, h) + lds_byte(wr * 64 + m * 16 + fr, k * 32 + fq * 8))
; #define LDB(dst, b, h) UFOR(n, 2) UFOR(k, 2) \
;     dst[n][k] = *reinterpret_cast<const bf16x8*>((char*)SB(b, h) + lds_byte(wc * 32 + n * 16 + fr, k * 32 + fq * 8))
; #define MMA(ai, bj, At, Bq) do { __builtin_amdgcn_s_setprio(1); \
;     UFOR(m, 4) UFOR(n, 2) UFOR(k, 2) \
;       acc[ai][bj][m][n] = __builtin_amdgcn_mfma_f32_16x16x32_bf16(Bq[n][k], At[m][k], acc[ai][bj][m][n], 0, 0, 0); \
;     __builtin_amdgcn_s_setprio(0); } while (0)
; #define WAIT_V(n) asm volatile("s_waitcnt vmcnt(" #n ")" ::: "memory")
; #define WAIT_L(n) asm volatile("s_waitcnt lgkmcnt(" #n ")" ::: "memory")
; #define BAR __builtin_amdgcn_s_barrier()
; template <int EPI, int K, int KL> ...
;     ...
;   { LDB(B0, 1, 0); LDA(At, 1, 0); WAIT_V(2); BAR; WAIT_L(0); MMA(0, 0, At, B0); BAR;
;     LDB(B1, 1, 1); WAIT_V(0); BAR; WAIT_L(0); MMA(0, 1, At, B1); BAR;
;     LDA(At, 1, 1); BAR; WAIT_L(0); MMA(1, 0, At, B0); MMA(1, 1, At, B1); BAR; }
;   if (wr == 0) BAR;
	s_waitcnt lgkmcnt(0)
	s_waitcnt lgkmcnt(0)
	v_mfma_f32_16x16x32_bf16 v[28:31], v[4:7], v[12:15], v[124:127]
	v_mfma_f32_16x16x32_bf16 v[128:131], v[8:11], v[20:23], v[28:31]
	v_mfma_f32_16x16x32_bf16 v[28:31], v[16:19], v[12:15], v[120:123]
	v_mfma_f32_16x16x32_bf16 v[92:95], v[164:167], v[20:23], v[28:31]
	v_mfma_f32_16x16x32_bf16 v[28:31], v[4:7], v[24:27], v[116:119]
	v_mfma_f32_16x16x32_bf16 v[120:123], v[8:11], v[44:47], v[28:31]
	v_mfma_f32_16x16x32_bf16 v[28:31], v[16:19], v[24:27], v[112:115]
	v_mfma_f32_16x16x32_bf16 v[88:91], v[164:167], v[44:47], v[28:31]
	v_mfma_f32_16x16x32_bf16 v[28:31], v[4:7], v[168:171], v[108:111]
	v_mfma_f32_16x16x32_bf16 v[116:119], v[8:11], v[194:197], v[28:31]
	v_mfma_f32_16x16x32_bf16 v[28:31], v[16:19], v[168:171], v[104:107]
	v_mfma_f32_16x16x32_bf16 v[84:87], v[164:167], v[194:197], v[28:31]
	v_mfma_f32_16x16x32_bf16 v[28:31], v[4:7], v[198:201], v[100:103]
	v_mfma_f32_16x16x32_bf16 v[108:111], v[8:11], v[202:205], v[28:31]
	v_mfma_f32_16x16x32_bf16 v[28:31], v[16:19], v[198:201], v[96:99]
	v_mfma_f32_16x16x32_bf16 v[72:75], v[164:167], v[202:205], v[28:31]
	s_barrier
	ds_read_b128 v[124:127], v163
	ds_read_b128 v[234:237], v163 offset:1024
	ds_read_b128 v[238:241], v163 offset:2048
	ds_read_b128 v[242:245], v163 offset:3072
	s_waitcnt vmcnt(0)
	s_barrier
	s_waitcnt lgkmcnt(0)
	s_waitcnt lgkmcnt(0)
	v_mfma_f32_16x16x32_bf16 v[28:31], v[124:127], v[12:15], v[214:217]
	v_mfma_f32_16x16x32_bf16 v[12:15], v[238:241], v[12:15], v[178:181]
	v_mfma_f32_16x16x32_bf16 v[60:63], v[234:237], v[20:23], v[28:31]
	v_mfma_f32_16x16x32_bf16 v[28:31], v[242:245], v[20:23], v[12:15]
	v_mfma_f32_16x16x32_bf16 v[12:15], v[124:127], v[24:27], v[182:185]
	v_mfma_f32_16x16x32_bf16 v[56:59], v[234:237], v[44:47], v[12:15]
	v_mfma_f32_16x16x32_bf16 v[12:15], v[238:241], v[24:27], v[80:83]
	v_mfma_f32_16x16x32_bf16 v[24:27], v[242:245], v[44:47], v[12:15]
	v_mfma_f32_16x16x32_bf16 v[12:15], v[124:127], v[168:171], v[76:79]
	v_mfma_f32_16x16x32_bf16 v[52:55], v[234:237], v[194:197], v[12:15]
	v_mfma_f32_16x16x32_bf16 v[12:15], v[238:241], v[168:171], v[186:189]
	v_mfma_f32_16x16x32_bf16 v[20:23], v[242:245], v[194:197], v[12:15]
	v_mfma_f32_16x16x32_bf16 v[12:15], v[124:127], v[198:201], v[68:71]
	v_mfma_f32_16x16x32_bf16 v[44:47], v[234:237], v[202:205], v[12:15]
	v_mfma_f32_16x16x32_bf16 v[12:15], v[238:241], v[198:201], v[64:67]
	v_mfma_f32_16x16x32_bf16 v[12:15], v[242:245], v[202:205], v[12:15]
	s_barrier
	ds_read_b128 v[168:171], v162 offset:49152
	ds_read_b128 v[178:181], v162 offset:50176
	ds_read_b128 v[182:185], v161 offset:49152
	ds_read_b128 v[186:189], v161 offset:50176
	ds_read_b128 v[194:197], v160 offset:49152
	ds_read_b128 v[160:163], v160 offset:50176
	ds_read_b128 v[198:201], v159 offset:49152
	ds_read_b128 v[156:159], v159 offset:50176
	s_barrier
	s_waitcnt lgkmcnt(0)
	s_waitcnt lgkmcnt(0)
	v_mfma_f32_16x16x32_bf16 v[64:67], v[4:7], v[168:171], v[208:211]
	v_mfma_f32_16x16x32_bf16 v[112:115], v[8:11], v[178:181], v[64:67]
	v_mfma_f32_16x16x32_bf16 v[64:67], v[16:19], v[168:171], v[218:221]
	v_mfma_f32_16x16x32_bf16 v[48:51], v[16:19], v[182:185], v[48:51]
	v_mfma_f32_16x16x32_bf16 v[80:83], v[164:167], v[178:181], v[64:67]
	v_mfma_f32_16x16x32_bf16 v[64:67], v[4:7], v[182:185], v[222:225]
	v_mfma_f32_16x16x32_bf16 v[76:79], v[164:167], v[186:189], v[48:51]
	v_mfma_f32_16x16x32_bf16 v[48:51], v[4:7], v[194:197], v[226:229]
	v_mfma_f32_16x16x32_bf16 v[4:7], v[4:7], v[198:201], v[36:39]
	v_mfma_f32_16x16x32_bf16 v[40:43], v[16:19], v[194:197], v[40:43]
	v_mfma_f32_16x16x32_bf16 v[96:99], v[8:11], v[156:159], v[4:7]
	v_mfma_f32_16x16x32_bf16 v[4:7], v[16:19], v[198:201], v[32:35]
	v_mfma_f32_16x16x32_bf16 v[104:107], v[8:11], v[186:189], v[64:67]
	v_mfma_f32_16x16x32_bf16 v[100:103], v[8:11], v[160:163], v[48:51]
	v_mfma_f32_16x16x32_bf16 v[68:71], v[164:167], v[160:163], v[40:43]
	v_mfma_f32_16x16x32_bf16 v[64:67], v[164:167], v[156:159], v[4:7]
	v_mfma_f32_16x16x32_bf16 v[4:7], v[124:127], v[168:171], v[136:139]
	v_mfma_f32_16x16x32_bf16 v[48:51], v[234:237], v[178:181], v[4:7]
	v_mfma_f32_16x16x32_bf16 v[4:7], v[238:241], v[168:171], v[144:147]
	v_mfma_f32_16x16x32_bf16 v[16:19], v[242:245], v[178:181], v[4:7]
	v_mfma_f32_16x16x32_bf16 v[4:7], v[124:127], v[182:185], v[148:151]
	v_mfma_f32_16x16x32_bf16 v[40:43], v[234:237], v[186:189], v[4:7]
	v_mfma_f32_16x16x32_bf16 v[4:7], v[238:241], v[182:185], v[174:177]
	v_mfma_f32_16x16x32_bf16 v[8:11], v[242:245], v[186:189], v[4:7]
	v_mfma_f32_16x16x32_bf16 v[4:7], v[124:127], v[194:197], v[230:233]
	v_mfma_f32_16x16x32_bf16 v[36:39], v[234:237], v[160:163], v[4:7]
	v_mfma_f32_16x16x32_bf16 v[4:7], v[238:241], v[194:197], v[190:193]
	v_mfma_f32_16x16x32_bf16 v[32:35], v[124:127], v[198:201], v[140:143]
	v_mfma_f32_16x16x32_bf16 v[0:3], v[238:241], v[198:201], v[0:3]
	v_mfma_f32_16x16x32_bf16 v[4:7], v[242:245], v[160:163], v[4:7]
	v_mfma_f32_16x16x32_bf16 v[32:35], v[234:237], v[156:159], v[32:35]
	v_mfma_f32_16x16x32_bf16 v[0:3], v[242:245], v[156:159], v[0:3]
	s_movk_i32 s19, 0x100
	v_cmp_gt_u32_e32 vcc, s19, v154
	s_barrier
	s_and_saveexec_b64 s[52:53], vcc
	s_cbranch_execnz .LBB0_1189
	s_or_b64 exec, exec, s[52:53]
	s_andn2_b64 vcc, exec, s[50:51]
	s_cbranch_vccz .LBB0_1190

; #define STAGE(P, BASE, br, kt) STAGET(tid_, P, BASE, br, kt)
; #define LDA(dst, b, h) UFOR(m, 4) UFOR(k, 2) \
;     dst[m][k] = *reinterpret_cast<const bf16x8*>((char*)SA(b, h) + lds_byte(wr * 64 + m * 16 + fr, k * 32 + fq * 8))
; #define LDB(dst, b, h) UFOR(n, 2) UFOR(k, 2) \
;     dst[n][k] = *reinterpret_cast<const bf16x8*>((char*)SB(b, h) + lds_byte(wc * 32 + n * 16 + fr, k * 32 + fq * 8))
; #define MMA(ai, bj, At, Bq) do { __builtin_amdgcn_s_setprio(1); \
;     UFOR(m, 4) UFOR(n, 2) UFOR(k, 2) \
;       acc[ai][bj][m][n] = __builtin_amdgcn_mfma_f32_16x16x32_bf16(Bq[n][k], At[m][k], acc[ai][bj][m][n], 0, 0, 0); \
;     __builtin_amdgcn_s_setprio(0); } while (0)
; #define WAIT_L(n) asm volatile("s_waitcnt lgkmcnt(" #n ")" ::: "memory")
; #define BAR __builtin_amdgcn_s_barrier()
; #define SCHED __builtin_amdgcn_sched_barrier(0)
; template <int EPI, int K, int KL> ...
;     ...
;   for (int t = 0; t < nt - 2; t += 2) {
;     LDB(B0, 0, 0); SCHED; LDA(At, 0, 0); STAGE(SA(1, 1), A, brow + HALF, t + 1);
;     WAIT_L(8); BAR; WAIT_L(0); MMA(0, 0, At, B0); BAR; SCHED;
;     LDB(B1, 0, 1); STAGE(SB(0, 0), Bt, bcol, t + 2);
;     BAR; WAIT_L(0); MMA(0, 1, At, B1); BAR;
;     LDA(At, 0, 1); STAGE(SA(0, 0), A, brow, t + 2);
;     BAR; WAIT_L(0); MMA(1, 0, At, B0); BAR; SCHED;
; __device__ __forceinline__ void gemm_ctx_splitk_down(const u16* A, const u16* Bt, float* P2, const EpiArgs& e0) {
;     ...
;   for (int u = bid_; u < 16 * P2_PARTS; u += gridDim.x) {
;     const int tile = u / P2_PARTS, part = u % P2_PARTS, pm = 128 + (tile >> 3), pn = tile & 7;
;     EpiArgs e = e0; e.part = P2 + (size_t)part * 512 * DM;
;     const long koff = (long)part * (DFF / P2_PARTS);
;     gemm_tile<EPI_PART, DFF, DFF / P2_PARTS>(A + koff, Bt + koff, (long)pm * BM, pn * BM, pn, 0, 0, e, true, false, 0, 0);
.LBB0_1204:
	ds_read_b128 v[136:139], v175
	ds_read_b128 v[178:181], v175 offset:1024
	ds_read_b128 v[182:185], v175 offset:2048
	ds_read_b128 v[186:189], v175 offset:3072
	ds_read_b128 v[190:193], v160
	ds_read_b128 v[194:197], v160 offset:1024
	ds_read_b128 v[198:201], v159
	ds_read_b128 v[202:205], v159 offset:1024
	ds_read_b128 v[208:211], v158
	ds_read_b128 v[214:217], v158 offset:1024
	ds_read_b128 v[218:221], v157
	ds_read_b128 v[222:225], v157 offset:1024
	v_add_u32_e32 v176, 0xc000, v161
	v_lshl_add_u64 v[152:153], v[148:149], 0, s[44:45]
	v_readfirstlane_b32 s15, v176
	v_lshl_add_u64 v[154:155], v[152:153], 0, s[58:59]
	s_mov_b32 m0, s15
	v_add_u32_e32 v177, 0xe000, v161
	global_load_lds_dwordx4 v[154:155], off
	v_lshl_add_u64 v[154:155], v[150:151], 0, s[44:45]
	v_readfirstlane_b32 s15, v177
	v_lshl_add_u64 v[226:227], v[154:155], 0, s[58:59]
	s_mov_b32 m0, s15
	s_nop 0
	global_load_lds_dwordx4 v[226:227], off
	s_waitcnt lgkmcnt(8)
	s_barrier
	s_waitcnt lgkmcnt(0)
	v_mfma_f32_16x16x32_bf16 v[124:127], v[136:139], v[190:193], v[124:127]
	v_mfma_f32_16x16x32_bf16 v[120:123], v[182:185], v[190:193], v[120:123]
	v_mfma_f32_16x16x32_bf16 v[116:119], v[136:139], v[198:201], v[116:119]
	v_mfma_f32_16x16x32_bf16 v[112:115], v[182:185], v[198:201], v[112:115]
	v_mfma_f32_16x16x32_bf16 v[108:111], v[136:139], v[208:211], v[108:111]
	v_mfma_f32_16x16x32_bf16 v[104:107], v[182:185], v[208:211], v[104:107]
	v_mfma_f32_16x16x32_bf16 v[100:103], v[136:139], v[218:221], v[100:103]
	v_mfma_f32_16x16x32_bf16 v[96:99], v[182:185], v[218:221], v[96:99]
	v_mfma_f32_16x16x32_bf16 v[124:127], v[178:181], v[194:197], v[124:127]
	v_mfma_f32_16x16x32_bf16 v[120:123], v[186:189], v[194:197], v[120:123]
	v_mfma_f32_16x16x32_bf16 v[116:119], v[178:181], v[202:205], v[116:119]
	v_mfma_f32_16x16x32_bf16 v[112:115], v[186:189], v[202:205], v[112:115]
	v_mfma_f32_16x16x32_bf16 v[108:111], v[178:181], v[214:217], v[108:111]
	v_mfma_f32_16x16x32_bf16 v[104:107], v[186:189], v[214:217], v[104:107]
	v_mfma_f32_16x16x32_bf16 v[100:103], v[178:181], v[222:225], v[100:103]
	v_mfma_f32_16x16x32_bf16 v[96:99], v[186:189], v[222:225], v[96:99]
	s_barrier
	ds_read_b128 v[226:229], v173
	ds_read_b128 v[230:233], v173 offset:1024
	ds_read_b128 v[234:237], v173 offset:2048
	ds_read_b128 v[238:241], v173 offset:3072
	v_lshl_add_u64 v[242:243], v[144:145], 0, s[44:45]
	v_readfirstlane_b32 s15, v156
	v_lshl_add_u64 v[244:245], v[242:243], 0, s[22:23]
	s_mov_b32 m0, s15
	v_add_u32_e32 v248, 0x2000, v156
	global_load_lds_dwordx4 v[244:245], off
	v_lshl_add_u64 v[244:245], v[146:147], 0, s[44:45]
	v_readfirstlane_b32 s15, v248
	v_lshl_add_u64 v[246:247], v[244:245], 0, s[22:23]
	s_mov_b32 m0, s15
	s_nop 0
	global_load_lds_dwordx4 v[246:247], off
	s_barrier
	s_waitcnt lgkmcnt(0)
	v_mfma_f32_16x16x32_bf16 v[92:95], v[226:229], v[190:193], v[92:95]
	v_mfma_f32_16x16x32_bf16 v[88:91], v[234:237], v[190:193], v[88:91]
	v_mfma_f32_16x16x32_bf16 v[84:87], v[226:229], v[198:201], v[84:87]
	v_mfma_f32_16x16x32_bf16 v[80:83], v[234:237], v[198:201], v[80:83]
	v_mfma_f32_16x16x32_bf16 v[76:79], v[226:229], v[208:211], v[76:79]
	v_mfma_f32_16x16x32_bf16 v[72:75], v[234:237], v[208:211], v[72:75]
	v_mfma_f32_16x16x32_bf16 v[68:71], v[226:229], v[218:221], v[68:71]
	v_mfma_f32_16x16x32_bf16 v[64:67], v[234:237], v[218:221], v[64:67]
	v_mfma_f32_16x16x32_bf16 v[92:95], v[230:233], v[194:197], v[92:95]
	v_mfma_f32_16x16x32_bf16 v[88:91], v[238:241], v[194:197], v[88:91]
	v_mfma_f32_16x16x32_bf16 v[84:87], v[230:233], v[202:205], v[84:87]
	v_mfma_f32_16x16x32_bf16 v[80:83], v[238:241], v[202:205], v[80:83]
	v_mfma_f32_16x16x32_bf16 v[76:79], v[230:233], v[214:217], v[76:79]
	v_mfma_f32_16x16x32_bf16 v[72:75], v[238:241], v[214:217], v[72:75]
	v_mfma_f32_16x16x32_bf16 v[68:71], v[230:233], v[222:225], v[68:71]
	v_mfma_f32_16x16x32_bf16 v[64:67], v[238:241], v[222:225], v[64:67]
	v_readfirstlane_b32 s15, v161
	v_lshl_add_u64 v[246:247], v[152:153], 0, s[60:61]
	s_mov_b32 m0, s15
	v_readfirstlane_b32 s15, v162
	s_barrier
	ds_read_b128 v[190:193], v160 offset:16384
	ds_read_b128 v[194:197], v160 offset:17408
	ds_read_b128 v[198:201], v159 offset:16384
	ds_read_b128 v[202:205], v159 offset:17408
	ds_read_b128 v[208:211], v158 offset:16384
	ds_read_b128 v[214:217], v158 offset:17408
	ds_read_b128 v[218:221], v157 offset:16384
	ds_read_b128 v[222:225], v157 offset:17408
	global_load_lds_dwordx4 v[246:247], off
	v_lshl_add_u64 v[246:247], v[154:155], 0, s[60:61]
	s_mov_b32 m0, s15
	s_nop 0
	global_load_lds_dwordx4 v[246:247], off
	s_barrier
	s_waitcnt lgkmcnt(0)
	v_mfma_f32_16x16x32_bf16 v[60:63], v[136:139], v[190:193], v[60:63]
	v_mfma_f32_16x16x32_bf16 v[56:59], v[182:185], v[190:193], v[56:59]
	v_mfma_f32_16x16x32_bf16 v[52:55], v[136:139], v[198:201], v[52:55]
	v_mfma_f32_16x16x32_bf16 v[48:51], v[182:185], v[198:201], v[48:51]
	v_mfma_f32_16x16x32_bf16 v[44:47], v[136:139], v[208:211], v[44:47]
	v_mfma_f32_16x16x32_bf16 v[40:43], v[182:185], v[208:211], v[40:43]
	v_mfma_f32_16x16x32_bf16 v[36:39], v[136:139], v[218:221], v[36:39]
	v_mfma_f32_16x16x32_bf16 v[32:35], v[182:185], v[218:221], v[32:35]
	v_mfma_f32_16x16x32_bf16 v[60:63], v[178:181], v[194:197], v[60:63]
	v_mfma_f32_16x16x32_bf16 v[56:59], v[186:189], v[194:197], v[56:59]
	v_mfma_f32_16x16x32_bf16 v[52:55], v[178:181], v[202:205], v[52:55]
	v_mfma_f32_16x16x32_bf16 v[48:51], v[186:189], v[202:205], v[48:51]
	v_mfma_f32_16x16x32_bf16 v[44:47], v[178:181], v[214:217], v[44:47]
	v_mfma_f32_16x16x32_bf16 v[40:43], v[186:189], v[214:217], v[40:43]
	v_mfma_f32_16x16x32_bf16 v[36:39], v[178:181], v[222:225], v[36:39]
	v_mfma_f32_16x16x32_bf16 v[32:35], v[186:189], v[222:225], v[32:35]
	s_barrier
; #define STAGE(P, BASE, br, kt) STAGET(tid_, P, BASE, br, kt)
; #define LDA(dst, b, h) UFOR(m, 4) UFOR(k, 2) \
;     dst[m][k] = *reinterpret_cast<const bf16x8*>((char*)SA(b, h) + lds_byte(wr * 64 + m * 16 + fr, k * 32 + fq * 8))
; #define LDB(dst, b, h) UFOR(n, 2) UFOR(k, 2) \
;     dst[n][k] = *reinterpret_cast<const bf16x8*>((char*)SB(b, h) + lds_byte(wc * 32 + n * 16 + fr, k * 32 + fq * 8))
; #define MMA(ai, bj, At, Bq) do { __builtin_amdgcn_s_setprio(1); \
;     UFOR(m, 4) UFOR(n, 2) UFOR(k, 2) \
;       acc[ai][bj][m][n] = __builtin_amdgcn_mfma_f32_16x16x32_bf16(Bq[n][k], At[m][k], acc[ai][bj][m][n], 0, 0, 0); \
;     __builtin_amdgcn_s_setprio(0); } while (0)
; #define WAIT_V(n) asm volatile("s_waitcnt vmcnt(" #n ")" ::: "memory")
; #define WAIT_L(n) asm volatile("s_waitcnt lgkmcnt(" #n ")" ::: "memory")
; #define BAR __builtin_amdgcn_s_barrier()
; #define SCHED __builtin_amdgcn_sched_barrier(0)
; template <int EPI, int K, int KL> ...
;     ...
;     BAR; WAIT_L(0); MMA(1, 0, At, B0); BAR; SCHED;
;     STAGE(SB(0, 1), Bt, bcol + HALF, t + 2);
;     WAIT_V(6); BAR; MMA(1, 1, At, B1); BAR;
;     LDB(B0, 1, 0); SCHED; LDA(At, 1, 0); STAGE(SA(0, 1), A, brow + HALF, t + 2);
;     WAIT_L(8); BAR; WAIT_L(0); MMA(0, 0, At, B0); BAR; SCHED;
;     LDB(B1, 1, 1); STAGE(SB(1, 0), Bt, bcol, t + 3);
;     BAR; WAIT_L(0); MMA(0, 1, At, B1); BAR;
;     LDA(At, 1, 1); STAGE(SA(1, 0), A, brow, t + 3);
	v_readfirstlane_b32 s15, v164
	v_add_u32_e32 v138, 0x2000, v164
	v_lshl_add_u64 v[136:137], v[242:243], 0, s[24:25]
	s_mov_b32 m0, s15
	v_readfirstlane_b32 s15, v138
	global_load_lds_dwordx4 v[136:137], off
	v_lshl_add_u64 v[136:137], v[244:245], 0, s[24:25]
	s_mov_b32 m0, s15
	s_nop 0
	global_load_lds_dwordx4 v[136:137], off
	s_waitcnt vmcnt(6)
	s_barrier
	v_mfma_f32_16x16x32_bf16 v[28:31], v[226:229], v[190:193], v[28:31]
	v_mfma_f32_16x16x32_bf16 v[24:27], v[234:237], v[190:193], v[24:27]
	v_mfma_f32_16x16x32_bf16 v[20:23], v[226:229], v[198:201], v[20:23]
	v_mfma_f32_16x16x32_bf16 v[16:19], v[234:237], v[198:201], v[16:19]
	v_mfma_f32_16x16x32_bf16 v[12:15], v[226:229], v[208:211], v[12:15]
	v_mfma_f32_16x16x32_bf16 v[8:11], v[234:237], v[208:211], v[8:11]
	v_mfma_f32_16x16x32_bf16 v[4:7], v[226:229], v[218:221], v[4:7]
	v_mfma_f32_16x16x32_bf16 v[0:3], v[234:237], v[218:221], v[0:3]
	v_mfma_f32_16x16x32_bf16 v[28:31], v[230:233], v[194:197], v[28:31]
	v_mfma_f32_16x16x32_bf16 v[24:27], v[238:241], v[194:197], v[24:27]
	v_mfma_f32_16x16x32_bf16 v[20:23], v[230:233], v[202:205], v[20:23]
	v_mfma_f32_16x16x32_bf16 v[16:19], v[238:241], v[202:205], v[16:19]
	v_mfma_f32_16x16x32_bf16 v[12:15], v[230:233], v[214:217], v[12:15]
	v_mfma_f32_16x16x32_bf16 v[8:11], v[238:241], v[214:217], v[8:11]
	v_mfma_f32_16x16x32_bf16 v[4:7], v[230:233], v[222:225], v[4:7]
	v_mfma_f32_16x16x32_bf16 v[0:3], v[238:241], v[222:225], v[0:3]
	s_barrier
	ds_read_b128 v[136:139], v166
	ds_read_b128 v[178:181], v166 offset:1024
	ds_read_b128 v[182:185], v166 offset:2048
	ds_read_b128 v[186:189], v166 offset:3072
	ds_read_b128 v[190:193], v160 offset:32768
	ds_read_b128 v[194:197], v160 offset:33792
	ds_read_b128 v[198:201], v159 offset:32768
	ds_read_b128 v[202:205], v159 offset:33792
	ds_read_b128 v[208:211], v158 offset:32768
	ds_read_b128 v[214:217], v158 offset:33792
	ds_read_b128 v[218:221], v157 offset:32768
	ds_read_b128 v[222:225], v157 offset:33792
	v_readfirstlane_b32 s15, v165
	v_lshl_add_u64 v[226:227], v[152:153], 0, s[62:63]
	s_mov_b32 m0, s15
	v_readfirstlane_b32 s15, v167
	global_load_lds_dwordx4 v[226:227], off
	v_lshl_add_u64 v[226:227], v[154:155], 0, s[62:63]
	s_mov_b32 m0, s15
	s_nop 0
	global_load_lds_dwordx4 v[226:227], off
	s_waitcnt lgkmcnt(8)
	s_barrier
	s_waitcnt lgkmcnt(0)
	v_mfma_f32_16x16x32_bf16 v[124:127], v[136:139], v[190:193], v[124:127]
	v_mfma_f32_16x16x32_bf16 v[120:123], v[182:185], v[190:193], v[120:123]
	v_mfma_f32_16x16x32_bf16 v[116:119], v[136:139], v[198:201], v[116:119]
	v_mfma_f32_16x16x32_bf16 v[112:115], v[182:185], v[198:201], v[112:115]
	v_mfma_f32_16x16x32_bf16 v[108:111], v[136:139], v[208:211], v[108:111]
	v_mfma_f32_16x16x32_bf16 v[104:107], v[182:185], v[208:211], v[104:107]
	v_mfma_f32_16x16x32_bf16 v[100:103], v[136:139], v[218:221], v[100:103]
	v_mfma_f32_16x16x32_bf16 v[96:99], v[182:185], v[218:221], v[96:99]
	v_mfma_f32_16x16x32_bf16 v[124:127], v[178:181], v[194:197], v[124:127]
	v_mfma_f32_16x16x32_bf16 v[120:123], v[186:189], v[194:197], v[120:123]
	v_mfma_f32_16x16x32_bf16 v[116:119], v[178:181], v[202:205], v[116:119]
	v_mfma_f32_16x16x32_bf16 v[112:115], v[186:189], v[202:205], v[112:115]
	v_mfma_f32_16x16x32_bf16 v[108:111], v[178:181], v[214:217], v[108:111]
	v_mfma_f32_16x16x32_bf16 v[104:107], v[186:189], v[214:217], v[104:107]
	v_mfma_f32_16x16x32_bf16 v[100:103], v[178:181], v[222:225], v[100:103]
	v_mfma_f32_16x16x32_bf16 v[96:99], v[186:189], v[222:225], v[96:99]
	s_barrier
	ds_read_b128 v[226:229], v163
	ds_read_b128 v[230:233], v163 offset:1024
	ds_read_b128 v[234:237], v163 offset:2048
	ds_read_b128 v[238:241], v163 offset:3072
	v_readfirstlane_b32 s15, v168
	v_lshl_add_u64 v[246:247], v[242:243], 0, s[94:95]
	s_mov_b32 m0, s15
	v_readfirstlane_b32 s15, v169
	global_load_lds_dwordx4 v[246:247], off
	v_lshl_add_u64 v[246:247], v[244:245], 0, s[94:95]
	s_mov_b32 m0, s15
	s_nop 0
	global_load_lds_dwordx4 v[246:247], off
	s_barrier
	s_waitcnt lgkmcnt(0)
	v_mfma_f32_16x16x32_bf16 v[92:95], v[226:229], v[190:193], v[92:95]
	v_mfma_f32_16x16x32_bf16 v[88:91], v[234:237], v[190:193], v[88:91]
	v_mfma_f32_16x16x32_bf16 v[84:87], v[226:229], v[198:201], v[84:87]
	v_mfma_f32_16x16x32_bf16 v[80:83], v[234:237], v[198:201], v[80:83]
	v_mfma_f32_16x16x32_bf16 v[76:79], v[226:229], v[208:211], v[76:79]
	v_mfma_f32_16x16x32_bf16 v[72:75], v[234:237], v[208:211], v[72:75]
	v_mfma_f32_16x16x32_bf16 v[68:71], v[226:229], v[218:221], v[68:71]
	v_mfma_f32_16x16x32_bf16 v[64:67], v[234:237], v[218:221], v[64:67]
	v_mfma_f32_16x16x32_bf16 v[92:95], v[230:233], v[194:197], v[92:95]
	v_mfma_f32_16x16x32_bf16 v[88:91], v[238:241], v[194:197], v[88:91]
	v_mfma_f32_16x16x32_bf16 v[84:87], v[230:233], v[202:205], v[84:87]
	v_mfma_f32_16x16x32_bf16 v[80:83], v[238:241], v[202:205], v[80:83]
	v_mfma_f32_16x16x32_bf16 v[76:79], v[230:233], v[214:217], v[76:79]
	v_mfma_f32_16x16x32_bf16 v[72:75], v[238:241], v[214:217], v[72:75]
	v_mfma_f32_16x16x32_bf16 v[68:71], v[230:233], v[222:225], v[68:71]
	v_mfma_f32_16x16x32_bf16 v[64:67], v[238:241], v[222:225], v[64:67]
	v_readfirstlane_b32 s15, v170
	v_lshl_add_u64 v[152:153], v[152:153], 0, s[64:65]
	s_mov_b32 m0, s15
	v_readfirstlane_b32 s15, v171
	s_barrier
	ds_read_b128 v[190:193], v160 offset:49152
	ds_read_b128 v[194:197], v160 offset:50176
	ds_read_b128 v[198:201], v159 offset:49152
	ds_read_b128 v[202:205], v159 offset:50176
	ds_read_b128 v[208:211], v158 offset:49152
	ds_read_b128 v[214:217], v158 offset:50176
	ds_read_b128 v[218:221], v157 offset:49152
	ds_read_b128 v[222:225], v157 offset:50176
	global_load_lds_dwordx4 v[152:153], off
	v_lshl_add_u64 v[152:153], v[154:155], 0, s[64:65]
	s_mov_b32 m0, s15
	s_nop 0
	global_load_lds_dwordx4 v[152:153], off
	s_barrier
; #define STAGE(P, BASE, br, kt) STAGET(tid_, P, BASE, br, kt)
; #define LDA(dst, b, h) UFOR(m, 4) UFOR(k, 2) \
;     dst[m][k] = *reinterpret_cast<const bf16x8*>((char*)SA(b, h) + lds_byte(wr * 64 + m * 16 + fr, k * 32 + fq * 8))
; #define LDB(dst, b, h) UFOR(n, 2) UFOR(k, 2) \
;     dst[n][k] = *reinterpret_cast<const bf16x8*>((char*)SB(b, h) + lds_byte(wc * 32 + n * 16 + fr, k * 32 + fq * 8))
; #define MMA(ai, bj, At, Bq) do { __builtin_amdgcn_s_setprio(1); \
;     UFOR(m, 4) UFOR(n, 2) UFOR(k, 2) \
;       acc[ai][bj][m][n] = __builtin_amdgcn_mfma_f32_16x16x32_bf16(Bq[n][k], At[m][k], acc[ai][bj][m][n], 0, 0, 0); \
;     __builtin_amdgcn_s_setprio(0); } while (0)
; #define WAIT_V(n) asm volatile("s_waitcnt vmcnt(" #n ")" ::: "memory")
; #define WAIT_L(n) asm volatile("s_waitcnt lgkmcnt(" #n ")" ::: "memory")
; #define BAR __builtin_amdgcn_s_barrier()
; #define SCHED __builtin_amdgcn_sched_barrier(0)
; template <int EPI, int K, int KL> ...
;     ...
;     LDA(At, 1, 1); STAGE(SA(1, 0), A, brow, t + 3);
;     BAR; WAIT_L(0); MMA(1, 0, At, B0); BAR; SCHED;
;     STAGE(SB(1, 1), Bt, bcol + HALF, t + 3);
;     WAIT_V(6); BAR; MMA(1, 1, At, B1); BAR;
;   }
;   { LDB(B0, 0, 0); LDA(At, 0, 0); STAGE(SA(1, 1), A, brow + HALF, nt - 1);
;     BAR; WAIT_L(0); MMA(0, 0, At, B0); BAR;
	s_waitcnt lgkmcnt(0)
	v_mfma_f32_16x16x32_bf16 v[60:63], v[136:139], v[190:193], v[60:63]
	v_mfma_f32_16x16x32_bf16 v[56:59], v[182:185], v[190:193], v[56:59]
	v_mfma_f32_16x16x32_bf16 v[52:55], v[136:139], v[198:201], v[52:55]
	v_mfma_f32_16x16x32_bf16 v[48:51], v[182:185], v[198:201], v[48:51]
	v_mfma_f32_16x16x32_bf16 v[44:47], v[136:139], v[208:211], v[44:47]
	v_mfma_f32_16x16x32_bf16 v[40:43], v[182:185], v[208:211], v[40:43]
	v_mfma_f32_16x16x32_bf16 v[36:39], v[136:139], v[218:221], v[36:39]
	v_mfma_f32_16x16x32_bf16 v[32:35], v[182:185], v[218:221], v[32:35]
	v_mfma_f32_16x16x32_bf16 v[60:63], v[178:181], v[194:197], v[60:63]
	v_mfma_f32_16x16x32_bf16 v[56:59], v[186:189], v[194:197], v[56:59]
	v_mfma_f32_16x16x32_bf16 v[52:55], v[178:181], v[202:205], v[52:55]
	v_mfma_f32_16x16x32_bf16 v[48:51], v[186:189], v[202:205], v[48:51]
	v_mfma_f32_16x16x32_bf16 v[44:47], v[178:181], v[214:217], v[44:47]
	v_mfma_f32_16x16x32_bf16 v[40:43], v[186:189], v[214:217], v[40:43]
	v_mfma_f32_16x16x32_bf16 v[36:39], v[178:181], v[222:225], v[36:39]
	v_mfma_f32_16x16x32_bf16 v[32:35], v[186:189], v[222:225], v[32:35]
	s_barrier
	v_readfirstlane_b32 s15, v172
	v_lshl_add_u64 v[136:137], v[242:243], 0, s[10:11]
	s_mov_b32 m0, s15
	v_readfirstlane_b32 s15, v174
	global_load_lds_dwordx4 v[136:137], off
	v_lshl_add_u64 v[136:137], v[244:245], 0, s[10:11]
	s_mov_b32 m0, s15
	s_nop 0
	global_load_lds_dwordx4 v[136:137], off
	s_waitcnt vmcnt(6)
	s_barrier
	v_mfma_f32_16x16x32_bf16 v[28:31], v[226:229], v[190:193], v[28:31]
	v_mfma_f32_16x16x32_bf16 v[24:27], v[234:237], v[190:193], v[24:27]
	v_mfma_f32_16x16x32_bf16 v[20:23], v[226:229], v[198:201], v[20:23]
	v_mfma_f32_16x16x32_bf16 v[16:19], v[234:237], v[198:201], v[16:19]
	v_mfma_f32_16x16x32_bf16 v[12:15], v[226:229], v[208:211], v[12:15]
	v_mfma_f32_16x16x32_bf16 v[8:11], v[234:237], v[208:211], v[8:11]
	v_mfma_f32_16x16x32_bf16 v[4:7], v[226:229], v[218:221], v[4:7]
	v_mfma_f32_16x16x32_bf16 v[0:3], v[234:237], v[218:221], v[0:3]
	v_mfma_f32_16x16x32_bf16 v[28:31], v[230:233], v[194:197], v[28:31]
	v_mfma_f32_16x16x32_bf16 v[24:27], v[238:241], v[194:197], v[24:27]
	v_mfma_f32_16x16x32_bf16 v[20:23], v[230:233], v[202:205], v[20:23]
	v_mfma_f32_16x16x32_bf16 v[16:19], v[238:241], v[202:205], v[16:19]
	v_mfma_f32_16x16x32_bf16 v[12:15], v[230:233], v[214:217], v[12:15]
	v_mfma_f32_16x16x32_bf16 v[8:11], v[238:241], v[214:217], v[8:11]
	v_mfma_f32_16x16x32_bf16 v[4:7], v[230:233], v[222:225], v[4:7]
	v_mfma_f32_16x16x32_bf16 v[0:3], v[238:241], v[222:225], v[0:3]
	s_add_i32 s14, s14, 2
	v_lshl_add_u64 v[144:145], v[144:145], 0, s[20:21]
	v_lshl_add_u64 v[146:147], v[146:147], 0, s[20:21]
	v_lshl_add_u64 v[148:149], v[148:149], 0, s[20:21]
	s_cmp_lt_u32 s14, 4
	v_lshl_add_u64 v[150:151], v[150:151], 0, s[20:21]
	s_cbranch_scc1 .Lkrot_1204
	s_barrier
	s_add_u32 s14, s46, 0x160380
	s_addc_u32 s15, s47, 0
	v_lshl_add_u64 v[142:143], s[14:15], 0, v[142:143]
	v_readfirstlane_b32 s18, v176
	v_lshl_add_u64 v[128:129], v[128:129], 1, v[142:143]
	s_mov_b32 m0, s18
	ds_read_b128 v[136:139], v175
	ds_read_b128 v[144:147], v175 offset:1024
	ds_read_b128 v[148:151], v175 offset:2048
	ds_read_b128 v[168:171], v175 offset:3072
	ds_read_b128 v[178:181], v160
	ds_read_b128 v[182:185], v160 offset:1024
	ds_read_b128 v[186:189], v159
	ds_read_b128 v[190:193], v159 offset:1024
	ds_read_b128 v[194:197], v158
	ds_read_b128 v[198:201], v158 offset:1024
	ds_read_b128 v[202:205], v157
	ds_read_b128 v[208:211], v157 offset:1024
	global_load_lds_dwordx4 v[128:129], off
	v_lshl_add_u64 v[128:129], s[14:15], 0, v[140:141]
	v_readfirstlane_b32 s14, v177
	v_lshl_add_u64 v[128:129], v[130:131], 1, v[128:129]
	s_mov_b32 m0, s14
	s_nop 0
	global_load_lds_dwordx4 v[128:129], off
	s_barrier
	s_waitcnt lgkmcnt(0)
	s_waitcnt lgkmcnt(0)
	v_mfma_f32_16x16x32_bf16 v[124:127], v[136:139], v[178:181], v[124:127]
	v_mfma_f32_16x16x32_bf16 v[120:123], v[148:151], v[178:181], v[120:123]
	v_mfma_f32_16x16x32_bf16 v[116:119], v[136:139], v[186:189], v[116:119]
	v_mfma_f32_16x16x32_bf16 v[112:115], v[148:151], v[186:189], v[112:115]
	v_mfma_f32_16x16x32_bf16 v[108:111], v[136:139], v[194:197], v[108:111]
	v_mfma_f32_16x16x32_bf16 v[104:107], v[148:151], v[194:197], v[104:107]
	v_mfma_f32_16x16x32_bf16 v[100:103], v[136:139], v[202:205], v[100:103]
	v_mfma_f32_16x16x32_bf16 v[96:99], v[148:151], v[202:205], v[96:99]
	v_mfma_f32_16x16x32_bf16 v[124:127], v[144:147], v[182:185], v[124:127]
	v_mfma_f32_16x16x32_bf16 v[120:123], v[168:171], v[182:185], v[120:123]
	v_mfma_f32_16x16x32_bf16 v[116:119], v[144:147], v[190:193], v[116:119]
	v_mfma_f32_16x16x32_bf16 v[112:115], v[168:171], v[190:193], v[112:115]
	v_mfma_f32_16x16x32_bf16 v[108:111], v[144:147], v[198:201], v[108:111]
	v_mfma_f32_16x16x32_bf16 v[104:107], v[168:171], v[198:201], v[104:107]
	v_mfma_f32_16x16x32_bf16 v[100:103], v[144:147], v[208:211], v[100:103]
	v_mfma_f32_16x16x32_bf16 v[96:99], v[168:171], v[208:211], v[96:99]
	s_barrier
	ds_read_b128 v[128:131], v173
	ds_read_b128 v[140:143], v173 offset:1024
	ds_read_b128 v[174:177], v173 offset:2048
	ds_read_b128 v[214:217], v173 offset:3072
	s_barrier
; #define STAGE(P, BASE, br, kt) STAGET(tid_, P, BASE, br, kt)
; #define LDA(dst, b, h) UFOR(m, 4) UFOR(k, 2) \
;     dst[m][k] = *reinterpret_cast<const bf16x8*>((char*)SA(b, h) + lds_byte(wr * 64 + m * 16 + fr, k * 32 + fq * 8))
; #define LDB(dst, b, h) UFOR(n, 2) UFOR(k, 2) \
;     dst[n][k] = *reinterpret_cast<const bf16x8*>((char*)SB(b, h) + lds_byte(wc * 32 + n * 16 + fr, k * 32 + fq * 8))
; #define MMA(ai, bj, At, Bq) do { __builtin_amdgcn_s_setprio(1); \
;     UFOR(m, 4) UFOR(n, 2) UFOR(k, 2) \
;       acc[ai][bj][m][n] = __builtin_amdgcn_mfma_f32_16x16x32_bf16(Bq[n][k], At[m][k], acc[ai][bj][m][n], 0, 0, 0); \
;     __builtin_amdgcn_s_setprio(0); } while (0)
; #define WAIT_V(n) asm volatile("s_waitcnt vmcnt(" #n ")" ::: "memory")
; #define WAIT_L(n) asm volatile("s_waitcnt lgkmcnt(" #n ")" ::: "memory")
; #define BAR __builtin_amdgcn_s_barrier()
; template <int EPI, int K, int KL> ...
;     ...
;   { LDB(B0, 0, 0); LDA(At, 0, 0); STAGE(SA(1, 1), A, brow + HALF, nt - 1);
;     BAR; WAIT_L(0); MMA(0, 0, At, B0); BAR;
;     LDB(B1, 0, 1); BAR; WAIT_L(0); MMA(0, 1, At, B1); BAR;
;     LDA(At, 0, 1); WAIT_V(4); BAR; WAIT_L(0); MMA(1, 0, At, B0); MMA(1, 1, At, B1); BAR; }
;   { LDB(B0, 1, 0); LDA(At, 1, 0); WAIT_V(2); BAR; WAIT_L(0); MMA(0, 0, At, B0); BAR;
	s_waitcnt lgkmcnt(0)
	s_waitcnt lgkmcnt(0)
	v_mfma_f32_16x16x32_bf16 v[92:95], v[128:131], v[178:181], v[92:95]
	v_mfma_f32_16x16x32_bf16 v[88:91], v[174:177], v[178:181], v[88:91]
	v_mfma_f32_16x16x32_bf16 v[84:87], v[128:131], v[186:189], v[84:87]
	v_mfma_f32_16x16x32_bf16 v[80:83], v[174:177], v[186:189], v[80:83]
	v_mfma_f32_16x16x32_bf16 v[76:79], v[128:131], v[194:197], v[76:79]
	v_mfma_f32_16x16x32_bf16 v[68:71], v[128:131], v[202:205], v[68:71]
	v_mfma_f32_16x16x32_bf16 v[64:67], v[174:177], v[202:205], v[64:67]
	v_mfma_f32_16x16x32_bf16 v[92:95], v[140:143], v[182:185], v[92:95]
	v_mfma_f32_16x16x32_bf16 v[88:91], v[214:217], v[182:185], v[88:91]
	v_mfma_f32_16x16x32_bf16 v[84:87], v[140:143], v[190:193], v[84:87]
	v_mfma_f32_16x16x32_bf16 v[80:83], v[214:217], v[190:193], v[80:83]
	v_mfma_f32_16x16x32_bf16 v[76:79], v[140:143], v[198:201], v[76:79]
	v_mfma_f32_16x16x32_bf16 v[72:75], v[174:177], v[194:197], v[72:75]
	v_mfma_f32_16x16x32_bf16 v[68:71], v[140:143], v[208:211], v[68:71]
	v_mfma_f32_16x16x32_bf16 v[64:67], v[214:217], v[208:211], v[64:67]
	v_mfma_f32_16x16x32_bf16 v[178:181], v[214:217], v[198:201], v[72:75]
	s_barrier
	s_nop 3
	ds_read_b128 v[72:75], v160 offset:16384
	ds_read_b128 v[182:185], v160 offset:17408
	ds_read_b128 v[186:189], v159 offset:16384
	ds_read_b128 v[190:193], v159 offset:17408
	ds_read_b128 v[194:197], v158 offset:16384
	ds_read_b128 v[198:201], v158 offset:17408
	ds_read_b128 v[202:205], v157 offset:16384
	ds_read_b128 v[208:211], v157 offset:17408
	s_waitcnt vmcnt(4)
	s_barrier
	s_waitcnt lgkmcnt(0)
	s_waitcnt lgkmcnt(0)
	v_mfma_f32_16x16x32_bf16 v[48:51], v[148:151], v[186:189], v[48:51]
	v_mfma_f32_16x16x32_bf16 v[60:63], v[136:139], v[72:75], v[60:63]
	v_mfma_f32_16x16x32_bf16 v[56:59], v[148:151], v[72:75], v[56:59]
	v_mfma_f32_16x16x32_bf16 v[52:55], v[136:139], v[186:189], v[52:55]
	v_mfma_f32_16x16x32_bf16 v[48:51], v[168:171], v[190:193], v[48:51]
	v_mfma_f32_16x16x32_bf16 v[44:47], v[136:139], v[194:197], v[44:47]
	v_mfma_f32_16x16x32_bf16 v[40:43], v[148:151], v[194:197], v[40:43]
	v_mfma_f32_16x16x32_bf16 v[36:39], v[136:139], v[202:205], v[36:39]
	v_mfma_f32_16x16x32_bf16 v[32:35], v[148:151], v[202:205], v[32:35]
	v_mfma_f32_16x16x32_bf16 v[218:221], v[144:147], v[182:185], v[60:63]
	v_mfma_f32_16x16x32_bf16 v[222:225], v[168:171], v[182:185], v[56:59]
	v_mfma_f32_16x16x32_bf16 v[226:229], v[144:147], v[190:193], v[52:55]
	v_mfma_f32_16x16x32_bf16 v[230:233], v[144:147], v[198:201], v[44:47]
	v_mfma_f32_16x16x32_bf16 v[234:237], v[168:171], v[198:201], v[40:43]
	v_mfma_f32_16x16x32_bf16 v[136:139], v[144:147], v[208:211], v[36:39]
	v_mfma_f32_16x16x32_bf16 v[144:147], v[168:171], v[208:211], v[32:35]
	v_mfma_f32_16x16x32_bf16 v[28:31], v[128:131], v[72:75], v[28:31]
	v_mfma_f32_16x16x32_bf16 v[24:27], v[174:177], v[72:75], v[24:27]
	v_mfma_f32_16x16x32_bf16 v[20:23], v[128:131], v[186:189], v[20:23]
	v_mfma_f32_16x16x32_bf16 v[16:19], v[174:177], v[186:189], v[16:19]
	v_mfma_f32_16x16x32_bf16 v[12:15], v[128:131], v[194:197], v[12:15]
	v_mfma_f32_16x16x32_bf16 v[8:11], v[174:177], v[194:197], v[8:11]
	v_mfma_f32_16x16x32_bf16 v[4:7], v[128:131], v[202:205], v[4:7]
	v_mfma_f32_16x16x32_bf16 v[0:3], v[174:177], v[202:205], v[0:3]
	v_mfma_f32_16x16x32_bf16 v[148:151], v[140:143], v[182:185], v[28:31]
	v_mfma_f32_16x16x32_bf16 v[168:171], v[214:217], v[182:185], v[24:27]
	v_mfma_f32_16x16x32_bf16 v[182:185], v[140:143], v[190:193], v[20:23]
	v_mfma_f32_16x16x32_bf16 v[186:189], v[214:217], v[190:193], v[16:19]
	v_mfma_f32_16x16x32_bf16 v[190:193], v[140:143], v[198:201], v[12:15]
	v_mfma_f32_16x16x32_bf16 v[194:197], v[214:217], v[198:201], v[8:11]
	v_mfma_f32_16x16x32_bf16 v[128:131], v[140:143], v[208:211], v[4:7]
	v_mfma_f32_16x16x32_bf16 v[140:143], v[214:217], v[208:211], v[0:3]
	s_barrier
	ds_read_b128 v[172:175], v166
	ds_read_b128 v[198:201], v166 offset:1024
	ds_read_b128 v[202:205], v166 offset:2048
	ds_read_b128 v[164:167], v166 offset:3072
	ds_read_b128 v[20:23], v160 offset:32768
	ds_read_b128 v[24:27], v160 offset:33792
	ds_read_b128 v[28:31], v159 offset:32768
	ds_read_b128 v[32:35], v159 offset:33792
	ds_read_b128 v[36:39], v158 offset:32768
	ds_read_b128 v[208:211], v158 offset:33792
	ds_read_b128 v[214:217], v157 offset:32768
	ds_read_b128 v[238:241], v157 offset:33792
	s_waitcnt vmcnt(2)
	s_barrier
; #define LDA(dst, b, h) UFOR(m, 4) UFOR(k, 2) \
;     dst[m][k] = *reinterpret_cast<const bf16x8*>((char*)SA(b, h) + lds_byte(wr * 64 + m * 16 + fr, k * 32 + fq * 8))
; #define LDB(dst, b, h) UFOR(n, 2) UFOR(k, 2) \
;     dst[n][k] = *reinterpret_cast<const bf16x8*>((char*)SB(b, h) + lds_byte(wc * 32 + n * 16 + fr, k * 32 + fq * 8))
; #define MMA(ai, bj, At, Bq) do { __builtin_amdgcn_s_setprio(1); \
;     UFOR(m, 4) UFOR(n, 2) UFOR(k, 2) \
;       acc[ai][bj][m][n] = __builtin_amdgcn_mfma_f32_16x16x32_bf16(Bq[n][k], At[m][k], acc[ai][bj][m][n], 0, 0, 0); \
;     __builtin_amdgcn_s_setprio(0); } while (0)
; #define WAIT_V(n) asm volatile("s_waitcnt vmcnt(" #n ")" ::: "memory")
; #define WAIT_L(n) asm volatile("s_waitcnt lgkmcnt(" #n ")" ::: "memory")
; #define BAR __builtin_amdgcn_s_barrier()
; template <int EPI, int K, int KL> ...
;     ...
;   { LDB(B0, 1, 0); LDA(At, 1, 0); WAIT_V(2); BAR; WAIT_L(0); MMA(0, 0, At, B0); BAR;
;     LDB(B1, 1, 1); WAIT_V(0); BAR; WAIT_L(0); MMA(0, 1, At, B1); BAR;
;     LDA(At, 1, 1); BAR; WAIT_L(0); MMA(1, 0, At, B0); MMA(1, 1, At, B1); BAR; }
;   if (wr == 0) BAR;
; __device__ __forceinline__ void gemm_ctx_splitk_down(const u16* A, const u16* Bt, float* P2, const EpiArgs& e0) {
;     ...
;   for (int u = bid_; u < 16 * P2_PARTS; u += gridDim.x) {
;     const int tile = u / P2_PARTS, part = u % P2_PARTS, pm = 128 + (tile >> 3), pn = tile & 7;
;     EpiArgs e = e0; e.part = P2 + (size_t)part * 512 * DM;
;     const long koff = (long)part * (DFF / P2_PARTS);
;     gemm_tile<EPI_PART, DFF, DFF / P2_PARTS>(A + koff, Bt + koff, (long)pm * BM, pn * BM, pn, 0, 0, e, true, false, 0, 0);
;   }
	s_waitcnt lgkmcnt(0)
	s_waitcnt lgkmcnt(0)
	v_mfma_f32_16x16x32_bf16 v[0:3], v[172:175], v[20:23], v[124:127]
	v_mfma_f32_16x16x32_bf16 v[44:47], v[198:201], v[24:27], v[0:3]
	v_mfma_f32_16x16x32_bf16 v[0:3], v[202:205], v[20:23], v[120:123]
	v_mfma_f32_16x16x32_bf16 v[52:55], v[164:167], v[24:27], v[0:3]
	v_mfma_f32_16x16x32_bf16 v[0:3], v[172:175], v[28:31], v[116:119]
	v_mfma_f32_16x16x32_bf16 v[40:43], v[198:201], v[32:35], v[0:3]
	v_mfma_f32_16x16x32_bf16 v[0:3], v[202:205], v[28:31], v[112:115]
	v_mfma_f32_16x16x32_bf16 v[16:19], v[164:167], v[32:35], v[0:3]
	v_mfma_f32_16x16x32_bf16 v[0:3], v[172:175], v[36:39], v[108:111]
	v_mfma_f32_16x16x32_bf16 v[8:11], v[198:201], v[208:211], v[0:3]
	v_mfma_f32_16x16x32_bf16 v[0:3], v[202:205], v[36:39], v[104:107]
	v_mfma_f32_16x16x32_bf16 v[12:15], v[164:167], v[208:211], v[0:3]
	v_mfma_f32_16x16x32_bf16 v[0:3], v[172:175], v[214:217], v[100:103]
	v_mfma_f32_16x16x32_bf16 v[4:7], v[202:205], v[214:217], v[96:99]
	v_mfma_f32_16x16x32_bf16 v[0:3], v[198:201], v[238:241], v[0:3]
	v_mfma_f32_16x16x32_bf16 v[4:7], v[164:167], v[238:241], v[4:7]
	s_barrier
	ds_read_b128 v[108:111], v163
	ds_read_b128 v[242:245], v163 offset:1024
	ds_read_b128 v[246:249], v163 offset:2048
	ds_read_b128 v[152:155], v163 offset:3072
	s_waitcnt vmcnt(0)
	s_barrier
	s_waitcnt lgkmcnt(0)
	s_waitcnt lgkmcnt(0)
	v_mfma_f32_16x16x32_bf16 v[56:59], v[108:111], v[20:23], v[92:95]
	v_mfma_f32_16x16x32_bf16 v[20:23], v[246:249], v[20:23], v[88:91]
	v_mfma_f32_16x16x32_bf16 v[72:75], v[152:155], v[24:27], v[20:23]
	v_mfma_f32_16x16x32_bf16 v[20:23], v[108:111], v[28:31], v[84:87]
	v_mfma_f32_16x16x32_bf16 v[60:63], v[242:245], v[24:27], v[56:59]
	v_mfma_f32_16x16x32_bf16 v[56:59], v[242:245], v[32:35], v[20:23]
	v_mfma_f32_16x16x32_bf16 v[20:23], v[246:249], v[28:31], v[80:83]
	v_mfma_f32_16x16x32_bf16 v[20:23], v[152:155], v[32:35], v[20:23]
	v_mfma_f32_16x16x32_bf16 v[24:27], v[108:111], v[36:39], v[76:79]
	v_mfma_f32_16x16x32_bf16 v[28:31], v[246:249], v[36:39], v[178:181]
	v_mfma_f32_16x16x32_bf16 v[32:35], v[108:111], v[214:217], v[68:71]
	v_mfma_f32_16x16x32_bf16 v[36:39], v[246:249], v[214:217], v[64:67]
	v_mfma_f32_16x16x32_bf16 v[24:27], v[242:245], v[208:211], v[24:27]
	v_mfma_f32_16x16x32_bf16 v[28:31], v[152:155], v[208:211], v[28:31]
	v_mfma_f32_16x16x32_bf16 v[32:35], v[242:245], v[238:241], v[32:35]
	v_mfma_f32_16x16x32_bf16 v[36:39], v[152:155], v[238:241], v[36:39]
	s_barrier
	ds_read_b128 v[88:91], v160 offset:49152
	ds_read_b128 v[92:95], v160 offset:50176
	ds_read_b128 v[96:99], v159 offset:49152
	ds_read_b128 v[100:103], v159 offset:50176
	ds_read_b128 v[104:107], v158 offset:49152
	ds_read_b128 v[158:161], v158 offset:50176
	ds_read_b128 v[176:179], v157 offset:49152
	ds_read_b128 v[208:211], v157 offset:50176
	s_barrier
	s_waitcnt lgkmcnt(0)
	s_waitcnt lgkmcnt(0)
	v_mfma_f32_16x16x32_bf16 v[48:51], v[202:205], v[96:99], v[48:51]
	v_mfma_f32_16x16x32_bf16 v[64:67], v[172:175], v[88:91], v[218:221]
	v_mfma_f32_16x16x32_bf16 v[116:119], v[164:167], v[100:103], v[48:51]
	v_mfma_f32_16x16x32_bf16 v[48:51], v[172:175], v[104:107], v[230:233]
	v_mfma_f32_16x16x32_bf16 v[120:123], v[198:201], v[92:95], v[64:67]
	v_mfma_f32_16x16x32_bf16 v[64:67], v[202:205], v[88:91], v[222:225]
	v_mfma_f32_16x16x32_bf16 v[76:79], v[198:201], v[158:161], v[48:51]
	v_mfma_f32_16x16x32_bf16 v[48:51], v[202:205], v[104:107], v[234:237]
	v_mfma_f32_16x16x32_bf16 v[124:127], v[164:167], v[92:95], v[64:67]
	v_mfma_f32_16x16x32_bf16 v[64:67], v[172:175], v[96:99], v[226:229]
	v_mfma_f32_16x16x32_bf16 v[80:83], v[164:167], v[158:161], v[48:51]
	v_mfma_f32_16x16x32_bf16 v[48:51], v[172:175], v[176:179], v[136:139]
	v_mfma_f32_16x16x32_bf16 v[112:115], v[198:201], v[100:103], v[64:67]
	v_mfma_f32_16x16x32_bf16 v[64:67], v[198:201], v[208:211], v[48:51]
	v_mfma_f32_16x16x32_bf16 v[48:51], v[202:205], v[176:179], v[144:147]
	v_mfma_f32_16x16x32_bf16 v[68:71], v[164:167], v[208:211], v[48:51]
	v_mfma_f32_16x16x32_bf16 v[48:51], v[108:111], v[88:91], v[148:151]
	v_mfma_f32_16x16x32_bf16 v[84:87], v[242:245], v[92:95], v[48:51]
	v_mfma_f32_16x16x32_bf16 v[48:51], v[246:249], v[88:91], v[168:171]
	v_mfma_f32_16x16x32_bf16 v[88:91], v[152:155], v[92:95], v[48:51]
	v_mfma_f32_16x16x32_bf16 v[48:51], v[108:111], v[96:99], v[182:185]
	v_mfma_f32_16x16x32_bf16 v[92:95], v[242:245], v[100:103], v[48:51]
	v_mfma_f32_16x16x32_bf16 v[48:51], v[246:249], v[96:99], v[186:189]
	v_mfma_f32_16x16x32_bf16 v[96:99], v[152:155], v[100:103], v[48:51]
	v_mfma_f32_16x16x32_bf16 v[48:51], v[108:111], v[104:107], v[190:193]
	v_mfma_f32_16x16x32_bf16 v[100:103], v[242:245], v[158:161], v[48:51]
	v_mfma_f32_16x16x32_bf16 v[48:51], v[246:249], v[104:107], v[194:197]
	v_mfma_f32_16x16x32_bf16 v[104:107], v[152:155], v[158:161], v[48:51]
	v_mfma_f32_16x16x32_bf16 v[48:51], v[108:111], v[176:179], v[128:131]
	v_mfma_f32_16x16x32_bf16 v[108:111], v[242:245], v[208:211], v[48:51]
	v_mfma_f32_16x16x32_bf16 v[48:51], v[246:249], v[176:179], v[140:143]
	v_mfma_f32_16x16x32_bf16 v[48:51], v[152:155], v[208:211], v[48:51]
	s_movk_i32 s14, 0x100
	v_cmp_gt_u32_e32 vcc, s14, v132
	s_barrier
	s_and_saveexec_b64 s[44:45], vcc
	s_cbranch_execz .LBB0_1200
	s_barrier
	s_branch .LBB0_1200
